# strategy 4: one static s_setprio 1 for the trailing half (waves 4-7) in all six GEMM phases, per-segment priority flips removed from the K-loops
# speedup vs baseline: 1.0027x; 1.0027x over previous
; #define PG8_STAGE(bufoff, gbase, voff) do { _Pragma("unroll") for (int _i = 0; _i < 2; ++_i) \
;         __builtin_amdgcn_global_load_lds((const unsigned*)((const char*)(gbase) + (voff)[_i]), (PG8_LAS unsigned*)(lds + (bufoff) + ldsw + _i * 8192), 16, 0, 0); } while (0)
; #define PG8_BAR __builtin_amdgcn_s_barrier()
; template <class Epi, class Sched, bool ALIGN_EPI = false, bool SP2 = false>
; __device__ __forceinline__ void gemm_phase(PG8_LAS unsigned char* lds, const Gemm g, const Sched& S, const Epi& E) {
;     int tid_ = threadIdx.x; asm volatile("" : "+v"(tid_));
;     const int tid = tid_, wid = __builtin_amdgcn_readfirstlane(tid >> 6), lane = tid & 63, wr = wid >> 2, wc = wid & 3, fr = lane & 15, fq = lane >> 4;
;     const int K = g.K, nt = K / BK;
;     unsigned voffA[2], voffB[2];
; #pragma unroll
;     for (int i = 0; i < 2; ++i) { int R, C; stage_rc(tid * 16 + i * 8192, R, C); const int Rb = Epi::PERM ? ((R & ~31) + perm32(R & 31)) : R;
;         voffA[i] = (unsigned)(R * K + C) * 2u; voffB[i] = (unsigned)(Rb * K + C) * 2u; }
;     const size_t kstep = (size_t)(BK * 2);
;     const size_t hstep = (size_t)HALF * K * 2;
;     const size_t tstep = 2 * hstep;
;     const unsigned ldsw = (unsigned)wid * 1024u;
;     const int aoff = lds_byte(wr * 64 + fr, fq * 8), boff = lds_byte(wc * 32 + fr, fq * 8);
;     ...
;     const char* cA = (const char*)g.A + (size_t)cur.pm * tstep; const char* cB = (const char*)g.Bt + (size_t)cur.pn * tstep;
;     S.a_ready(cur);
;     if constexpr (SP2) {
;         PG8_STAGE(PG8_SB(0, 0), cB, voffB); PG8_STAGE(PG8_SB(0, 1), cB + hstep, voffB); PG8_STAGE(PG8_SA(0, 0), cA, voffA); PG8_STAGE(PG8_SA(0, 1), cA + hstep, voffA);
;         if (wr == 1) PG8_BAR;
.LBB0_135:
	s_waitcnt lgkmcnt(0)
	v_ashrrev_i32_e32 v1, 31, v8
	v_lshrrev_b32_e32 v1, 26, v1
	v_add_u32_e32 v1, v8, v1
	v_ashrrev_i32_e32 v9, 6, v1
	v_bfe_i32 v1, v8, 27, 1
	v_lshlrev_b32_e32 v0, 4, v8
	v_lshrrev_b32_e32 v1, 22, v1
	v_add_u32_e32 v1, v0, v1
	v_and_b32_e32 v1, 0xfffffc00, v1
	v_sub_u32_e32 v1, v0, v1
	v_lshrrev_b32_e32 v2, 4, v1
	v_bitop3_b32 v1, v2, v1, 32 bitop3:0x6c
	v_ashrrev_i32_e32 v3, 31, v1
	v_lshrrev_b32_e32 v3, 26, v3
	v_add_u32_e32 v3, v1, v3
	v_lshlrev_b32_e32 v2, 3, v9
	v_ashrrev_i32_e32 v10, 6, v3
	v_and_b32_e32 v3, 0xc0, v3
	v_and_b32_e32 v2, -16, v2
	v_sub_u32_e32 v1, v1, v3
	v_add_u32_e32 v2, v10, v2
	v_ashrrev_i16_sdwa v1, v240, sext(v1) dst_sel:DWORD dst_unused:UNUSED_PAD src0_sel:DWORD src1_sel:BYTE_0
	v_lshlrev_b32_e32 v4, 5, v9
	v_bfe_i32 v11, v1, 0, 16
	v_lshlrev_b32_e32 v1, 1, v2
	v_lshrrev_b32_e32 v3, 2, v2
	v_and_b32_e32 v5, 3, v10
	s_mov_b32 s1, 0xfffe0
	v_and_b32_e32 v4, 32, v4
	v_and_b32_e32 v1, 24, v1
	v_and_b32_e32 v3, 4, v3
	v_and_or_b32 v5, v2, s1, v5
	v_or3_b32 v1, v5, v3, v1
	v_add_lshl_u32 v3, v4, v11, 1
	v_add_u32_e32 v0, 0x2000, v0
	v_lshl_add_u32 v132, v1, 12, v3
	v_ashrrev_i32_e32 v1, 31, v0
	v_lshrrev_b32_e32 v1, 22, v1
	v_add_u32_e32 v1, v0, v1
	v_ashrrev_i32_e32 v12, 10, v1
	v_mul_i32_i24_e32 v1, 0x400, v12
	v_sub_u32_e32 v0, v0, v1
	v_lshrrev_b32_e32 v1, 4, v0
	v_bitop3_b32 v0, v1, v0, 32 bitop3:0x6c
	v_lshl_add_u32 v130, v2, 12, v3
	v_ashrrev_i32_e32 v2, 31, v0
	s_add_u32 s10, s48, 0x2ab00000
	v_lshrrev_b32_e32 v2, 26, v2
	s_addc_u32 s11, s49, 0
	v_lshlrev_b32_e32 v1, 3, v12
	v_add_u32_e32 v2, v0, v2
	s_add_u32 s26, s48, 0x4300000
	v_and_b32_e32 v1, -16, v1
	v_ashrrev_i32_e32 v13, 6, v2
	s_addc_u32 s62, s49, 0
	v_add_u32_e32 v1, v13, v1
	v_and_b32_e32 v4, 3, v13
	s_add_i32 s0, s4, s0
	v_and_or_b32 v4, v1, s1, v4
	s_ashr_i32 s1, s0, 31
	v_and_b32_e32 v2, 0xc0, v2
	s_lshr_b32 s1, s1, 25
	v_sub_u32_e32 v0, v0, v2
	s_add_i32 s1, s0, s1
	v_ashrrev_i16_sdwa v0, v240, sext(v0) dst_sel:DWORD dst_unused:UNUSED_PAD src0_sel:DWORD src1_sel:BYTE_0
	s_ashr_i32 s4, s1, 7
	v_lshlrev_b32_e32 v3, 5, v12
	v_bfe_i32 v14, v0, 0, 16
	v_lshlrev_b32_e32 v0, 1, v1
	v_lshrrev_b32_e32 v2, 2, v1
	s_lshl_b32 s4, s4, 3
	v_and_b32_e32 v3, 32, v3
	v_and_b32_e32 v0, 24, v0
	v_and_b32_e32 v2, 4, v2
	s_sub_i32 s5, 4, s4
	v_or3_b32 v0, v4, v2, v0
	v_add_lshl_u32 v2, v3, v14, 1
	s_min_u32 s5, s5, 8
	s_and_b32 s1, s1, 0xffffff80
	v_lshl_add_u32 v134, v1, 12, v2
	s_sub_i32 s18, s0, s1
	v_cvt_f32_ubyte0_e32 v1, s5
	v_lshl_add_u32 v136, v0, 12, v2
	v_cvt_f32_i32_e32 v0, s18
	v_rcp_iflag_f32_e32 v2, v1
	s_ashr_i32 s15, s12, 6
	s_ashr_i32 s0, s18, 30
	s_ashr_i32 s13, s12, 8
	v_mul_f32_e32 v2, v0, v2
	v_trunc_f32_e32 v2, v2
	v_fma_f32 v0, -v2, v1, v0
	v_cvt_i32_f32_e32 v2, v2
	s_lshl_b32 s63, s15, 10
	s_or_b32 s14, s0, 1
	v_cmp_ge_f32_e64 s[0:1], |v0|, v1
	s_and_b64 s[0:1], s[0:1], exec
	s_cselect_b32 s0, s14, 0
	v_readfirstlane_b32 s1, v2
	s_add_i32 s14, s1, s0
	s_mul_i32 s0, s14, s5
	s_sub_i32 s0, s18, s0
	s_sext_i32_i8 s0, s0
	s_add_i32 s54, s4, s0
	s_ashr_i32 s55, s54, 31
	s_bfe_i64 s[4:5], s[14:15], 0x80000
	s_lshl_b64 s[0:1], s[54:55], 20
	s_lshl_b64 s[4:5], s[4:5], 20
	s_add_u32 s56, s26, s4
	s_addc_u32 s57, s62, s5
	s_add_i32 s55, s63, 0
	s_add_i32 m0, s55, 0x10000
	v_mov_b32_e32 v133, v96
	global_load_lds_dwordx4 v132, s[56:57]
	s_add_i32 m0, s55, 0x12000
	s_add_u32 s4, s56, 0x80000
	global_load_lds_dwordx4 v136, s[56:57]
	s_addc_u32 s5, s57, 0
	s_add_i32 m0, s55, 0x14000
	v_mov_b32_e32 v137, v96
	global_load_lds_dwordx4 v132, s[4:5]
	s_add_i32 m0, s55, 0x16000
	s_add_u32 s58, s10, s0
	s_addc_u32 s59, s11, s1
	s_add_i32 s64, s55, 0x2000
	global_load_lds_dwordx4 v136, s[4:5]
	s_mov_b32 m0, s55
	s_add_u32 s0, s58, 0x80000
	global_load_lds_dwordx4 v130, s[58:59]
	s_mov_b32 m0, s64
	s_addc_u32 s1, s59, 0
	s_add_i32 s65, s55, 0x4000
	global_load_lds_dwordx4 v134, s[58:59]
	s_mov_b32 m0, s65
	s_add_i32 s67, s55, 0x6000
	global_load_lds_dwordx4 v130, s[0:1]
	s_mov_b32 m0, s67
	v_mov_b32_e32 v131, v96
	global_load_lds_dwordx4 v134, s[0:1]
	v_mov_b32_e32 v135, v96
	s_cmp_eq_u32 s13, 1
	v_lshl_add_u64 v[6:7], s[56:57], 0, v[132:133]
	v_lshl_add_u64 v[4:5], s[56:57], 0, v[136:137]
	v_lshl_add_u64 v[0:1], s[58:59], 0, v[130:131]
	s_cselect_b64 s[0:1], -1, 0
	s_cmp_lg_u32 s13, 1
	v_lshl_add_u64 v[2:3], s[58:59], 0, v[134:135]
	s_cbranch_scc1 .LBB0_137
	s_barrier
	s_setprio 1

; #define PG8_STAGE(bufoff, gbase, voff) do { _Pragma("unroll") for (int _i = 0; _i < 2; ++_i) \
;         __builtin_amdgcn_global_load_lds((const unsigned*)((const char*)(gbase) + (voff)[_i]), (PG8_LAS unsigned*)(lds + (bufoff) + ldsw + _i * 8192), 16, 0, 0); } while (0)
; #define PG8_LDA(dst, b, h) do { _Pragma("unroll") for (int m = 0; m < 4; ++m) _Pragma("unroll") for (int k = 0; k < 2; ++k) dst[m][k] = *(const PG8_LAS bf16x8*)(lds + PG8_SA(b, h) + aoff + m * 2048 + k * 1024); } while (0)
; #define PG8_LDB(dst, b, h) do { _Pragma("unroll") for (int n = 0; n < 2; ++n) _Pragma("unroll") for (int k = 0; k < 2; ++k) dst[n][k] = *(const PG8_LAS bf16x8*)(lds + PG8_SB(b, h) + boff + n * 2048 + k * 1024); } while (0)
; #define PG8_MMA(ai, bj, At, Bt) do { __builtin_amdgcn_s_setprio(1); _Pragma("unroll") for (int m = 0; m < 4; ++m) _Pragma("unroll") for (int n = 0; n < 2; ++n) _Pragma("unroll") for (int k = 0; k < 2; ++k) \
;         acc[ai][bj][m][n] = __builtin_amdgcn_mfma_f32_16x16x32_bf16(Bt[n][k], At[m][k], acc[ai][bj][m][n], 0, 0, 0); __builtin_amdgcn_s_setprio(0); } while (0)
; #define PG8_WAIT_V(n) asm volatile("s_waitcnt vmcnt(" #n ")" ::: "memory")
; #define PG8_WAIT_L(n) asm volatile("s_waitcnt lgkmcnt(" #n ")" ::: "memory")
; #define PG8_BAR __builtin_amdgcn_s_barrier()
; #define PG8_SCHED __builtin_amdgcn_sched_barrier(0)
; template <class Epi, class Sched, bool ALIGN_EPI = false, bool SP2 = false>
; __device__ __forceinline__ void gemm_phase(PG8_LAS unsigned char* lds, const Gemm g, const Sched& S, const Epi& E) {
;     ...
;             PG8_LDB(B0, 0, 0); PG8_LDB(B1, 0, 1); PG8_SCHED; PG8_LDA(At, 0, 0); PG8_STAGE(PG8_SA(1, 1), a1 + hstep, voffA);
;             PG8_WAIT_V(8); PG8_WAIT_L(0); PG8_BAR; PG8_MMA(0, 0, At, B0); PG8_MMA(0, 1, At, B1); PG8_BAR; PG8_SCHED;
;             PG8_LDA(At, 0, 1); PG8_STAGE(PG8_SB(0, 0), b2, voffB); PG8_STAGE(PG8_SB(0, 1), b2 + hstep, voffB); PG8_STAGE(PG8_SA(0, 0), a2, voffA);
;             PG8_WAIT_V(8); PG8_WAIT_L(0); PG8_BAR; PG8_MMA(1, 0, At, B0); PG8_MMA(1, 1, At, B1); PG8_BAR; PG8_SCHED;
.LBB0_147:
	s_add_u32 s12, s56, 0xfff80080
	s_addc_u32 s13, s57, -1
	s_add_i32 s85, 0, 0x10000
	s_cmp_eq_u32 s84, 28
	s_cselect_b32 s61, s18, s13
	s_cselect_b32 s60, s19, s12
	v_add_u32_e32 v142, s85, v145
	s_cselect_b32 s59, s43, s73
	s_cselect_b32 s58, s47, s72
	s_add_i32 s92, 0, 0x14000
	ds_read_b128 v[148:151], v142
	ds_read_b128 v[152:155], v142 offset:1024
	ds_read_b128 v[156:159], v142 offset:2048
	ds_read_b128 v[160:163], v142 offset:3072
	v_add_u32_e32 v142, s92, v145
	ds_read_b128 v[164:167], v142
	ds_read_b128 v[168:171], v142 offset:1024
	ds_read_b128 v[172:175], v142 offset:2048
	ds_read_b128 v[176:179], v142 offset:3072
	v_lshl_add_u64 v[142:143], s[56:57], 0, v[140:141]
	s_add_i32 m0, s55, 0xc000
	ds_read_b128 v[180:183], v147
	ds_read_b128 v[184:187], v147 offset:1024
	ds_read_b128 v[188:191], v147 offset:2048
	ds_read_b128 v[202:205], v147 offset:3072
	ds_read_b128 v[206:209], v147 offset:4096
	ds_read_b128 v[210:213], v147 offset:5120
	ds_read_b128 v[214:217], v147 offset:6144
	ds_read_b128 v[218:221], v147 offset:7168
	global_load_lds_dwordx4 v[142:143], off
	v_lshl_add_u64 v[142:143], s[56:57], 0, v[138:139]
	s_add_i32 m0, s55, 0xe000
	s_nop 0
	global_load_lds_dwordx4 v[142:143], off
	s_waitcnt vmcnt(8)
	s_waitcnt lgkmcnt(0)
	s_barrier
	s_waitcnt lgkmcnt(0)
	v_mfma_f32_16x16x32_bf16 v[126:129], v[148:151], v[180:183], v[126:129]
	v_mfma_f32_16x16x32_bf16 v[122:125], v[156:159], v[180:183], v[122:125]
	v_mfma_f32_16x16x32_bf16 v[118:121], v[148:151], v[188:191], v[118:121]
	v_mfma_f32_16x16x32_bf16 v[110:113], v[156:159], v[188:191], v[110:113]
	v_mfma_f32_16x16x32_bf16 v[102:105], v[148:151], v[206:209], v[102:105]
	v_mfma_f32_16x16x32_bf16 v[92:95], v[156:159], v[206:209], v[92:95]
	v_mfma_f32_16x16x32_bf16 v[84:87], v[148:151], v[214:217], v[84:87]
	v_mfma_f32_16x16x32_bf16 v[76:79], v[156:159], v[214:217], v[76:79]
	v_mfma_f32_16x16x32_bf16 v[126:129], v[152:155], v[184:187], v[126:129]
	v_mfma_f32_16x16x32_bf16 v[122:125], v[160:163], v[184:187], v[122:125]
	v_mfma_f32_16x16x32_bf16 v[118:121], v[152:155], v[202:205], v[118:121]
	v_mfma_f32_16x16x32_bf16 v[110:113], v[160:163], v[202:205], v[110:113]
	v_mfma_f32_16x16x32_bf16 v[102:105], v[152:155], v[210:213], v[102:105]
	v_mfma_f32_16x16x32_bf16 v[92:95], v[160:163], v[210:213], v[92:95]
	v_mfma_f32_16x16x32_bf16 v[84:87], v[152:155], v[218:221], v[84:87]
	v_mfma_f32_16x16x32_bf16 v[76:79], v[160:163], v[218:221], v[76:79]
	v_mfma_f32_16x16x32_bf16 v[114:117], v[164:167], v[180:183], v[114:117]
	v_mfma_f32_16x16x32_bf16 v[106:109], v[172:175], v[180:183], v[106:109]
	v_mfma_f32_16x16x32_bf16 v[98:101], v[164:167], v[188:191], v[98:101]
	v_mfma_f32_16x16x32_bf16 v[88:91], v[172:175], v[188:191], v[88:91]
	v_mfma_f32_16x16x32_bf16 v[80:83], v[164:167], v[206:209], v[80:83]
	v_mfma_f32_16x16x32_bf16 v[72:75], v[172:175], v[206:209], v[72:75]
	v_mfma_f32_16x16x32_bf16 v[68:71], v[164:167], v[214:217], v[68:71]
	v_mfma_f32_16x16x32_bf16 v[64:67], v[172:175], v[214:217], v[64:67]
	v_mfma_f32_16x16x32_bf16 v[114:117], v[168:171], v[184:187], v[114:117]
	v_mfma_f32_16x16x32_bf16 v[106:109], v[176:179], v[184:187], v[106:109]
	v_mfma_f32_16x16x32_bf16 v[98:101], v[168:171], v[202:205], v[98:101]
	v_mfma_f32_16x16x32_bf16 v[88:91], v[176:179], v[202:205], v[88:91]
	v_mfma_f32_16x16x32_bf16 v[80:83], v[168:171], v[210:213], v[80:83]
	v_mfma_f32_16x16x32_bf16 v[72:75], v[176:179], v[210:213], v[72:75]
	v_mfma_f32_16x16x32_bf16 v[68:71], v[168:171], v[218:221], v[68:71]
	v_mfma_f32_16x16x32_bf16 v[64:67], v[176:179], v[218:221], v[64:67]
	s_barrier
	s_add_i32 s12, s85, s63
	v_lshl_add_u64 v[142:143], s[58:59], 0, v[132:133]
	s_mov_b32 m0, s12
	ds_read_b128 v[180:183], v147 offset:16384
	ds_read_b128 v[184:187], v147 offset:17408
	ds_read_b128 v[188:191], v147 offset:18432
	ds_read_b128 v[202:205], v147 offset:19456
	ds_read_b128 v[206:209], v147 offset:20480
	ds_read_b128 v[210:213], v147 offset:21504
	ds_read_b128 v[214:217], v147 offset:22528
	ds_read_b128 v[218:221], v147 offset:23552
	global_load_lds_dwordx4 v[142:143], off
	s_add_i32 m0, s12, 0x2000
	s_add_u32 s12, s58, 0x80000
	v_lshl_add_u64 v[192:193], s[58:59], 0, v[136:137]
	s_addc_u32 s13, s59, 0
	s_add_i32 s85, s92, s63
	global_load_lds_dwordx4 v[192:193], off
	v_lshl_add_u64 v[222:223], s[12:13], 0, v[132:133]
	s_mov_b32 m0, s85
	v_lshl_add_u64 v[224:225], s[60:61], 0, v[134:135]
	global_load_lds_dwordx4 v[222:223], off
	v_lshl_add_u64 v[222:223], s[12:13], 0, v[136:137]
	s_add_i32 m0, s85, 0x2000
	s_nop 0
	global_load_lds_dwordx4 v[222:223], off
	v_lshl_add_u64 v[222:223], s[60:61], 0, v[130:131]
	s_mov_b32 m0, s55
	s_nop 0
	global_load_lds_dwordx4 v[222:223], off
	s_mov_b32 m0, s64
	s_nop 0
	global_load_lds_dwordx4 v[224:225], off
	s_waitcnt vmcnt(8)
	s_waitcnt lgkmcnt(0)
	s_barrier
; #define PG8_STAGE(bufoff, gbase, voff) do { _Pragma("unroll") for (int _i = 0; _i < 2; ++_i) \
;         __builtin_amdgcn_global_load_lds((const unsigned*)((const char*)(gbase) + (voff)[_i]), (PG8_LAS unsigned*)(lds + (bufoff) + ldsw + _i * 8192), 16, 0, 0); } while (0)
; #define PG8_LDA(dst, b, h) do { _Pragma("unroll") for (int m = 0; m < 4; ++m) _Pragma("unroll") for (int k = 0; k < 2; ++k) dst[m][k] = *(const PG8_LAS bf16x8*)(lds + PG8_SA(b, h) + aoff + m * 2048 + k * 1024); } while (0)
; #define PG8_LDB(dst, b, h) do { _Pragma("unroll") for (int n = 0; n < 2; ++n) _Pragma("unroll") for (int k = 0; k < 2; ++k) dst[n][k] = *(const PG8_LAS bf16x8*)(lds + PG8_SB(b, h) + boff + n * 2048 + k * 1024); } while (0)
; #define PG8_MMA(ai, bj, At, Bt) do { __builtin_amdgcn_s_setprio(1); _Pragma("unroll") for (int m = 0; m < 4; ++m) _Pragma("unroll") for (int n = 0; n < 2; ++n) _Pragma("unroll") for (int k = 0; k < 2; ++k) \
;         acc[ai][bj][m][n] = __builtin_amdgcn_mfma_f32_16x16x32_bf16(Bt[n][k], At[m][k], acc[ai][bj][m][n], 0, 0, 0); __builtin_amdgcn_s_setprio(0); } while (0)
; #define PG8_WAIT_V(n) asm volatile("s_waitcnt vmcnt(" #n ")" ::: "memory")
; #define PG8_WAIT_L(n) asm volatile("s_waitcnt lgkmcnt(" #n ")" ::: "memory")
; #define PG8_BAR __builtin_amdgcn_s_barrier()
; #define PG8_SCHED __builtin_amdgcn_sched_barrier(0)
; template <class Epi, class Sched, bool ALIGN_EPI = false, bool SP2 = false>
; __device__ __forceinline__ void gemm_phase(PG8_LAS unsigned char* lds, const Gemm g, const Sched& S, const Epi& E) {
;     ...
;             PG8_WAIT_V(8); PG8_WAIT_L(0); PG8_BAR; PG8_MMA(1, 0, At, B0); PG8_MMA(1, 1, At, B1); PG8_BAR; PG8_SCHED;
;             PG8_LDB(B0, 1, 0); PG8_LDB(B1, 1, 1); PG8_SCHED; PG8_LDA(At, 1, 0); PG8_STAGE(PG8_SA(0, 1), a2 + hstep, voffA);
;             PG8_WAIT_V(8); PG8_WAIT_L(0); PG8_BAR; PG8_MMA(0, 0, At, B0); PG8_MMA(0, 1, At, B1); PG8_BAR; PG8_SCHED;
	s_waitcnt lgkmcnt(0)
	v_mfma_f32_16x16x32_bf16 v[60:63], v[148:151], v[180:183], v[60:63]
	v_mfma_f32_16x16x32_bf16 v[56:59], v[156:159], v[180:183], v[56:59]
	v_mfma_f32_16x16x32_bf16 v[52:55], v[148:151], v[188:191], v[52:55]
	v_mfma_f32_16x16x32_bf16 v[44:47], v[156:159], v[188:191], v[44:47]
	v_mfma_f32_16x16x32_bf16 v[36:39], v[148:151], v[206:209], v[36:39]
	v_mfma_f32_16x16x32_bf16 v[28:31], v[156:159], v[206:209], v[28:31]
	v_mfma_f32_16x16x32_bf16 v[20:23], v[148:151], v[214:217], v[20:23]
	v_mfma_f32_16x16x32_bf16 v[12:15], v[156:159], v[214:217], v[12:15]
	v_mfma_f32_16x16x32_bf16 v[60:63], v[152:155], v[184:187], v[60:63]
	v_mfma_f32_16x16x32_bf16 v[56:59], v[160:163], v[184:187], v[56:59]
	v_mfma_f32_16x16x32_bf16 v[52:55], v[152:155], v[202:205], v[52:55]
	v_mfma_f32_16x16x32_bf16 v[44:47], v[160:163], v[202:205], v[44:47]
	v_mfma_f32_16x16x32_bf16 v[36:39], v[152:155], v[210:213], v[36:39]
	v_mfma_f32_16x16x32_bf16 v[28:31], v[160:163], v[210:213], v[28:31]
	v_mfma_f32_16x16x32_bf16 v[20:23], v[152:155], v[218:221], v[20:23]
	v_mfma_f32_16x16x32_bf16 v[12:15], v[160:163], v[218:221], v[12:15]
	v_mfma_f32_16x16x32_bf16 v[48:51], v[164:167], v[180:183], v[48:51]
	v_mfma_f32_16x16x32_bf16 v[40:43], v[172:175], v[180:183], v[40:43]
	v_mfma_f32_16x16x32_bf16 v[32:35], v[164:167], v[188:191], v[32:35]
	v_mfma_f32_16x16x32_bf16 v[24:27], v[172:175], v[188:191], v[24:27]
	v_mfma_f32_16x16x32_bf16 v[16:19], v[164:167], v[206:209], v[16:19]
	v_mfma_f32_16x16x32_bf16 v[8:11], v[172:175], v[206:209], v[8:11]
	v_mfma_f32_16x16x32_bf16 v[4:7], v[164:167], v[214:217], v[4:7]
	v_mfma_f32_16x16x32_bf16 v[0:3], v[172:175], v[214:217], v[0:3]
	v_mfma_f32_16x16x32_bf16 v[48:51], v[168:171], v[184:187], v[48:51]
	v_mfma_f32_16x16x32_bf16 v[40:43], v[176:179], v[184:187], v[40:43]
	v_mfma_f32_16x16x32_bf16 v[32:35], v[168:171], v[202:205], v[32:35]
	v_mfma_f32_16x16x32_bf16 v[24:27], v[176:179], v[202:205], v[24:27]
	v_mfma_f32_16x16x32_bf16 v[16:19], v[168:171], v[210:213], v[16:19]
	v_mfma_f32_16x16x32_bf16 v[8:11], v[176:179], v[210:213], v[8:11]
	v_mfma_f32_16x16x32_bf16 v[4:7], v[168:171], v[218:221], v[4:7]
	v_mfma_f32_16x16x32_bf16 v[0:3], v[176:179], v[218:221], v[0:3]
	s_barrier
	s_add_i32 s85, 0, 0x18000
	s_add_i32 s92, 0, 0x1c000
	v_add_u32_e32 v160, s85, v145
	v_add_u32_e32 v176, s92, v145
	ds_read_b128 v[148:151], v160
	ds_read_b128 v[152:155], v160 offset:1024
	ds_read_b128 v[156:159], v160 offset:2048
	ds_read_b128 v[160:163], v160 offset:3072
	ds_read_b128 v[164:167], v176
	ds_read_b128 v[168:171], v176 offset:1024
	ds_read_b128 v[172:175], v176 offset:2048
	ds_read_b128 v[176:179], v176 offset:3072
	s_add_u32 s12, s60, 0x80000
	s_addc_u32 s13, s61, 0
	s_mov_b32 m0, s65
	v_lshl_add_u64 v[226:227], s[12:13], 0, v[130:131]
	ds_read_b128 v[180:183], v147 offset:32768
	ds_read_b128 v[184:187], v147 offset:33792
	ds_read_b128 v[188:191], v147 offset:34816
	ds_read_b128 v[202:205], v147 offset:35840
	ds_read_b128 v[206:209], v147 offset:36864
	ds_read_b128 v[210:213], v147 offset:37888
	ds_read_b128 v[214:217], v147 offset:38912
	ds_read_b128 v[218:221], v147 offset:39936
	global_load_lds_dwordx4 v[226:227], off
	v_lshl_add_u64 v[226:227], s[12:13], 0, v[134:135]
	s_mov_b32 m0, s67
	s_nop 0
	global_load_lds_dwordx4 v[226:227], off
	s_waitcnt vmcnt(8)
	s_waitcnt lgkmcnt(0)
	s_barrier
	s_waitcnt lgkmcnt(0)
	v_mfma_f32_16x16x32_bf16 v[126:129], v[148:151], v[180:183], v[126:129]
	v_mfma_f32_16x16x32_bf16 v[122:125], v[156:159], v[180:183], v[122:125]
	v_mfma_f32_16x16x32_bf16 v[118:121], v[148:151], v[188:191], v[118:121]
	v_mfma_f32_16x16x32_bf16 v[110:113], v[156:159], v[188:191], v[110:113]
	v_mfma_f32_16x16x32_bf16 v[102:105], v[148:151], v[206:209], v[102:105]
	v_mfma_f32_16x16x32_bf16 v[92:95], v[156:159], v[206:209], v[92:95]
	v_mfma_f32_16x16x32_bf16 v[84:87], v[148:151], v[214:217], v[84:87]
	v_mfma_f32_16x16x32_bf16 v[76:79], v[156:159], v[214:217], v[76:79]
	v_mfma_f32_16x16x32_bf16 v[126:129], v[152:155], v[184:187], v[126:129]
	v_mfma_f32_16x16x32_bf16 v[122:125], v[160:163], v[184:187], v[122:125]
	v_mfma_f32_16x16x32_bf16 v[118:121], v[152:155], v[202:205], v[118:121]
	v_mfma_f32_16x16x32_bf16 v[110:113], v[160:163], v[202:205], v[110:113]
	v_mfma_f32_16x16x32_bf16 v[102:105], v[152:155], v[210:213], v[102:105]
	v_mfma_f32_16x16x32_bf16 v[92:95], v[160:163], v[210:213], v[92:95]
	v_mfma_f32_16x16x32_bf16 v[84:87], v[152:155], v[218:221], v[84:87]
	v_mfma_f32_16x16x32_bf16 v[76:79], v[160:163], v[218:221], v[76:79]
	v_mfma_f32_16x16x32_bf16 v[114:117], v[164:167], v[180:183], v[114:117]
	v_mfma_f32_16x16x32_bf16 v[106:109], v[172:175], v[180:183], v[106:109]
	v_mfma_f32_16x16x32_bf16 v[98:101], v[164:167], v[188:191], v[98:101]
	v_mfma_f32_16x16x32_bf16 v[88:91], v[172:175], v[188:191], v[88:91]
	v_mfma_f32_16x16x32_bf16 v[80:83], v[164:167], v[206:209], v[80:83]
	v_mfma_f32_16x16x32_bf16 v[72:75], v[172:175], v[206:209], v[72:75]
	v_mfma_f32_16x16x32_bf16 v[68:71], v[164:167], v[214:217], v[68:71]
	v_mfma_f32_16x16x32_bf16 v[64:67], v[172:175], v[214:217], v[64:67]
	v_mfma_f32_16x16x32_bf16 v[114:117], v[168:171], v[184:187], v[114:117]
	v_mfma_f32_16x16x32_bf16 v[106:109], v[176:179], v[184:187], v[106:109]
	v_mfma_f32_16x16x32_bf16 v[98:101], v[168:171], v[202:205], v[98:101]
	v_mfma_f32_16x16x32_bf16 v[88:91], v[176:179], v[202:205], v[88:91]
	v_mfma_f32_16x16x32_bf16 v[80:83], v[168:171], v[210:213], v[80:83]
	v_mfma_f32_16x16x32_bf16 v[72:75], v[176:179], v[210:213], v[72:75]
	v_mfma_f32_16x16x32_bf16 v[68:71], v[168:171], v[218:221], v[68:71]
	v_mfma_f32_16x16x32_bf16 v[64:67], v[176:179], v[218:221], v[64:67]
	s_barrier
; #define PG8_STAGE(bufoff, gbase, voff) do { _Pragma("unroll") for (int _i = 0; _i < 2; ++_i) \
;         __builtin_amdgcn_global_load_lds((const unsigned*)((const char*)(gbase) + (voff)[_i]), (PG8_LAS unsigned*)(lds + (bufoff) + ldsw + _i * 8192), 16, 0, 0); } while (0)
; #define PG8_LDA(dst, b, h) do { _Pragma("unroll") for (int m = 0; m < 4; ++m) _Pragma("unroll") for (int k = 0; k < 2; ++k) dst[m][k] = *(const PG8_LAS bf16x8*)(lds + PG8_SA(b, h) + aoff + m * 2048 + k * 1024); } while (0)
; #define PG8_MMA(ai, bj, At, Bt) do { __builtin_amdgcn_s_setprio(1); _Pragma("unroll") for (int m = 0; m < 4; ++m) _Pragma("unroll") for (int n = 0; n < 2; ++n) _Pragma("unroll") for (int k = 0; k < 2; ++k) \
;         acc[ai][bj][m][n] = __builtin_amdgcn_mfma_f32_16x16x32_bf16(Bt[n][k], At[m][k], acc[ai][bj][m][n], 0, 0, 0); __builtin_amdgcn_s_setprio(0); } while (0)
; #define PG8_WAIT_V(n) asm volatile("s_waitcnt vmcnt(" #n ")" ::: "memory")
; #define PG8_WAIT_L(n) asm volatile("s_waitcnt lgkmcnt(" #n ")" ::: "memory")
; #define PG8_BAR __builtin_amdgcn_s_barrier()
; #define PG8_SCHED __builtin_amdgcn_sched_barrier(0)
; template <class Epi, class Sched, bool ALIGN_EPI = false, bool SP2 = false>
; __device__ __forceinline__ void gemm_phase(PG8_LAS unsigned char* lds, const Gemm g, const Sched& S, const Epi& E) {
;     ...
;             PG8_LDA(At, 1, 1); PG8_STAGE(PG8_SB(1, 0), b3, voffB); PG8_STAGE(PG8_SB(1, 1), b3 + hstep, voffB); PG8_STAGE(PG8_SA(1, 0), a3, voffA);
;             PG8_WAIT_V(8); PG8_WAIT_L(0); PG8_BAR; PG8_MMA(1, 0, At, B0); PG8_MMA(1, 1, At, B1); PG8_BAR; PG8_SCHED;
	s_add_i32 s12, s85, s63
	v_lshl_add_u64 v[142:143], v[142:143], 0, s[36:37]
	s_mov_b32 m0, s12
	ds_read_b128 v[180:183], v147 offset:49152
	ds_read_b128 v[184:187], v147 offset:50176
	ds_read_b128 v[188:191], v147 offset:51200
	ds_read_b128 v[202:205], v147 offset:52224
	ds_read_b128 v[206:209], v147 offset:53248
	ds_read_b128 v[210:213], v147 offset:54272
	ds_read_b128 v[214:217], v147 offset:55296
	ds_read_b128 v[218:221], v147 offset:56320
	global_load_lds_dwordx4 v[142:143], off
	s_add_i32 m0, s12, 0x2000
	s_add_u32 s12, s58, 0x80080
	v_lshl_add_u64 v[142:143], v[192:193], 0, s[36:37]
	s_addc_u32 s13, s59, 0
	s_add_i32 s58, s92, s63
	global_load_lds_dwordx4 v[142:143], off
	v_lshl_add_u64 v[142:143], s[12:13], 0, v[132:133]
	s_mov_b32 m0, s58
	s_nop 0
	global_load_lds_dwordx4 v[142:143], off
	v_lshl_add_u64 v[142:143], s[12:13], 0, v[136:137]
	s_add_i32 m0, s58, 0x2000
	s_nop 0
	global_load_lds_dwordx4 v[142:143], off
	v_lshl_add_u64 v[142:143], v[222:223], 0, s[36:37]
	s_mov_b32 m0, s68
	s_nop 0
	global_load_lds_dwordx4 v[142:143], off
	v_lshl_add_u64 v[142:143], v[224:225], 0, s[36:37]
	s_mov_b32 m0, s69
	s_nop 0
	global_load_lds_dwordx4 v[142:143], off
	s_waitcnt vmcnt(8)
	s_waitcnt lgkmcnt(0)
	s_barrier
	s_waitcnt lgkmcnt(0)
	v_mfma_f32_16x16x32_bf16 v[60:63], v[148:151], v[180:183], v[60:63]
	v_mfma_f32_16x16x32_bf16 v[56:59], v[156:159], v[180:183], v[56:59]
	v_mfma_f32_16x16x32_bf16 v[52:55], v[148:151], v[188:191], v[52:55]
	v_mfma_f32_16x16x32_bf16 v[44:47], v[156:159], v[188:191], v[44:47]
	v_mfma_f32_16x16x32_bf16 v[36:39], v[148:151], v[206:209], v[36:39]
	v_mfma_f32_16x16x32_bf16 v[28:31], v[156:159], v[206:209], v[28:31]
	v_mfma_f32_16x16x32_bf16 v[20:23], v[148:151], v[214:217], v[20:23]
	v_mfma_f32_16x16x32_bf16 v[12:15], v[156:159], v[214:217], v[12:15]
	v_mfma_f32_16x16x32_bf16 v[60:63], v[152:155], v[184:187], v[60:63]
	v_mfma_f32_16x16x32_bf16 v[56:59], v[160:163], v[184:187], v[56:59]
	v_mfma_f32_16x16x32_bf16 v[52:55], v[152:155], v[202:205], v[52:55]
	v_mfma_f32_16x16x32_bf16 v[44:47], v[160:163], v[202:205], v[44:47]
	v_mfma_f32_16x16x32_bf16 v[36:39], v[152:155], v[210:213], v[36:39]
	v_mfma_f32_16x16x32_bf16 v[28:31], v[160:163], v[210:213], v[28:31]
	v_mfma_f32_16x16x32_bf16 v[20:23], v[152:155], v[218:221], v[20:23]
	v_mfma_f32_16x16x32_bf16 v[12:15], v[160:163], v[218:221], v[12:15]
	v_mfma_f32_16x16x32_bf16 v[48:51], v[164:167], v[180:183], v[48:51]
	v_mfma_f32_16x16x32_bf16 v[40:43], v[172:175], v[180:183], v[40:43]
	v_mfma_f32_16x16x32_bf16 v[32:35], v[164:167], v[188:191], v[32:35]
	v_mfma_f32_16x16x32_bf16 v[24:27], v[172:175], v[188:191], v[24:27]
	v_mfma_f32_16x16x32_bf16 v[16:19], v[164:167], v[206:209], v[16:19]
	v_mfma_f32_16x16x32_bf16 v[8:11], v[172:175], v[206:209], v[8:11]
	v_mfma_f32_16x16x32_bf16 v[4:7], v[164:167], v[214:217], v[4:7]
	v_mfma_f32_16x16x32_bf16 v[0:3], v[172:175], v[214:217], v[0:3]
	v_mfma_f32_16x16x32_bf16 v[48:51], v[168:171], v[184:187], v[48:51]
	v_mfma_f32_16x16x32_bf16 v[40:43], v[176:179], v[184:187], v[40:43]
	v_mfma_f32_16x16x32_bf16 v[32:35], v[168:171], v[202:205], v[32:35]
	v_mfma_f32_16x16x32_bf16 v[24:27], v[176:179], v[202:205], v[24:27]
	v_mfma_f32_16x16x32_bf16 v[16:19], v[168:171], v[210:213], v[16:19]
	v_mfma_f32_16x16x32_bf16 v[8:11], v[176:179], v[210:213], v[8:11]
	v_mfma_f32_16x16x32_bf16 v[4:7], v[168:171], v[218:221], v[4:7]
	v_mfma_f32_16x16x32_bf16 v[0:3], v[176:179], v[218:221], v[0:3]
	s_barrier
	s_add_i32 s84, s84, 2
	s_add_u32 s72, s72, 0x100
	s_addc_u32 s73, s73, 0
	s_add_u32 s56, s56, 0x100
	s_addc_u32 s57, s57, 0
	s_cmp_gt_u32 s84, 29
	s_cbranch_scc0 .LBB0_147
	s_and_b64 vcc, exec, s[14:15]
	s_cbranch_vccz .LBB0_150
	s_barrier

; #define PG8_WAIT_V(n) asm volatile("s_waitcnt vmcnt(" #n ")" ::: "memory")
; #define PG8_BAR __builtin_amdgcn_s_barrier()
; template <class Epi, class Sched, bool ALIGN_EPI = false, bool SP2 = false>
; __device__ __forceinline__ void gemm_phase(PG8_LAS unsigned char* lds, const Gemm g, const Sched& S, const Epi& E) {
;     ...
;     PG8_WAIT_V(0);
;     if constexpr (!ALIGN_EPI) { if (wr == 0) PG8_BAR; }
;     PG8_BAR;
.LBB0_153:
	s_setprio 0
	s_waitcnt vmcnt(0)
	s_barrier

; #define PG8_STAGE(bufoff, gbase, voff) do { _Pragma("unroll") for (int _i = 0; _i < 2; ++_i) \
;         __builtin_amdgcn_global_load_lds((const unsigned*)((const char*)(gbase) + (voff)[_i]), (PG8_LAS unsigned*)(lds + (bufoff) + ldsw + _i * 8192), 16, 0, 0); } while (0)
; #define PG8_BAR __builtin_amdgcn_s_barrier()
; template <class Epi, class Sched, bool ALIGN_EPI = false, bool SP2 = false>
; __device__ __forceinline__ void gemm_phase(PG8_LAS unsigned char* lds, const Gemm g, const Sched& S, const Epi& E) {
;     ...
;     for (int i = 0; i < 2; ++i) { int R, C; stage_rc(tid * 16 + i * 8192, R, C); const int Rb = Epi::PERM ? ((R & ~31) + perm32(R & 31)) : R;
;         voffA[i] = (unsigned)(R * K + C) * 2u; voffB[i] = (unsigned)(Rb * K + C) * 2u; }
;     ...
;         PG8_STAGE(PG8_SB(0, 0), cB, voffB); PG8_STAGE(PG8_SB(0, 1), cB + hstep, voffB); PG8_STAGE(PG8_SA(0, 0), cA, voffA); PG8_STAGE(PG8_SA(0, 1), cA + hstep, voffA);
;         if (wr == 1) PG8_BAR;
.LBB0_166:
	s_and_b64 vcc, exec, s[40:41]
	s_cbranch_vccnz .LBB0_214
	v_ashrrev_i32_e32 v1, 31, v14
	v_lshrrev_b32_e32 v1, 26, v1
	v_add_u32_e32 v1, v14, v1
	v_ashrrev_i32_e32 v8, 6, v1
	v_bfe_i32 v1, v14, 27, 1
	v_lshlrev_b32_e32 v0, 4, v14
	v_lshrrev_b32_e32 v1, 22, v1
	v_add_u32_e32 v1, v0, v1
	v_and_b32_e32 v1, 0xfffffc00, v1
	v_sub_u32_e32 v1, v0, v1
	v_lshrrev_b32_e32 v2, 4, v1
	v_bitop3_b32 v1, v2, v1, 32 bitop3:0x6c
	v_ashrrev_i32_e32 v3, 31, v1
	v_lshrrev_b32_e32 v3, 26, v3
	v_add_u32_e32 v3, v1, v3
	v_lshlrev_b32_e32 v2, 3, v8
	v_ashrrev_i32_e32 v9, 6, v3
	v_and_b32_e32 v3, 0xc0, v3
	v_and_b32_e32 v2, -16, v2
	v_sub_u32_e32 v1, v1, v3
	v_add_u32_e32 v2, v9, v2
	v_ashrrev_i16_sdwa v1, v240, sext(v1) dst_sel:DWORD dst_unused:UNUSED_PAD src0_sel:DWORD src1_sel:BYTE_0
	v_lshlrev_b32_e32 v4, 5, v8
	v_bfe_i32 v10, v1, 0, 16
	v_lshlrev_b32_e32 v1, 1, v2
	v_lshrrev_b32_e32 v3, 2, v2
	v_and_b32_e32 v5, 3, v9
	s_mov_b32 s4, 0xfffe0
	v_and_b32_e32 v4, 32, v4
	v_and_b32_e32 v1, 24, v1
	v_and_b32_e32 v3, 4, v3
	v_and_or_b32 v5, v2, s4, v5
	v_or3_b32 v1, v5, v3, v1
	v_add_lshl_u32 v3, v4, v10, 1
	v_add_u32_e32 v0, 0x2000, v0
	v_lshl_add_u32 v132, v1, 12, v3
	v_ashrrev_i32_e32 v1, 31, v0
	v_lshrrev_b32_e32 v1, 22, v1
	v_add_u32_e32 v1, v0, v1
	v_ashrrev_i32_e32 v11, 10, v1
	v_mul_i32_i24_e32 v1, 0x400, v11
	v_sub_u32_e32 v0, v0, v1
	v_lshrrev_b32_e32 v1, 4, v0
	v_bitop3_b32 v0, v1, v0, 32 bitop3:0x6c
	v_lshl_add_u32 v130, v2, 12, v3
	v_ashrrev_i32_e32 v2, 31, v0
	v_lshrrev_b32_e32 v2, 26, v2
	v_lshlrev_b32_e32 v1, 3, v11
	v_add_u32_e32 v2, v0, v2
	v_and_b32_e32 v1, -16, v1
	v_ashrrev_i32_e32 v12, 6, v2
	v_add_u32_e32 v1, v12, v1
	v_and_b32_e32 v4, 3, v12
	v_and_or_b32 v4, v1, s4, v4
	s_ashr_i32 s4, s0, 6
	s_mul_i32 s26, s7, 0x500000
	s_ashr_i32 s1, s0, 8
	s_lshl_b32 s70, s4, 10
	s_lshl_b64 s[10:11], s[26:27], 1
	s_add_u32 s5, s48, s10
	s_addc_u32 s10, s49, s11
	s_add_u32 s26, s5, 0x2f00000
	v_and_b32_e32 v2, 0xc0, v2
	s_addc_u32 s71, s10, 0
	s_ashr_i32 s15, s14, 31
	s_ashr_i32 s61, s60, 31
	v_sub_u32_e32 v0, v0, v2
	s_lshl_b64 s[10:11], s[14:15], 20
	s_lshl_b64 s[12:13], s[60:61], 20
	v_ashrrev_i16_sdwa v0, v240, sext(v0) dst_sel:DWORD dst_unused:UNUSED_PAD src0_sel:DWORD src1_sel:BYTE_0
	s_add_u32 s42, s26, s12
	v_lshlrev_b32_e32 v3, 5, v11
	v_bfe_i32 v13, v0, 0, 16
	v_lshlrev_b32_e32 v0, 1, v1
	v_lshrrev_b32_e32 v2, 2, v1
	s_addc_u32 s43, s71, s13
	s_add_i32 s61, s70, 0
	v_and_b32_e32 v3, 32, v3
	v_and_b32_e32 v0, 24, v0
	v_and_b32_e32 v2, 4, v2
	s_add_i32 m0, s61, 0x10000
	v_or3_b32 v0, v4, v2, v0
	v_add_lshl_u32 v2, v3, v13, 1
	global_load_lds_dwordx4 v132, s[42:43]
	s_add_i32 m0, s61, 0x12000
	v_lshl_add_u32 v136, v0, 12, v2
	s_add_u32 s12, s42, 0x80000
	global_load_lds_dwordx4 v136, s[42:43]
	s_addc_u32 s13, s43, 0
	s_add_i32 m0, s61, 0x14000
	v_lshl_add_u32 v134, v1, 12, v2
	global_load_lds_dwordx4 v132, s[12:13]
	s_add_i32 m0, s61, 0x16000
	s_add_u32 s62, s67, s10
	s_addc_u32 s63, s68, s11
	s_add_i32 s72, s61, 0x2000
	global_load_lds_dwordx4 v136, s[12:13]
	s_mov_b32 m0, s61
	s_add_u32 s10, s62, 0x80000
	global_load_lds_dwordx4 v130, s[62:63]
	s_mov_b32 m0, s72
	s_addc_u32 s11, s63, 0
	s_add_i32 s73, s61, 0x4000
	global_load_lds_dwordx4 v134, s[62:63]
	s_mov_b32 m0, s73
	s_add_i32 s84, s61, 0x6000
	global_load_lds_dwordx4 v130, s[10:11]
	s_mov_b32 m0, s84
	v_mov_b32_e32 v133, v96
	global_load_lds_dwordx4 v134, s[10:11]
	v_mov_b32_e32 v137, v96
	v_mov_b32_e32 v131, v96
	v_mov_b32_e32 v135, v96
	s_cmp_eq_u32 s1, 1
	v_lshl_add_u64 v[6:7], s[42:43], 0, v[132:133]
	v_lshl_add_u64 v[4:5], s[42:43], 0, v[136:137]
	v_lshl_add_u64 v[0:1], s[62:63], 0, v[130:131]
	s_cselect_b64 s[52:53], -1, 0
	s_cmp_lg_u32 s1, 1
	v_lshl_add_u64 v[2:3], s[62:63], 0, v[134:135]
	s_cbranch_scc1 .LBB0_169
	s_barrier
	s_setprio 1

; #define PG8_STAGE(bufoff, gbase, voff) do { _Pragma("unroll") for (int _i = 0; _i < 2; ++_i) \
;         __builtin_amdgcn_global_load_lds((const unsigned*)((const char*)(gbase) + (voff)[_i]), (PG8_LAS unsigned*)(lds + (bufoff) + ldsw + _i * 8192), 16, 0, 0); } while (0)
; #define PG8_LDA(dst, b, h) do { _Pragma("unroll") for (int m = 0; m < 4; ++m) _Pragma("unroll") for (int k = 0; k < 2; ++k) dst[m][k] = *(const PG8_LAS bf16x8*)(lds + PG8_SA(b, h) + aoff + m * 2048 + k * 1024); } while (0)
; #define PG8_LDB(dst, b, h) do { _Pragma("unroll") for (int n = 0; n < 2; ++n) _Pragma("unroll") for (int k = 0; k < 2; ++k) dst[n][k] = *(const PG8_LAS bf16x8*)(lds + PG8_SB(b, h) + boff + n * 2048 + k * 1024); } while (0)
; #define PG8_MMA(ai, bj, At, Bt) do { __builtin_amdgcn_s_setprio(1); _Pragma("unroll") for (int m = 0; m < 4; ++m) _Pragma("unroll") for (int n = 0; n < 2; ++n) _Pragma("unroll") for (int k = 0; k < 2; ++k) \
;         acc[ai][bj][m][n] = __builtin_amdgcn_mfma_f32_16x16x32_bf16(Bt[n][k], At[m][k], acc[ai][bj][m][n], 0, 0, 0); __builtin_amdgcn_s_setprio(0); } while (0)
; #define PG8_WAIT_V(n) asm volatile("s_waitcnt vmcnt(" #n ")" ::: "memory")
; #define PG8_WAIT_L(n) asm volatile("s_waitcnt lgkmcnt(" #n ")" ::: "memory")
; #define PG8_BAR __builtin_amdgcn_s_barrier()
; #define PG8_SCHED __builtin_amdgcn_sched_barrier(0)
; template <class Epi, class Sched, bool ALIGN_EPI = false, bool SP2 = false>
; __device__ __forceinline__ void gemm_phase(PG8_LAS unsigned char* lds, const Gemm g, const Sched& S, const Epi& E) {
;     ...
;         for (int t = 0; t < nt; t += 2) {
;             const bool last = (t == nt - 2);
;             const char* a1 = cA + (size_t)(t + 1) * kstep;
;             const char* a2 = last ? nA : cA + (size_t)(t + 2) * kstep; const char* b2 = last ? nB : cB + (size_t)(t + 2) * kstep;
;             const char* a3 = a2 + kstep; const char* b3 = b2 + kstep;
;             if (last && has_next) S.a_ready(nxt);
;             if constexpr (SP2) {
;             PG8_LDB(B0, 0, 0); PG8_LDB(B1, 0, 1); PG8_SCHED; PG8_LDA(At, 0, 0); PG8_STAGE(PG8_SA(1, 1), a1 + hstep, voffA);
;             PG8_WAIT_V(8); PG8_WAIT_L(0); PG8_BAR; PG8_MMA(0, 0, At, B0); PG8_MMA(0, 1, At, B1); PG8_BAR; PG8_SCHED;
;             PG8_LDA(At, 0, 1); PG8_STAGE(PG8_SB(0, 0), b2, voffB); PG8_STAGE(PG8_SB(0, 1), b2 + hstep, voffB); PG8_STAGE(PG8_SA(0, 0), a2, voffA);
.LBB0_175:
	s_add_u32 s12, s42, 0xfff80080
	s_addc_u32 s13, s43, -1
	s_add_i32 vcc_lo, 0, 0x10000
	s_cmp_eq_u32 s55, 28
	s_cselect_b32 s65, s10, s13
	s_cselect_b32 s64, s11, s12
	v_add_u32_e32 v148, vcc_lo, v150
	s_cselect_b32 s63, s5, s19
	s_cselect_b32 s62, s15, s18
	s_add_i32 vcc_hi, 0, 0x14000
	ds_read_b128 v[144:147], v148
	ds_read_b128 v[154:157], v148 offset:1024
	ds_read_b128 v[158:161], v148 offset:2048
	ds_read_b128 v[162:165], v148 offset:3072
	v_add_u32_e32 v148, vcc_hi, v150
	ds_read_b128 v[166:169], v148
	ds_read_b128 v[170:173], v148 offset:1024
	ds_read_b128 v[174:177], v148 offset:2048
	ds_read_b128 v[178:181], v148 offset:3072
	v_lshl_add_u64 v[222:223], s[42:43], 0, v[142:143]
	s_add_i32 m0, s61, 0xc000
	ds_read_b128 v[182:185], v153
	ds_read_b128 v[186:189], v153 offset:1024
	ds_read_b128 v[190:193], v153 offset:2048
	ds_read_b128 v[202:205], v153 offset:3072
	ds_read_b128 v[206:209], v153 offset:4096
	ds_read_b128 v[210:213], v153 offset:5120
	ds_read_b128 v[214:217], v153 offset:6144
	ds_read_b128 v[218:221], v153 offset:7168
	global_load_lds_dwordx4 v[222:223], off
	v_lshl_add_u64 v[222:223], s[42:43], 0, v[140:141]
	s_add_i32 m0, s61, 0xe000
	s_nop 0
	global_load_lds_dwordx4 v[222:223], off
	s_waitcnt vmcnt(8)
	s_waitcnt lgkmcnt(0)
	s_barrier
	s_waitcnt lgkmcnt(0)
	v_mfma_f32_16x16x32_bf16 v[126:129], v[144:147], v[182:185], v[126:129]
	v_mfma_f32_16x16x32_bf16 v[122:125], v[158:161], v[182:185], v[122:125]
	v_mfma_f32_16x16x32_bf16 v[110:113], v[144:147], v[190:193], v[110:113]
	v_mfma_f32_16x16x32_bf16 v[106:109], v[158:161], v[190:193], v[106:109]
	v_mfma_f32_16x16x32_bf16 v[92:95], v[144:147], v[206:209], v[92:95]
	v_mfma_f32_16x16x32_bf16 v[88:91], v[158:161], v[206:209], v[88:91]
	v_mfma_f32_16x16x32_bf16 v[76:79], v[144:147], v[214:217], v[76:79]
	v_mfma_f32_16x16x32_bf16 v[72:75], v[158:161], v[214:217], v[72:75]
	v_mfma_f32_16x16x32_bf16 v[126:129], v[154:157], v[186:189], v[126:129]
	v_mfma_f32_16x16x32_bf16 v[122:125], v[162:165], v[186:189], v[122:125]
	v_mfma_f32_16x16x32_bf16 v[110:113], v[154:157], v[202:205], v[110:113]
	v_mfma_f32_16x16x32_bf16 v[106:109], v[162:165], v[202:205], v[106:109]
	v_mfma_f32_16x16x32_bf16 v[92:95], v[154:157], v[210:213], v[92:95]
	v_mfma_f32_16x16x32_bf16 v[88:91], v[162:165], v[210:213], v[88:91]
	v_mfma_f32_16x16x32_bf16 v[76:79], v[154:157], v[218:221], v[76:79]
	v_mfma_f32_16x16x32_bf16 v[72:75], v[162:165], v[218:221], v[72:75]
	v_mfma_f32_16x16x32_bf16 v[118:121], v[166:169], v[182:185], v[118:121]
	v_mfma_f32_16x16x32_bf16 v[114:117], v[174:177], v[182:185], v[114:117]
	v_mfma_f32_16x16x32_bf16 v[102:105], v[166:169], v[190:193], v[102:105]
	v_mfma_f32_16x16x32_bf16 v[98:101], v[174:177], v[190:193], v[98:101]
	v_mfma_f32_16x16x32_bf16 v[84:87], v[166:169], v[206:209], v[84:87]
	v_mfma_f32_16x16x32_bf16 v[80:83], v[174:177], v[206:209], v[80:83]
	v_mfma_f32_16x16x32_bf16 v[68:71], v[166:169], v[214:217], v[68:71]
	v_mfma_f32_16x16x32_bf16 v[64:67], v[174:177], v[214:217], v[64:67]
	v_mfma_f32_16x16x32_bf16 v[118:121], v[170:173], v[186:189], v[118:121]
	v_mfma_f32_16x16x32_bf16 v[114:117], v[178:181], v[186:189], v[114:117]
	v_mfma_f32_16x16x32_bf16 v[102:105], v[170:173], v[202:205], v[102:105]
	v_mfma_f32_16x16x32_bf16 v[98:101], v[178:181], v[202:205], v[98:101]
	v_mfma_f32_16x16x32_bf16 v[84:87], v[170:173], v[210:213], v[84:87]
	v_mfma_f32_16x16x32_bf16 v[80:83], v[178:181], v[210:213], v[80:83]
	v_mfma_f32_16x16x32_bf16 v[68:71], v[170:173], v[218:221], v[68:71]
	v_mfma_f32_16x16x32_bf16 v[64:67], v[178:181], v[218:221], v[64:67]
	s_barrier
	s_add_i32 s12, vcc_lo, s70
	v_lshl_add_u64 v[222:223], s[62:63], 0, v[132:133]
	s_mov_b32 m0, s12
	ds_read_b128 v[182:185], v153 offset:16384
	ds_read_b128 v[186:189], v153 offset:17408
	ds_read_b128 v[190:193], v153 offset:18432
	ds_read_b128 v[202:205], v153 offset:19456
	ds_read_b128 v[206:209], v153 offset:20480
	ds_read_b128 v[210:213], v153 offset:21504
	ds_read_b128 v[214:217], v153 offset:22528
	ds_read_b128 v[218:221], v153 offset:23552
	global_load_lds_dwordx4 v[222:223], off
	s_add_i32 m0, s12, 0x2000
	s_add_u32 s12, s62, 0x80000
	v_lshl_add_u64 v[224:225], s[62:63], 0, v[136:137]
	s_addc_u32 s13, s63, 0
	s_add_i32 vcc_lo, vcc_hi, s70
	global_load_lds_dwordx4 v[224:225], off
	v_lshl_add_u64 v[226:227], s[12:13], 0, v[132:133]
	s_mov_b32 m0, vcc_lo
	v_lshl_add_u64 v[228:229], s[64:65], 0, v[134:135]
	global_load_lds_dwordx4 v[226:227], off
	v_lshl_add_u64 v[226:227], s[12:13], 0, v[136:137]
	s_add_i32 m0, vcc_lo, 0x2000
	s_nop 0
	global_load_lds_dwordx4 v[226:227], off
	v_lshl_add_u64 v[226:227], s[64:65], 0, v[130:131]
	s_mov_b32 m0, s61
	s_nop 0
	global_load_lds_dwordx4 v[226:227], off
	s_mov_b32 m0, s72
	s_nop 0
	global_load_lds_dwordx4 v[228:229], off
	s_waitcnt vmcnt(8)
	s_waitcnt lgkmcnt(0)
	s_barrier
; #define PG8_STAGE(bufoff, gbase, voff) do { _Pragma("unroll") for (int _i = 0; _i < 2; ++_i) \
;         __builtin_amdgcn_global_load_lds((const unsigned*)((const char*)(gbase) + (voff)[_i]), (PG8_LAS unsigned*)(lds + (bufoff) + ldsw + _i * 8192), 16, 0, 0); } while (0)
; #define PG8_LDA(dst, b, h) do { _Pragma("unroll") for (int m = 0; m < 4; ++m) _Pragma("unroll") for (int k = 0; k < 2; ++k) dst[m][k] = *(const PG8_LAS bf16x8*)(lds + PG8_SA(b, h) + aoff + m * 2048 + k * 1024); } while (0)
; #define PG8_LDB(dst, b, h) do { _Pragma("unroll") for (int n = 0; n < 2; ++n) _Pragma("unroll") for (int k = 0; k < 2; ++k) dst[n][k] = *(const PG8_LAS bf16x8*)(lds + PG8_SB(b, h) + boff + n * 2048 + k * 1024); } while (0)
; #define PG8_MMA(ai, bj, At, Bt) do { __builtin_amdgcn_s_setprio(1); _Pragma("unroll") for (int m = 0; m < 4; ++m) _Pragma("unroll") for (int n = 0; n < 2; ++n) _Pragma("unroll") for (int k = 0; k < 2; ++k) \
;         acc[ai][bj][m][n] = __builtin_amdgcn_mfma_f32_16x16x32_bf16(Bt[n][k], At[m][k], acc[ai][bj][m][n], 0, 0, 0); __builtin_amdgcn_s_setprio(0); } while (0)
; #define PG8_WAIT_V(n) asm volatile("s_waitcnt vmcnt(" #n ")" ::: "memory")
; #define PG8_WAIT_L(n) asm volatile("s_waitcnt lgkmcnt(" #n ")" ::: "memory")
; #define PG8_BAR __builtin_amdgcn_s_barrier()
; #define PG8_SCHED __builtin_amdgcn_sched_barrier(0)
; template <class Epi, class Sched, bool ALIGN_EPI = false, bool SP2 = false>
; __device__ __forceinline__ void gemm_phase(PG8_LAS unsigned char* lds, const Gemm g, const Sched& S, const Epi& E) {
;     ...
;             PG8_WAIT_V(8); PG8_WAIT_L(0); PG8_BAR; PG8_MMA(1, 0, At, B0); PG8_MMA(1, 1, At, B1); PG8_BAR; PG8_SCHED;
;             PG8_LDB(B0, 1, 0); PG8_LDB(B1, 1, 1); PG8_SCHED; PG8_LDA(At, 1, 0); PG8_STAGE(PG8_SA(0, 1), a2 + hstep, voffA);
;             PG8_WAIT_V(8); PG8_WAIT_L(0); PG8_BAR; PG8_MMA(0, 0, At, B0); PG8_MMA(0, 1, At, B1); PG8_BAR; PG8_SCHED;
	s_waitcnt lgkmcnt(0)
	v_mfma_f32_16x16x32_bf16 v[60:63], v[144:147], v[182:185], v[60:63]
	v_mfma_f32_16x16x32_bf16 v[56:59], v[158:161], v[182:185], v[56:59]
	v_mfma_f32_16x16x32_bf16 v[44:47], v[144:147], v[190:193], v[44:47]
	v_mfma_f32_16x16x32_bf16 v[40:43], v[158:161], v[190:193], v[40:43]
	v_mfma_f32_16x16x32_bf16 v[28:31], v[144:147], v[206:209], v[28:31]
	v_mfma_f32_16x16x32_bf16 v[24:27], v[158:161], v[206:209], v[24:27]
	v_mfma_f32_16x16x32_bf16 v[12:15], v[144:147], v[214:217], v[12:15]
	v_mfma_f32_16x16x32_bf16 v[8:11], v[158:161], v[214:217], v[8:11]
	v_mfma_f32_16x16x32_bf16 v[60:63], v[154:157], v[186:189], v[60:63]
	v_mfma_f32_16x16x32_bf16 v[56:59], v[162:165], v[186:189], v[56:59]
	v_mfma_f32_16x16x32_bf16 v[44:47], v[154:157], v[202:205], v[44:47]
	v_mfma_f32_16x16x32_bf16 v[40:43], v[162:165], v[202:205], v[40:43]
	v_mfma_f32_16x16x32_bf16 v[28:31], v[154:157], v[210:213], v[28:31]
	v_mfma_f32_16x16x32_bf16 v[24:27], v[162:165], v[210:213], v[24:27]
	v_mfma_f32_16x16x32_bf16 v[12:15], v[154:157], v[218:221], v[12:15]
	v_mfma_f32_16x16x32_bf16 v[8:11], v[162:165], v[218:221], v[8:11]
	v_mfma_f32_16x16x32_bf16 v[52:55], v[166:169], v[182:185], v[52:55]
	v_mfma_f32_16x16x32_bf16 v[48:51], v[174:177], v[182:185], v[48:51]
	v_mfma_f32_16x16x32_bf16 v[36:39], v[166:169], v[190:193], v[36:39]
	v_mfma_f32_16x16x32_bf16 v[32:35], v[174:177], v[190:193], v[32:35]
	v_mfma_f32_16x16x32_bf16 v[20:23], v[166:169], v[206:209], v[20:23]
	v_mfma_f32_16x16x32_bf16 v[16:19], v[174:177], v[206:209], v[16:19]
	v_mfma_f32_16x16x32_bf16 v[4:7], v[166:169], v[214:217], v[4:7]
	v_mfma_f32_16x16x32_bf16 v[0:3], v[174:177], v[214:217], v[0:3]
	v_mfma_f32_16x16x32_bf16 v[52:55], v[170:173], v[186:189], v[52:55]
	v_mfma_f32_16x16x32_bf16 v[48:51], v[178:181], v[186:189], v[48:51]
	v_mfma_f32_16x16x32_bf16 v[36:39], v[170:173], v[202:205], v[36:39]
	v_mfma_f32_16x16x32_bf16 v[32:35], v[178:181], v[202:205], v[32:35]
	v_mfma_f32_16x16x32_bf16 v[20:23], v[170:173], v[210:213], v[20:23]
	v_mfma_f32_16x16x32_bf16 v[16:19], v[178:181], v[210:213], v[16:19]
	v_mfma_f32_16x16x32_bf16 v[4:7], v[170:173], v[218:221], v[4:7]
	v_mfma_f32_16x16x32_bf16 v[0:3], v[178:181], v[218:221], v[0:3]
	s_barrier
	s_add_i32 vcc_lo, 0, 0x18000
	v_add_u32_e32 v148, vcc_lo, v150
	s_add_i32 vcc_hi, 0, 0x1c000
	ds_read_b128 v[144:147], v148
	ds_read_b128 v[154:157], v148 offset:1024
	ds_read_b128 v[158:161], v148 offset:2048
	ds_read_b128 v[162:165], v148 offset:3072
	v_add_u32_e32 v148, vcc_hi, v150
	ds_read_b128 v[166:169], v148
	ds_read_b128 v[170:173], v148 offset:1024
	ds_read_b128 v[174:177], v148 offset:2048
	ds_read_b128 v[178:181], v148 offset:3072
	s_add_u32 s12, s64, 0x80000
	s_addc_u32 s13, s65, 0
	s_mov_b32 m0, s73
	v_lshl_add_u64 v[230:231], s[12:13], 0, v[130:131]
	ds_read_b128 v[182:185], v153 offset:32768
	ds_read_b128 v[186:189], v153 offset:33792
	ds_read_b128 v[190:193], v153 offset:34816
	ds_read_b128 v[202:205], v153 offset:35840
	ds_read_b128 v[206:209], v153 offset:36864
	ds_read_b128 v[210:213], v153 offset:37888
	ds_read_b128 v[214:217], v153 offset:38912
	ds_read_b128 v[218:221], v153 offset:39936
	global_load_lds_dwordx4 v[230:231], off
	v_lshl_add_u64 v[230:231], s[12:13], 0, v[134:135]
	s_mov_b32 m0, s84
	s_nop 0
	global_load_lds_dwordx4 v[230:231], off
	s_waitcnt vmcnt(8)
	s_waitcnt lgkmcnt(0)
	s_barrier
	s_waitcnt lgkmcnt(0)
	v_mfma_f32_16x16x32_bf16 v[126:129], v[144:147], v[182:185], v[126:129]
	v_mfma_f32_16x16x32_bf16 v[122:125], v[158:161], v[182:185], v[122:125]
	v_mfma_f32_16x16x32_bf16 v[110:113], v[144:147], v[190:193], v[110:113]
	v_mfma_f32_16x16x32_bf16 v[106:109], v[158:161], v[190:193], v[106:109]
	v_mfma_f32_16x16x32_bf16 v[92:95], v[144:147], v[206:209], v[92:95]
	v_mfma_f32_16x16x32_bf16 v[88:91], v[158:161], v[206:209], v[88:91]
	v_mfma_f32_16x16x32_bf16 v[76:79], v[144:147], v[214:217], v[76:79]
	v_mfma_f32_16x16x32_bf16 v[72:75], v[158:161], v[214:217], v[72:75]
	v_mfma_f32_16x16x32_bf16 v[126:129], v[154:157], v[186:189], v[126:129]
	v_mfma_f32_16x16x32_bf16 v[122:125], v[162:165], v[186:189], v[122:125]
	v_mfma_f32_16x16x32_bf16 v[110:113], v[154:157], v[202:205], v[110:113]
	v_mfma_f32_16x16x32_bf16 v[106:109], v[162:165], v[202:205], v[106:109]
	v_mfma_f32_16x16x32_bf16 v[92:95], v[154:157], v[210:213], v[92:95]
	v_mfma_f32_16x16x32_bf16 v[88:91], v[162:165], v[210:213], v[88:91]
	v_mfma_f32_16x16x32_bf16 v[76:79], v[154:157], v[218:221], v[76:79]
	v_mfma_f32_16x16x32_bf16 v[72:75], v[162:165], v[218:221], v[72:75]
	v_mfma_f32_16x16x32_bf16 v[118:121], v[166:169], v[182:185], v[118:121]
	v_mfma_f32_16x16x32_bf16 v[114:117], v[174:177], v[182:185], v[114:117]
	v_mfma_f32_16x16x32_bf16 v[102:105], v[166:169], v[190:193], v[102:105]
	v_mfma_f32_16x16x32_bf16 v[98:101], v[174:177], v[190:193], v[98:101]
	v_mfma_f32_16x16x32_bf16 v[84:87], v[166:169], v[206:209], v[84:87]
	v_mfma_f32_16x16x32_bf16 v[80:83], v[174:177], v[206:209], v[80:83]
	v_mfma_f32_16x16x32_bf16 v[68:71], v[166:169], v[214:217], v[68:71]
	v_mfma_f32_16x16x32_bf16 v[64:67], v[174:177], v[214:217], v[64:67]
	v_mfma_f32_16x16x32_bf16 v[118:121], v[170:173], v[186:189], v[118:121]
	v_mfma_f32_16x16x32_bf16 v[114:117], v[178:181], v[186:189], v[114:117]
	v_mfma_f32_16x16x32_bf16 v[102:105], v[170:173], v[202:205], v[102:105]
	v_mfma_f32_16x16x32_bf16 v[98:101], v[178:181], v[202:205], v[98:101]
	v_mfma_f32_16x16x32_bf16 v[84:87], v[170:173], v[210:213], v[84:87]
	v_mfma_f32_16x16x32_bf16 v[80:83], v[178:181], v[210:213], v[80:83]
	v_mfma_f32_16x16x32_bf16 v[68:71], v[170:173], v[218:221], v[68:71]
	v_mfma_f32_16x16x32_bf16 v[64:67], v[178:181], v[218:221], v[64:67]
	s_barrier
; #define PG8_STAGE(bufoff, gbase, voff) do { _Pragma("unroll") for (int _i = 0; _i < 2; ++_i) \
;         __builtin_amdgcn_global_load_lds((const unsigned*)((const char*)(gbase) + (voff)[_i]), (PG8_LAS unsigned*)(lds + (bufoff) + ldsw + _i * 8192), 16, 0, 0); } while (0)
; #define PG8_LDA(dst, b, h) do { _Pragma("unroll") for (int m = 0; m < 4; ++m) _Pragma("unroll") for (int k = 0; k < 2; ++k) dst[m][k] = *(const PG8_LAS bf16x8*)(lds + PG8_SA(b, h) + aoff + m * 2048 + k * 1024); } while (0)
; #define PG8_MMA(ai, bj, At, Bt) do { __builtin_amdgcn_s_setprio(1); _Pragma("unroll") for (int m = 0; m < 4; ++m) _Pragma("unroll") for (int n = 0; n < 2; ++n) _Pragma("unroll") for (int k = 0; k < 2; ++k) \
;         acc[ai][bj][m][n] = __builtin_amdgcn_mfma_f32_16x16x32_bf16(Bt[n][k], At[m][k], acc[ai][bj][m][n], 0, 0, 0); __builtin_amdgcn_s_setprio(0); } while (0)
; #define PG8_WAIT_V(n) asm volatile("s_waitcnt vmcnt(" #n ")" ::: "memory")
; #define PG8_WAIT_L(n) asm volatile("s_waitcnt lgkmcnt(" #n ")" ::: "memory")
; #define PG8_BAR __builtin_amdgcn_s_barrier()
; #define PG8_SCHED __builtin_amdgcn_sched_barrier(0)
; template <class Epi, class Sched, bool ALIGN_EPI = false, bool SP2 = false>
; __device__ __forceinline__ void gemm_phase(PG8_LAS unsigned char* lds, const Gemm g, const Sched& S, const Epi& E) {
;     ...
;             PG8_LDA(At, 1, 1); PG8_STAGE(PG8_SB(1, 0), b3, voffB); PG8_STAGE(PG8_SB(1, 1), b3 + hstep, voffB); PG8_STAGE(PG8_SA(1, 0), a3, voffA);
;             PG8_WAIT_V(8); PG8_WAIT_L(0); PG8_BAR; PG8_MMA(1, 0, At, B0); PG8_MMA(1, 1, At, B1); PG8_BAR; PG8_SCHED;
	s_add_i32 s12, vcc_lo, s70
	v_lshl_add_u64 v[222:223], v[222:223], 0, s[36:37]
	s_mov_b32 m0, s12
	ds_read_b128 v[182:185], v153 offset:49152
	ds_read_b128 v[186:189], v153 offset:50176
	ds_read_b128 v[190:193], v153 offset:51200
	ds_read_b128 v[202:205], v153 offset:52224
	ds_read_b128 v[206:209], v153 offset:53248
	ds_read_b128 v[210:213], v153 offset:54272
	ds_read_b128 v[214:217], v153 offset:55296
	ds_read_b128 v[218:221], v153 offset:56320
	global_load_lds_dwordx4 v[222:223], off
	s_add_i32 m0, s12, 0x2000
	s_add_u32 s12, s62, 0x80080
	v_lshl_add_u64 v[222:223], v[224:225], 0, s[36:37]
	s_addc_u32 s13, s63, 0
	s_add_i32 s62, vcc_hi, s70
	global_load_lds_dwordx4 v[222:223], off
	v_lshl_add_u64 v[222:223], s[12:13], 0, v[132:133]
	s_mov_b32 m0, s62
	s_nop 0
	global_load_lds_dwordx4 v[222:223], off
	v_lshl_add_u64 v[222:223], s[12:13], 0, v[136:137]
	s_add_i32 m0, s62, 0x2000
	s_nop 0
	global_load_lds_dwordx4 v[222:223], off
	v_lshl_add_u64 v[222:223], v[226:227], 0, s[36:37]
	s_mov_b32 m0, s85
	s_nop 0
	global_load_lds_dwordx4 v[222:223], off
	v_lshl_add_u64 v[222:223], v[228:229], 0, s[36:37]
	s_mov_b32 m0, s92
	s_nop 0
	global_load_lds_dwordx4 v[222:223], off
	s_waitcnt vmcnt(8)
	s_waitcnt lgkmcnt(0)
	s_barrier
	s_waitcnt lgkmcnt(0)
	v_mfma_f32_16x16x32_bf16 v[60:63], v[144:147], v[182:185], v[60:63]
	v_mfma_f32_16x16x32_bf16 v[56:59], v[158:161], v[182:185], v[56:59]
	v_mfma_f32_16x16x32_bf16 v[44:47], v[144:147], v[190:193], v[44:47]
	v_mfma_f32_16x16x32_bf16 v[40:43], v[158:161], v[190:193], v[40:43]
	v_mfma_f32_16x16x32_bf16 v[28:31], v[144:147], v[206:209], v[28:31]
	v_mfma_f32_16x16x32_bf16 v[24:27], v[158:161], v[206:209], v[24:27]
	v_mfma_f32_16x16x32_bf16 v[12:15], v[144:147], v[214:217], v[12:15]
	v_mfma_f32_16x16x32_bf16 v[8:11], v[158:161], v[214:217], v[8:11]
	v_mfma_f32_16x16x32_bf16 v[60:63], v[154:157], v[186:189], v[60:63]
	v_mfma_f32_16x16x32_bf16 v[56:59], v[162:165], v[186:189], v[56:59]
	v_mfma_f32_16x16x32_bf16 v[44:47], v[154:157], v[202:205], v[44:47]
	v_mfma_f32_16x16x32_bf16 v[40:43], v[162:165], v[202:205], v[40:43]
	v_mfma_f32_16x16x32_bf16 v[28:31], v[154:157], v[210:213], v[28:31]
	v_mfma_f32_16x16x32_bf16 v[24:27], v[162:165], v[210:213], v[24:27]
	v_mfma_f32_16x16x32_bf16 v[12:15], v[154:157], v[218:221], v[12:15]
	v_mfma_f32_16x16x32_bf16 v[8:11], v[162:165], v[218:221], v[8:11]
	v_mfma_f32_16x16x32_bf16 v[52:55], v[166:169], v[182:185], v[52:55]
	v_mfma_f32_16x16x32_bf16 v[48:51], v[174:177], v[182:185], v[48:51]
	v_mfma_f32_16x16x32_bf16 v[36:39], v[166:169], v[190:193], v[36:39]
	v_mfma_f32_16x16x32_bf16 v[32:35], v[174:177], v[190:193], v[32:35]
	v_mfma_f32_16x16x32_bf16 v[20:23], v[166:169], v[206:209], v[20:23]
	v_mfma_f32_16x16x32_bf16 v[16:19], v[174:177], v[206:209], v[16:19]
	v_mfma_f32_16x16x32_bf16 v[4:7], v[166:169], v[214:217], v[4:7]
	v_mfma_f32_16x16x32_bf16 v[0:3], v[174:177], v[214:217], v[0:3]
	v_mfma_f32_16x16x32_bf16 v[52:55], v[170:173], v[186:189], v[52:55]
	v_mfma_f32_16x16x32_bf16 v[48:51], v[178:181], v[186:189], v[48:51]
	v_mfma_f32_16x16x32_bf16 v[36:39], v[170:173], v[202:205], v[36:39]
	v_mfma_f32_16x16x32_bf16 v[32:35], v[178:181], v[202:205], v[32:35]
	v_mfma_f32_16x16x32_bf16 v[20:23], v[170:173], v[210:213], v[20:23]
	v_mfma_f32_16x16x32_bf16 v[16:19], v[178:181], v[210:213], v[16:19]
	v_mfma_f32_16x16x32_bf16 v[4:7], v[170:173], v[218:221], v[4:7]
	v_mfma_f32_16x16x32_bf16 v[0:3], v[178:181], v[218:221], v[0:3]
	s_barrier
	s_add_i32 s55, s55, 2
	s_add_u32 s18, s18, 0x100
	s_addc_u32 s19, s19, 0
	s_add_u32 s42, s42, 0x100
	s_addc_u32 s43, s43, 0
	s_cmp_gt_u32 s55, 29
	s_cbranch_scc0 .LBB0_175
	s_and_b64 vcc, exec, s[0:1]
	s_cbranch_vccz .LBB0_178
	s_barrier

; #define PG8_WAIT_V(n) asm volatile("s_waitcnt vmcnt(" #n ")" ::: "memory")
; #define PG8_BAR __builtin_amdgcn_s_barrier()
; template <class Epi, class Sched, bool ALIGN_EPI = false, bool SP2 = false>
; __device__ __forceinline__ void gemm_phase(PG8_LAS unsigned char* lds, const Gemm g, const Sched& S, const Epi& E) {
;     ...
;     PG8_WAIT_V(0);
;     if constexpr (!ALIGN_EPI) { if (wr == 0) PG8_BAR; }
;     PG8_BAR;
.LBB0_213:
	s_setprio 0
	s_waitcnt vmcnt(0)
	v_readlane_b32 s93, v255, 20
	s_barrier

; #define PG8_STAGE(bufoff, gbase, voff) do { _Pragma("unroll") for (int _i = 0; _i < 2; ++_i) \
;         __builtin_amdgcn_global_load_lds((const unsigned*)((const char*)(gbase) + (voff)[_i]), (PG8_LAS unsigned*)(lds + (bufoff) + ldsw + _i * 8192), 16, 0, 0); } while (0)
; #define PG8_BAR __builtin_amdgcn_s_barrier()
; template <class Epi, class Sched, bool ALIGN_EPI = false, bool SP2 = false>
; __device__ __forceinline__ void gemm_phase(PG8_LAS unsigned char* lds, const Gemm g, const Sched& S, const Epi& E) {
;     ...
;     for (int i = 0; i < 2; ++i) { int R, C; stage_rc(tid * 16 + i * 8192, R, C); const int Rb = Epi::PERM ? ((R & ~31) + perm32(R & 31)) : R;
;         voffA[i] = (unsigned)(R * K + C) * 2u; voffB[i] = (unsigned)(Rb * K + C) * 2u; }
;     ...
;         PG8_STAGE(PG8_SB(0, 0), cB, voffB); PG8_STAGE(PG8_SB(0, 1), cB + hstep, voffB); PG8_STAGE(PG8_SA(0, 0), cA, voffA); PG8_STAGE(PG8_SA(0, 1), cA + hstep, voffA);
;         if (wr == 1) PG8_BAR;
.LBB0_227:
	s_and_b64 vcc, exec, s[40:41]
	s_cbranch_vccnz .LBB0_275
	v_ashrrev_i32_e32 v1, 31, v14
	v_lshrrev_b32_e32 v1, 26, v1
	v_add_u32_e32 v1, v14, v1
	v_ashrrev_i32_e32 v8, 6, v1
	v_bfe_i32 v1, v14, 27, 1
	v_lshlrev_b32_e32 v0, 4, v14
	v_lshrrev_b32_e32 v1, 22, v1
	v_add_u32_e32 v1, v0, v1
	v_and_b32_e32 v1, 0xfffffc00, v1
	v_sub_u32_e32 v1, v0, v1
	v_lshrrev_b32_e32 v2, 4, v1
	v_bitop3_b32 v1, v2, v1, 32 bitop3:0x6c
	v_ashrrev_i32_e32 v3, 31, v1
	v_lshrrev_b32_e32 v3, 26, v3
	v_add_u32_e32 v3, v1, v3
	v_lshlrev_b32_e32 v2, 3, v8
	v_ashrrev_i32_e32 v9, 6, v3
	v_and_b32_e32 v3, 0xc0, v3
	v_and_b32_e32 v2, -16, v2
	v_sub_u32_e32 v1, v1, v3
	v_add_u32_e32 v2, v9, v2
	v_ashrrev_i16_sdwa v1, v240, sext(v1) dst_sel:DWORD dst_unused:UNUSED_PAD src0_sel:DWORD src1_sel:BYTE_0
	v_lshlrev_b32_e32 v4, 5, v8
	v_bfe_i32 v10, v1, 0, 16
	v_lshlrev_b32_e32 v1, 1, v2
	v_lshrrev_b32_e32 v3, 2, v2
	v_and_b32_e32 v5, 3, v9
	s_mov_b32 s4, 0xfffe0
	v_and_b32_e32 v4, 32, v4
	v_and_b32_e32 v1, 24, v1
	v_and_b32_e32 v3, 4, v3
	v_and_or_b32 v5, v2, s4, v5
	v_or3_b32 v1, v5, v3, v1
	v_add_lshl_u32 v3, v4, v10, 1
	v_add_u32_e32 v0, 0x2000, v0
	v_lshl_add_u32 v132, v1, 12, v3
	v_ashrrev_i32_e32 v1, 31, v0
	v_lshrrev_b32_e32 v1, 22, v1
	v_add_u32_e32 v1, v0, v1
	v_ashrrev_i32_e32 v11, 10, v1
	v_mul_i32_i24_e32 v1, 0x400, v11
	v_sub_u32_e32 v0, v0, v1
	v_lshrrev_b32_e32 v1, 4, v0
	v_bitop3_b32 v0, v1, v0, 32 bitop3:0x6c
	v_lshl_add_u32 v130, v2, 12, v3
	v_ashrrev_i32_e32 v2, 31, v0
	v_lshrrev_b32_e32 v2, 26, v2
	v_lshlrev_b32_e32 v1, 3, v11
	v_add_u32_e32 v2, v0, v2
	v_and_b32_e32 v1, -16, v1
	v_ashrrev_i32_e32 v12, 6, v2
	v_add_u32_e32 v1, v12, v1
	v_and_b32_e32 v4, 3, v12
	v_and_or_b32 v4, v1, s4, v4
	s_ashr_i32 s4, s0, 6
	s_mul_i32 s26, s7, 0xb80000
	s_ashr_i32 s1, s0, 8
	s_lshl_b32 s9, s4, 10
	s_lshl_b64 s[10:11], s[26:27], 1
	s_add_u32 s5, s48, s10
	s_addc_u32 s10, s49, s11
	s_add_u32 s26, s5, 0x100000
	v_and_b32_e32 v2, 0xc0, v2
	s_addc_u32 s62, s10, 0
	s_ashr_i32 s15, s14, 31
	s_ashr_i32 s57, s56, 31
	v_sub_u32_e32 v0, v0, v2
	s_lshl_b64 s[10:11], s[14:15], 20
	s_lshl_b64 s[12:13], s[56:57], 20
	v_ashrrev_i16_sdwa v0, v240, sext(v0) dst_sel:DWORD dst_unused:UNUSED_PAD src0_sel:DWORD src1_sel:BYTE_0
	s_add_u32 s42, s26, s12
	v_lshlrev_b32_e32 v3, 5, v11
	v_bfe_i32 v13, v0, 0, 16
	v_lshlrev_b32_e32 v0, 1, v1
	v_lshrrev_b32_e32 v2, 2, v1
	s_addc_u32 s43, s62, s13
	s_add_i32 s57, s9, 0
	v_and_b32_e32 v3, 32, v3
	v_and_b32_e32 v0, 24, v0
	v_and_b32_e32 v2, 4, v2
	s_add_i32 m0, s57, 0x10000
	v_or3_b32 v0, v4, v2, v0
	v_add_lshl_u32 v2, v3, v13, 1
	global_load_lds_dwordx4 v132, s[42:43]
	s_add_i32 m0, s57, 0x12000
	v_lshl_add_u32 v136, v0, 12, v2
	s_add_u32 s12, s42, 0x80000
	global_load_lds_dwordx4 v136, s[42:43]
	s_addc_u32 s13, s43, 0
	s_add_i32 m0, s57, 0x14000
	v_lshl_add_u32 v134, v1, 12, v2
	global_load_lds_dwordx4 v132, s[12:13]
	s_add_i32 m0, s57, 0x16000
	s_add_u32 s58, s67, s10
	s_addc_u32 s59, s68, s11
	s_add_i32 s63, s57, 0x2000
	global_load_lds_dwordx4 v136, s[12:13]
	s_mov_b32 m0, s57
	s_add_u32 s10, s58, 0x80000
	global_load_lds_dwordx4 v130, s[58:59]
	s_mov_b32 m0, s63
	s_addc_u32 s11, s59, 0
	s_add_i32 s64, s57, 0x4000
	global_load_lds_dwordx4 v134, s[58:59]
	s_mov_b32 m0, s64
	s_add_i32 s65, s57, 0x6000
	global_load_lds_dwordx4 v130, s[10:11]
	s_mov_b32 m0, s65
	v_mov_b32_e32 v133, v96
	global_load_lds_dwordx4 v134, s[10:11]
	v_mov_b32_e32 v137, v96
	v_mov_b32_e32 v131, v96
	v_mov_b32_e32 v135, v96
	s_cmp_eq_u32 s1, 1
	v_lshl_add_u64 v[6:7], s[42:43], 0, v[132:133]
	v_lshl_add_u64 v[4:5], s[42:43], 0, v[136:137]
	v_lshl_add_u64 v[0:1], s[58:59], 0, v[130:131]
	s_cselect_b64 s[48:49], -1, 0
	s_cmp_lg_u32 s1, 1
	v_lshl_add_u64 v[2:3], s[58:59], 0, v[134:135]
	s_cbranch_scc1 .LBB0_230
	s_barrier
	s_setprio 1

; #define PG8_STAGE(bufoff, gbase, voff) do { _Pragma("unroll") for (int _i = 0; _i < 2; ++_i) \
;         __builtin_amdgcn_global_load_lds((const unsigned*)((const char*)(gbase) + (voff)[_i]), (PG8_LAS unsigned*)(lds + (bufoff) + ldsw + _i * 8192), 16, 0, 0); } while (0)
; #define PG8_LDA(dst, b, h) do { _Pragma("unroll") for (int m = 0; m < 4; ++m) _Pragma("unroll") for (int k = 0; k < 2; ++k) dst[m][k] = *(const PG8_LAS bf16x8*)(lds + PG8_SA(b, h) + aoff + m * 2048 + k * 1024); } while (0)
; #define PG8_LDB(dst, b, h) do { _Pragma("unroll") for (int n = 0; n < 2; ++n) _Pragma("unroll") for (int k = 0; k < 2; ++k) dst[n][k] = *(const PG8_LAS bf16x8*)(lds + PG8_SB(b, h) + boff + n * 2048 + k * 1024); } while (0)
; #define PG8_MMA(ai, bj, At, Bt) do { __builtin_amdgcn_s_setprio(1); _Pragma("unroll") for (int m = 0; m < 4; ++m) _Pragma("unroll") for (int n = 0; n < 2; ++n) _Pragma("unroll") for (int k = 0; k < 2; ++k) \
;         acc[ai][bj][m][n] = __builtin_amdgcn_mfma_f32_16x16x32_bf16(Bt[n][k], At[m][k], acc[ai][bj][m][n], 0, 0, 0); __builtin_amdgcn_s_setprio(0); } while (0)
; #define PG8_WAIT_V(n) asm volatile("s_waitcnt vmcnt(" #n ")" ::: "memory")
; #define PG8_WAIT_L(n) asm volatile("s_waitcnt lgkmcnt(" #n ")" ::: "memory")
; #define PG8_BAR __builtin_amdgcn_s_barrier()
; #define PG8_SCHED __builtin_amdgcn_sched_barrier(0)
; template <class Epi, class Sched, bool ALIGN_EPI = false, bool SP2 = false>
; __device__ __forceinline__ void gemm_phase(PG8_LAS unsigned char* lds, const Gemm g, const Sched& S, const Epi& E) {
;     ...
;         for (int t = 0; t < nt; t += 2) {
;             const bool last = (t == nt - 2);
;             const char* a1 = cA + (size_t)(t + 1) * kstep;
;             const char* a2 = last ? nA : cA + (size_t)(t + 2) * kstep; const char* b2 = last ? nB : cB + (size_t)(t + 2) * kstep;
;             const char* a3 = a2 + kstep; const char* b3 = b2 + kstep;
;             if (last && has_next) S.a_ready(nxt);
;             if constexpr (SP2) {
;             PG8_LDB(B0, 0, 0); PG8_LDB(B1, 0, 1); PG8_SCHED; PG8_LDA(At, 0, 0); PG8_STAGE(PG8_SA(1, 1), a1 + hstep, voffA);
;             PG8_WAIT_V(8); PG8_WAIT_L(0); PG8_BAR; PG8_MMA(0, 0, At, B0); PG8_MMA(0, 1, At, B1); PG8_BAR; PG8_SCHED;
;             PG8_LDA(At, 0, 1); PG8_STAGE(PG8_SB(0, 0), b2, voffB); PG8_STAGE(PG8_SB(0, 1), b2 + hstep, voffB); PG8_STAGE(PG8_SA(0, 0), a2, voffA);
.LBB0_236:
	s_add_u32 s12, s42, 0xfff80080
	s_addc_u32 s13, s43, -1
	s_add_i32 s73, 0, 0x10000
	s_cmp_eq_u32 s51, 28
	s_cselect_b32 s61, s10, s13
	s_cselect_b32 s60, s11, s12
	v_add_u32_e32 v148, s73, v149
	s_cselect_b32 s59, s5, s19
	s_cselect_b32 s58, s15, s18
	s_add_i32 s84, 0, 0x14000
	ds_read_b128 v[144:147], v148
	ds_read_b128 v[154:157], v148 offset:1024
	ds_read_b128 v[158:161], v148 offset:2048
	ds_read_b128 v[162:165], v148 offset:3072
	v_add_u32_e32 v148, s84, v149
	ds_read_b128 v[166:169], v148
	ds_read_b128 v[170:173], v148 offset:1024
	ds_read_b128 v[174:177], v148 offset:2048
	ds_read_b128 v[178:181], v148 offset:3072
	v_lshl_add_u64 v[222:223], s[42:43], 0, v[142:143]
	s_add_i32 m0, s57, 0xc000
	ds_read_b128 v[182:185], v152
	ds_read_b128 v[186:189], v152 offset:1024
	ds_read_b128 v[190:193], v152 offset:2048
	ds_read_b128 v[202:205], v152 offset:3072
	ds_read_b128 v[206:209], v152 offset:4096
	ds_read_b128 v[210:213], v152 offset:5120
	ds_read_b128 v[214:217], v152 offset:6144
	ds_read_b128 v[218:221], v152 offset:7168
	global_load_lds_dwordx4 v[222:223], off
	v_lshl_add_u64 v[222:223], s[42:43], 0, v[140:141]
	s_add_i32 m0, s57, 0xe000
	s_nop 0
	global_load_lds_dwordx4 v[222:223], off
	s_waitcnt vmcnt(8)
	s_waitcnt lgkmcnt(0)
	s_barrier
	s_waitcnt lgkmcnt(0)
	v_mfma_f32_16x16x32_bf16 v[126:129], v[144:147], v[182:185], v[126:129]
	v_mfma_f32_16x16x32_bf16 v[122:125], v[158:161], v[182:185], v[122:125]
	v_mfma_f32_16x16x32_bf16 v[110:113], v[144:147], v[190:193], v[110:113]
	v_mfma_f32_16x16x32_bf16 v[106:109], v[158:161], v[190:193], v[106:109]
	v_mfma_f32_16x16x32_bf16 v[92:95], v[144:147], v[206:209], v[92:95]
	v_mfma_f32_16x16x32_bf16 v[88:91], v[158:161], v[206:209], v[88:91]
	v_mfma_f32_16x16x32_bf16 v[76:79], v[144:147], v[214:217], v[76:79]
	v_mfma_f32_16x16x32_bf16 v[72:75], v[158:161], v[214:217], v[72:75]
	v_mfma_f32_16x16x32_bf16 v[126:129], v[154:157], v[186:189], v[126:129]
	v_mfma_f32_16x16x32_bf16 v[122:125], v[162:165], v[186:189], v[122:125]
	v_mfma_f32_16x16x32_bf16 v[110:113], v[154:157], v[202:205], v[110:113]
	v_mfma_f32_16x16x32_bf16 v[106:109], v[162:165], v[202:205], v[106:109]
	v_mfma_f32_16x16x32_bf16 v[92:95], v[154:157], v[210:213], v[92:95]
	v_mfma_f32_16x16x32_bf16 v[88:91], v[162:165], v[210:213], v[88:91]
	v_mfma_f32_16x16x32_bf16 v[76:79], v[154:157], v[218:221], v[76:79]
	v_mfma_f32_16x16x32_bf16 v[72:75], v[162:165], v[218:221], v[72:75]
	v_mfma_f32_16x16x32_bf16 v[118:121], v[166:169], v[182:185], v[118:121]
	v_mfma_f32_16x16x32_bf16 v[114:117], v[174:177], v[182:185], v[114:117]
	v_mfma_f32_16x16x32_bf16 v[102:105], v[166:169], v[190:193], v[102:105]
	v_mfma_f32_16x16x32_bf16 v[98:101], v[174:177], v[190:193], v[98:101]
	v_mfma_f32_16x16x32_bf16 v[84:87], v[166:169], v[206:209], v[84:87]
	v_mfma_f32_16x16x32_bf16 v[80:83], v[174:177], v[206:209], v[80:83]
	v_mfma_f32_16x16x32_bf16 v[68:71], v[166:169], v[214:217], v[68:71]
	v_mfma_f32_16x16x32_bf16 v[64:67], v[174:177], v[214:217], v[64:67]
	v_mfma_f32_16x16x32_bf16 v[118:121], v[170:173], v[186:189], v[118:121]
	v_mfma_f32_16x16x32_bf16 v[114:117], v[178:181], v[186:189], v[114:117]
	v_mfma_f32_16x16x32_bf16 v[102:105], v[170:173], v[202:205], v[102:105]
	v_mfma_f32_16x16x32_bf16 v[98:101], v[178:181], v[202:205], v[98:101]
	v_mfma_f32_16x16x32_bf16 v[84:87], v[170:173], v[210:213], v[84:87]
	v_mfma_f32_16x16x32_bf16 v[80:83], v[178:181], v[210:213], v[80:83]
	v_mfma_f32_16x16x32_bf16 v[68:71], v[170:173], v[218:221], v[68:71]
	v_mfma_f32_16x16x32_bf16 v[64:67], v[178:181], v[218:221], v[64:67]
	s_barrier
	s_add_i32 s12, s73, s9
	v_lshl_add_u64 v[222:223], s[58:59], 0, v[132:133]
	s_mov_b32 m0, s12
	ds_read_b128 v[182:185], v152 offset:16384
	ds_read_b128 v[186:189], v152 offset:17408
	ds_read_b128 v[190:193], v152 offset:18432
	ds_read_b128 v[202:205], v152 offset:19456
	ds_read_b128 v[206:209], v152 offset:20480
	ds_read_b128 v[210:213], v152 offset:21504
	ds_read_b128 v[214:217], v152 offset:22528
	ds_read_b128 v[218:221], v152 offset:23552
	global_load_lds_dwordx4 v[222:223], off
	s_add_i32 m0, s12, 0x2000
	s_add_u32 s12, s58, 0x80000
	v_lshl_add_u64 v[224:225], s[58:59], 0, v[136:137]
	s_addc_u32 s13, s59, 0
	s_add_i32 s73, s84, s9
	global_load_lds_dwordx4 v[224:225], off
	v_lshl_add_u64 v[226:227], s[12:13], 0, v[132:133]
	s_mov_b32 m0, s73
	v_lshl_add_u64 v[228:229], s[60:61], 0, v[134:135]
	global_load_lds_dwordx4 v[226:227], off
	v_lshl_add_u64 v[226:227], s[12:13], 0, v[136:137]
	s_add_i32 m0, s73, 0x2000
	s_nop 0
	global_load_lds_dwordx4 v[226:227], off
	v_lshl_add_u64 v[226:227], s[60:61], 0, v[130:131]
	s_mov_b32 m0, s57
	s_nop 0
	global_load_lds_dwordx4 v[226:227], off
	s_mov_b32 m0, s63
	s_nop 0
	global_load_lds_dwordx4 v[228:229], off
	s_waitcnt vmcnt(8)
	s_waitcnt lgkmcnt(0)
	s_barrier
; #define PG8_STAGE(bufoff, gbase, voff) do { _Pragma("unroll") for (int _i = 0; _i < 2; ++_i) \
;         __builtin_amdgcn_global_load_lds((const unsigned*)((const char*)(gbase) + (voff)[_i]), (PG8_LAS unsigned*)(lds + (bufoff) + ldsw + _i * 8192), 16, 0, 0); } while (0)
; #define PG8_LDA(dst, b, h) do { _Pragma("unroll") for (int m = 0; m < 4; ++m) _Pragma("unroll") for (int k = 0; k < 2; ++k) dst[m][k] = *(const PG8_LAS bf16x8*)(lds + PG8_SA(b, h) + aoff + m * 2048 + k * 1024); } while (0)
; #define PG8_LDB(dst, b, h) do { _Pragma("unroll") for (int n = 0; n < 2; ++n) _Pragma("unroll") for (int k = 0; k < 2; ++k) dst[n][k] = *(const PG8_LAS bf16x8*)(lds + PG8_SB(b, h) + boff + n * 2048 + k * 1024); } while (0)
; #define PG8_MMA(ai, bj, At, Bt) do { __builtin_amdgcn_s_setprio(1); _Pragma("unroll") for (int m = 0; m < 4; ++m) _Pragma("unroll") for (int n = 0; n < 2; ++n) _Pragma("unroll") for (int k = 0; k < 2; ++k) \
;         acc[ai][bj][m][n] = __builtin_amdgcn_mfma_f32_16x16x32_bf16(Bt[n][k], At[m][k], acc[ai][bj][m][n], 0, 0, 0); __builtin_amdgcn_s_setprio(0); } while (0)
; #define PG8_WAIT_V(n) asm volatile("s_waitcnt vmcnt(" #n ")" ::: "memory")
; #define PG8_WAIT_L(n) asm volatile("s_waitcnt lgkmcnt(" #n ")" ::: "memory")
; #define PG8_BAR __builtin_amdgcn_s_barrier()
; #define PG8_SCHED __builtin_amdgcn_sched_barrier(0)
; template <class Epi, class Sched, bool ALIGN_EPI = false, bool SP2 = false>
; __device__ __forceinline__ void gemm_phase(PG8_LAS unsigned char* lds, const Gemm g, const Sched& S, const Epi& E) {
;     ...
;             PG8_WAIT_V(8); PG8_WAIT_L(0); PG8_BAR; PG8_MMA(1, 0, At, B0); PG8_MMA(1, 1, At, B1); PG8_BAR; PG8_SCHED;
;             PG8_LDB(B0, 1, 0); PG8_LDB(B1, 1, 1); PG8_SCHED; PG8_LDA(At, 1, 0); PG8_STAGE(PG8_SA(0, 1), a2 + hstep, voffA);
;             PG8_WAIT_V(8); PG8_WAIT_L(0); PG8_BAR; PG8_MMA(0, 0, At, B0); PG8_MMA(0, 1, At, B1); PG8_BAR; PG8_SCHED;
	s_waitcnt lgkmcnt(0)
	v_mfma_f32_16x16x32_bf16 v[60:63], v[144:147], v[182:185], v[60:63]
	v_mfma_f32_16x16x32_bf16 v[56:59], v[158:161], v[182:185], v[56:59]
	v_mfma_f32_16x16x32_bf16 v[44:47], v[144:147], v[190:193], v[44:47]
	v_mfma_f32_16x16x32_bf16 v[40:43], v[158:161], v[190:193], v[40:43]
	v_mfma_f32_16x16x32_bf16 v[28:31], v[144:147], v[206:209], v[28:31]
	v_mfma_f32_16x16x32_bf16 v[24:27], v[158:161], v[206:209], v[24:27]
	v_mfma_f32_16x16x32_bf16 v[12:15], v[144:147], v[214:217], v[12:15]
	v_mfma_f32_16x16x32_bf16 v[8:11], v[158:161], v[214:217], v[8:11]
	v_mfma_f32_16x16x32_bf16 v[60:63], v[154:157], v[186:189], v[60:63]
	v_mfma_f32_16x16x32_bf16 v[56:59], v[162:165], v[186:189], v[56:59]
	v_mfma_f32_16x16x32_bf16 v[44:47], v[154:157], v[202:205], v[44:47]
	v_mfma_f32_16x16x32_bf16 v[40:43], v[162:165], v[202:205], v[40:43]
	v_mfma_f32_16x16x32_bf16 v[28:31], v[154:157], v[210:213], v[28:31]
	v_mfma_f32_16x16x32_bf16 v[24:27], v[162:165], v[210:213], v[24:27]
	v_mfma_f32_16x16x32_bf16 v[12:15], v[154:157], v[218:221], v[12:15]
	v_mfma_f32_16x16x32_bf16 v[8:11], v[162:165], v[218:221], v[8:11]
	v_mfma_f32_16x16x32_bf16 v[52:55], v[166:169], v[182:185], v[52:55]
	v_mfma_f32_16x16x32_bf16 v[48:51], v[174:177], v[182:185], v[48:51]
	v_mfma_f32_16x16x32_bf16 v[36:39], v[166:169], v[190:193], v[36:39]
	v_mfma_f32_16x16x32_bf16 v[32:35], v[174:177], v[190:193], v[32:35]
	v_mfma_f32_16x16x32_bf16 v[20:23], v[166:169], v[206:209], v[20:23]
	v_mfma_f32_16x16x32_bf16 v[16:19], v[174:177], v[206:209], v[16:19]
	v_mfma_f32_16x16x32_bf16 v[4:7], v[166:169], v[214:217], v[4:7]
	v_mfma_f32_16x16x32_bf16 v[0:3], v[174:177], v[214:217], v[0:3]
	v_mfma_f32_16x16x32_bf16 v[52:55], v[170:173], v[186:189], v[52:55]
	v_mfma_f32_16x16x32_bf16 v[48:51], v[178:181], v[186:189], v[48:51]
	v_mfma_f32_16x16x32_bf16 v[36:39], v[170:173], v[202:205], v[36:39]
	v_mfma_f32_16x16x32_bf16 v[32:35], v[178:181], v[202:205], v[32:35]
	v_mfma_f32_16x16x32_bf16 v[20:23], v[170:173], v[210:213], v[20:23]
	v_mfma_f32_16x16x32_bf16 v[16:19], v[178:181], v[210:213], v[16:19]
	v_mfma_f32_16x16x32_bf16 v[4:7], v[170:173], v[218:221], v[4:7]
	v_mfma_f32_16x16x32_bf16 v[0:3], v[178:181], v[218:221], v[0:3]
	s_barrier
	s_add_i32 s73, 0, 0x18000
	v_add_u32_e32 v148, s73, v149
	s_add_i32 s84, 0, 0x1c000
	ds_read_b128 v[144:147], v148
	ds_read_b128 v[154:157], v148 offset:1024
	ds_read_b128 v[158:161], v148 offset:2048
	ds_read_b128 v[162:165], v148 offset:3072
	v_add_u32_e32 v148, s84, v149
	ds_read_b128 v[166:169], v148
	ds_read_b128 v[170:173], v148 offset:1024
	ds_read_b128 v[174:177], v148 offset:2048
	ds_read_b128 v[178:181], v148 offset:3072
	s_add_u32 s12, s60, 0x80000
	s_addc_u32 s13, s61, 0
	s_mov_b32 m0, s64
	v_lshl_add_u64 v[230:231], s[12:13], 0, v[130:131]
	ds_read_b128 v[182:185], v152 offset:32768
	ds_read_b128 v[186:189], v152 offset:33792
	ds_read_b128 v[190:193], v152 offset:34816
	ds_read_b128 v[202:205], v152 offset:35840
	ds_read_b128 v[206:209], v152 offset:36864
	ds_read_b128 v[210:213], v152 offset:37888
	ds_read_b128 v[214:217], v152 offset:38912
	ds_read_b128 v[218:221], v152 offset:39936
	global_load_lds_dwordx4 v[230:231], off
	v_lshl_add_u64 v[230:231], s[12:13], 0, v[134:135]
	s_mov_b32 m0, s65
	s_nop 0
	global_load_lds_dwordx4 v[230:231], off
	s_waitcnt vmcnt(8)
	s_waitcnt lgkmcnt(0)
	s_barrier
	s_waitcnt lgkmcnt(0)
	v_mfma_f32_16x16x32_bf16 v[126:129], v[144:147], v[182:185], v[126:129]
	v_mfma_f32_16x16x32_bf16 v[122:125], v[158:161], v[182:185], v[122:125]
	v_mfma_f32_16x16x32_bf16 v[110:113], v[144:147], v[190:193], v[110:113]
	v_mfma_f32_16x16x32_bf16 v[106:109], v[158:161], v[190:193], v[106:109]
	v_mfma_f32_16x16x32_bf16 v[92:95], v[144:147], v[206:209], v[92:95]
	v_mfma_f32_16x16x32_bf16 v[88:91], v[158:161], v[206:209], v[88:91]
	v_mfma_f32_16x16x32_bf16 v[76:79], v[144:147], v[214:217], v[76:79]
	v_mfma_f32_16x16x32_bf16 v[72:75], v[158:161], v[214:217], v[72:75]
	v_mfma_f32_16x16x32_bf16 v[126:129], v[154:157], v[186:189], v[126:129]
	v_mfma_f32_16x16x32_bf16 v[122:125], v[162:165], v[186:189], v[122:125]
	v_mfma_f32_16x16x32_bf16 v[110:113], v[154:157], v[202:205], v[110:113]
	v_mfma_f32_16x16x32_bf16 v[106:109], v[162:165], v[202:205], v[106:109]
	v_mfma_f32_16x16x32_bf16 v[92:95], v[154:157], v[210:213], v[92:95]
	v_mfma_f32_16x16x32_bf16 v[88:91], v[162:165], v[210:213], v[88:91]
	v_mfma_f32_16x16x32_bf16 v[76:79], v[154:157], v[218:221], v[76:79]
	v_mfma_f32_16x16x32_bf16 v[72:75], v[162:165], v[218:221], v[72:75]
	v_mfma_f32_16x16x32_bf16 v[118:121], v[166:169], v[182:185], v[118:121]
	v_mfma_f32_16x16x32_bf16 v[114:117], v[174:177], v[182:185], v[114:117]
	v_mfma_f32_16x16x32_bf16 v[102:105], v[166:169], v[190:193], v[102:105]
	v_mfma_f32_16x16x32_bf16 v[98:101], v[174:177], v[190:193], v[98:101]
	v_mfma_f32_16x16x32_bf16 v[84:87], v[166:169], v[206:209], v[84:87]
	v_mfma_f32_16x16x32_bf16 v[80:83], v[174:177], v[206:209], v[80:83]
	v_mfma_f32_16x16x32_bf16 v[68:71], v[166:169], v[214:217], v[68:71]
	v_mfma_f32_16x16x32_bf16 v[64:67], v[174:177], v[214:217], v[64:67]
	v_mfma_f32_16x16x32_bf16 v[118:121], v[170:173], v[186:189], v[118:121]
	v_mfma_f32_16x16x32_bf16 v[114:117], v[178:181], v[186:189], v[114:117]
	v_mfma_f32_16x16x32_bf16 v[102:105], v[170:173], v[202:205], v[102:105]
	v_mfma_f32_16x16x32_bf16 v[98:101], v[178:181], v[202:205], v[98:101]
	v_mfma_f32_16x16x32_bf16 v[84:87], v[170:173], v[210:213], v[84:87]
	v_mfma_f32_16x16x32_bf16 v[80:83], v[178:181], v[210:213], v[80:83]
	v_mfma_f32_16x16x32_bf16 v[68:71], v[170:173], v[218:221], v[68:71]
	v_mfma_f32_16x16x32_bf16 v[64:67], v[178:181], v[218:221], v[64:67]
	s_barrier
; #define PG8_STAGE(bufoff, gbase, voff) do { _Pragma("unroll") for (int _i = 0; _i < 2; ++_i) \
;         __builtin_amdgcn_global_load_lds((const unsigned*)((const char*)(gbase) + (voff)[_i]), (PG8_LAS unsigned*)(lds + (bufoff) + ldsw + _i * 8192), 16, 0, 0); } while (0)
; #define PG8_LDA(dst, b, h) do { _Pragma("unroll") for (int m = 0; m < 4; ++m) _Pragma("unroll") for (int k = 0; k < 2; ++k) dst[m][k] = *(const PG8_LAS bf16x8*)(lds + PG8_SA(b, h) + aoff + m * 2048 + k * 1024); } while (0)
; #define PG8_MMA(ai, bj, At, Bt) do { __builtin_amdgcn_s_setprio(1); _Pragma("unroll") for (int m = 0; m < 4; ++m) _Pragma("unroll") for (int n = 0; n < 2; ++n) _Pragma("unroll") for (int k = 0; k < 2; ++k) \
;         acc[ai][bj][m][n] = __builtin_amdgcn_mfma_f32_16x16x32_bf16(Bt[n][k], At[m][k], acc[ai][bj][m][n], 0, 0, 0); __builtin_amdgcn_s_setprio(0); } while (0)
; #define PG8_WAIT_V(n) asm volatile("s_waitcnt vmcnt(" #n ")" ::: "memory")
; #define PG8_WAIT_L(n) asm volatile("s_waitcnt lgkmcnt(" #n ")" ::: "memory")
; #define PG8_BAR __builtin_amdgcn_s_barrier()
; #define PG8_SCHED __builtin_amdgcn_sched_barrier(0)
; template <class Epi, class Sched, bool ALIGN_EPI = false, bool SP2 = false>
; __device__ __forceinline__ void gemm_phase(PG8_LAS unsigned char* lds, const Gemm g, const Sched& S, const Epi& E) {
;     ...
;             PG8_LDA(At, 1, 1); PG8_STAGE(PG8_SB(1, 0), b3, voffB); PG8_STAGE(PG8_SB(1, 1), b3 + hstep, voffB); PG8_STAGE(PG8_SA(1, 0), a3, voffA);
;             PG8_WAIT_V(8); PG8_WAIT_L(0); PG8_BAR; PG8_MMA(1, 0, At, B0); PG8_MMA(1, 1, At, B1); PG8_BAR; PG8_SCHED;
	s_add_i32 s12, s73, s9
	v_lshl_add_u64 v[222:223], v[222:223], 0, s[36:37]
	s_mov_b32 m0, s12
	ds_read_b128 v[182:185], v152 offset:49152
	ds_read_b128 v[186:189], v152 offset:50176
	ds_read_b128 v[190:193], v152 offset:51200
	ds_read_b128 v[202:205], v152 offset:52224
	ds_read_b128 v[206:209], v152 offset:53248
	ds_read_b128 v[210:213], v152 offset:54272
	ds_read_b128 v[214:217], v152 offset:55296
	ds_read_b128 v[218:221], v152 offset:56320
	global_load_lds_dwordx4 v[222:223], off
	s_add_i32 m0, s12, 0x2000
	s_add_u32 s12, s58, 0x80080
	v_lshl_add_u64 v[222:223], v[224:225], 0, s[36:37]
	s_addc_u32 s13, s59, 0
	s_add_i32 s58, s84, s9
	global_load_lds_dwordx4 v[222:223], off
	v_lshl_add_u64 v[222:223], s[12:13], 0, v[132:133]
	s_mov_b32 m0, s58
	s_nop 0
	global_load_lds_dwordx4 v[222:223], off
	v_lshl_add_u64 v[222:223], s[12:13], 0, v[136:137]
	s_add_i32 m0, s58, 0x2000
	s_nop 0
	global_load_lds_dwordx4 v[222:223], off
	v_lshl_add_u64 v[222:223], v[226:227], 0, s[36:37]
	s_mov_b32 m0, s70
	s_nop 0
	global_load_lds_dwordx4 v[222:223], off
	v_lshl_add_u64 v[222:223], v[228:229], 0, s[36:37]
	s_mov_b32 m0, s71
	s_nop 0
	global_load_lds_dwordx4 v[222:223], off
	s_waitcnt vmcnt(8)
	s_waitcnt lgkmcnt(0)
	s_barrier
	s_waitcnt lgkmcnt(0)
	v_mfma_f32_16x16x32_bf16 v[60:63], v[144:147], v[182:185], v[60:63]
	v_mfma_f32_16x16x32_bf16 v[56:59], v[158:161], v[182:185], v[56:59]
	v_mfma_f32_16x16x32_bf16 v[44:47], v[144:147], v[190:193], v[44:47]
	v_mfma_f32_16x16x32_bf16 v[40:43], v[158:161], v[190:193], v[40:43]
	v_mfma_f32_16x16x32_bf16 v[28:31], v[144:147], v[206:209], v[28:31]
	v_mfma_f32_16x16x32_bf16 v[24:27], v[158:161], v[206:209], v[24:27]
	v_mfma_f32_16x16x32_bf16 v[12:15], v[144:147], v[214:217], v[12:15]
	v_mfma_f32_16x16x32_bf16 v[8:11], v[158:161], v[214:217], v[8:11]
	v_mfma_f32_16x16x32_bf16 v[60:63], v[154:157], v[186:189], v[60:63]
	v_mfma_f32_16x16x32_bf16 v[56:59], v[162:165], v[186:189], v[56:59]
	v_mfma_f32_16x16x32_bf16 v[44:47], v[154:157], v[202:205], v[44:47]
	v_mfma_f32_16x16x32_bf16 v[40:43], v[162:165], v[202:205], v[40:43]
	v_mfma_f32_16x16x32_bf16 v[28:31], v[154:157], v[210:213], v[28:31]
	v_mfma_f32_16x16x32_bf16 v[24:27], v[162:165], v[210:213], v[24:27]
	v_mfma_f32_16x16x32_bf16 v[12:15], v[154:157], v[218:221], v[12:15]
	v_mfma_f32_16x16x32_bf16 v[8:11], v[162:165], v[218:221], v[8:11]
	v_mfma_f32_16x16x32_bf16 v[52:55], v[166:169], v[182:185], v[52:55]
	v_mfma_f32_16x16x32_bf16 v[48:51], v[174:177], v[182:185], v[48:51]
	v_mfma_f32_16x16x32_bf16 v[36:39], v[166:169], v[190:193], v[36:39]
	v_mfma_f32_16x16x32_bf16 v[32:35], v[174:177], v[190:193], v[32:35]
	v_mfma_f32_16x16x32_bf16 v[20:23], v[166:169], v[206:209], v[20:23]
	v_mfma_f32_16x16x32_bf16 v[16:19], v[174:177], v[206:209], v[16:19]
	v_mfma_f32_16x16x32_bf16 v[4:7], v[166:169], v[214:217], v[4:7]
	v_mfma_f32_16x16x32_bf16 v[0:3], v[174:177], v[214:217], v[0:3]
	v_mfma_f32_16x16x32_bf16 v[52:55], v[170:173], v[186:189], v[52:55]
	v_mfma_f32_16x16x32_bf16 v[48:51], v[178:181], v[186:189], v[48:51]
	v_mfma_f32_16x16x32_bf16 v[36:39], v[170:173], v[202:205], v[36:39]
	v_mfma_f32_16x16x32_bf16 v[32:35], v[178:181], v[202:205], v[32:35]
	v_mfma_f32_16x16x32_bf16 v[20:23], v[170:173], v[210:213], v[20:23]
	v_mfma_f32_16x16x32_bf16 v[16:19], v[178:181], v[210:213], v[16:19]
	v_mfma_f32_16x16x32_bf16 v[4:7], v[170:173], v[218:221], v[4:7]
	v_mfma_f32_16x16x32_bf16 v[0:3], v[178:181], v[218:221], v[0:3]
	s_barrier
	s_add_i32 s51, s51, 2
	s_add_u32 s18, s18, 0x100
	s_addc_u32 s19, s19, 0
	s_add_u32 s42, s42, 0x100
	s_addc_u32 s43, s43, 0
	s_cmp_gt_u32 s51, 29
	s_cbranch_scc0 .LBB0_236
	s_and_b64 vcc, exec, s[0:1]
	s_cbranch_vccz .LBB0_239
	s_barrier

; #define PG8_STAGE(bufoff, gbase, voff) do { _Pragma("unroll") for (int _i = 0; _i < 2; ++_i) \
;         __builtin_amdgcn_global_load_lds((const unsigned*)((const char*)(gbase) + (voff)[_i]), (PG8_LAS unsigned*)(lds + (bufoff) + ldsw + _i * 8192), 16, 0, 0); } while (0)
; #define PG8_BAR __builtin_amdgcn_s_barrier()
; template <class Epi, class Sched, bool ALIGN_EPI = false, bool SP2 = false>
; __device__ __forceinline__ void gemm_phase(PG8_LAS unsigned char* lds, const Gemm g, const Sched& S, const Epi& E) {
;     ...
;     for (int i = 0; i < 2; ++i) { int R, C; stage_rc(tid * 16 + i * 8192, R, C); const int Rb = Epi::PERM ? ((R & ~31) + perm32(R & 31)) : R;
;         voffA[i] = (unsigned)(R * K + C) * 2u; voffB[i] = (unsigned)(Rb * K + C) * 2u; }
;     ...
;         PG8_STAGE(PG8_SB(0, 0), cB, voffB); PG8_STAGE(PG8_SB(0, 1), cB + hstep, voffB); PG8_STAGE(PG8_SA(0, 0), cA, voffA); PG8_STAGE(PG8_SA(0, 1), cA + hstep, voffA);
;         if (wr == 1) PG8_BAR;
.LBB0_880:
	s_waitcnt lgkmcnt(0)
	v_ashrrev_i32_e32 v1, 31, v11
	v_lshrrev_b32_e32 v1, 26, v1
	v_add_u32_e32 v1, v11, v1
	v_ashrrev_i32_e32 v8, 6, v1
	v_bfe_i32 v1, v11, 27, 1
	v_lshlrev_b32_e32 v0, 4, v11
	v_lshrrev_b32_e32 v1, 22, v1
	v_add_u32_e32 v1, v0, v1
	v_and_b32_e32 v1, 0xfffffc00, v1
	v_sub_u32_e32 v1, v0, v1
	v_lshrrev_b32_e32 v2, 4, v1
	v_bitop3_b32 v1, v2, v1, 32 bitop3:0x6c
	v_ashrrev_i32_e32 v3, 31, v1
	v_lshrrev_b32_e32 v3, 26, v3
	s_add_u32 s7, s14, 0x26b00000
	v_add_u32_e32 v3, v1, v3
	s_addc_u32 s8, s15, 0
	s_lshl_b32 s0, s33, 23
	v_lshlrev_b32_e32 v2, 3, v8
	v_ashrrev_i32_e32 v9, 6, v3
	v_and_b32_e32 v3, 0xc0, v3
	s_add_u32 s0, s14, s0
	v_and_b32_e32 v2, -16, v2
	v_sub_u32_e32 v1, v1, v3
	s_addc_u32 s1, s15, 0
	v_add_u32_e32 v2, v9, v2
	v_ashrrev_i16_sdwa v1, v240, sext(v1) dst_sel:DWORD dst_unused:UNUSED_PAD src0_sel:DWORD src1_sel:BYTE_0
	s_add_u32 s9, s0, 0x5300000
	v_lshlrev_b32_e32 v4, 5, v8
	v_bfe_i32 v10, v1, 0, 16
	v_lshlrev_b32_e32 v1, 1, v2
	v_lshrrev_b32_e32 v3, 2, v2
	v_and_b32_e32 v5, 3, v9
	s_mov_b32 s0, 0xfffe0
	v_and_b32_e32 v4, 32, v4
	v_and_b32_e32 v1, 24, v1
	v_and_b32_e32 v3, 4, v3
	v_and_or_b32 v5, v2, s0, v5
	v_or3_b32 v1, v5, v3, v1
	v_add_lshl_u32 v3, v4, v10, 1
	v_add_u32_e32 v0, 0x2000, v0
	v_lshl_add_u32 v204, v1, 12, v3
	v_ashrrev_i32_e32 v1, 31, v0
	v_lshrrev_b32_e32 v1, 22, v1
	v_add_u32_e32 v1, v0, v1
	v_ashrrev_i32_e32 v12, 10, v1
	v_mul_i32_i24_e32 v1, 0x400, v12
	v_sub_u32_e32 v0, v0, v1
	v_lshrrev_b32_e32 v1, 4, v0
	v_bitop3_b32 v0, v1, v0, 32 bitop3:0x6c
	v_lshl_add_u32 v202, v2, 12, v3
	v_ashrrev_i32_e32 v2, 31, v0
	v_lshrrev_b32_e32 v2, 26, v2
	v_lshlrev_b32_e32 v1, 3, v12
	v_add_u32_e32 v2, v0, v2
	v_and_b32_e32 v1, -16, v1
	v_ashrrev_i32_e32 v13, 6, v2
	s_addc_u32 s10, s1, 0
	s_ashr_i32 s12, s18, 6
	v_add_u32_e32 v1, v13, v1
	v_and_b32_e32 v2, 0xc0, v2
	v_and_b32_e32 v4, 3, v13
	s_ashr_i32 s57, s56, 31
	s_ashr_i32 s55, s54, 31
	v_sub_u32_e32 v0, v0, v2
	v_and_or_b32 v4, v1, s0, v4
	s_ashr_i32 s13, s18, 8
	s_lshl_b32 s11, s12, 10
	s_lshl_b64 s[0:1], s[56:57], 20
	s_lshl_b64 s[4:5], s[54:55], 20
	v_ashrrev_i16_sdwa v0, v240, sext(v0) dst_sel:DWORD dst_unused:UNUSED_PAD src0_sel:DWORD src1_sel:BYTE_0
	s_add_u32 s58, s9, s4
	v_lshlrev_b32_e32 v3, 5, v12
	v_bfe_i32 v14, v0, 0, 16
	v_lshlrev_b32_e32 v0, 1, v1
	v_lshrrev_b32_e32 v2, 2, v1
	s_addc_u32 s59, s10, s5
	s_add_i32 s57, s11, 0
	v_and_b32_e32 v3, 32, v3
	v_and_b32_e32 v0, 24, v0
	v_and_b32_e32 v2, 4, v2
	s_add_i32 m0, s57, 0x10000
	v_or3_b32 v0, v4, v2, v0
	v_add_lshl_u32 v2, v3, v14, 1
	global_load_lds_dwordx4 v204, s[58:59]
	s_add_i32 m0, s57, 0x12000
	v_lshl_add_u32 v208, v0, 12, v2
	s_add_u32 s4, s58, 0x80000
	global_load_lds_dwordx4 v208, s[58:59]
	s_addc_u32 s5, s59, 0
	s_add_i32 m0, s57, 0x14000
	v_lshl_add_u32 v206, v1, 12, v2
	global_load_lds_dwordx4 v204, s[4:5]
	s_add_i32 m0, s57, 0x16000
	s_add_u32 s60, s7, s0
	s_addc_u32 s61, s8, s1
	s_add_i32 s65, s57, 0x2000
	global_load_lds_dwordx4 v208, s[4:5]
	s_mov_b32 m0, s57
	s_add_u32 s0, s60, 0x80000
	global_load_lds_dwordx4 v202, s[60:61]
	s_mov_b32 m0, s65
	s_addc_u32 s1, s61, 0
	s_add_i32 s66, s57, 0x4000
	global_load_lds_dwordx4 v206, s[60:61]
	s_mov_b32 m0, s66
	s_add_i32 s67, s57, 0x6000
	global_load_lds_dwordx4 v202, s[0:1]
	s_mov_b32 m0, s67
	v_mov_b32_e32 v205, v96
	global_load_lds_dwordx4 v206, s[0:1]
	v_mov_b32_e32 v209, v96
	v_mov_b32_e32 v203, v96
	v_mov_b32_e32 v207, v96
	s_cmp_eq_u32 s13, 1
	v_lshl_add_u64 v[6:7], s[58:59], 0, v[204:205]
	v_lshl_add_u64 v[4:5], s[58:59], 0, v[208:209]
	v_lshl_add_u64 v[0:1], s[60:61], 0, v[202:203]
	s_cselect_b64 s[0:1], -1, 0
	s_cmp_lg_u32 s13, 1
	v_lshl_add_u64 v[2:3], s[60:61], 0, v[206:207]
	s_cbranch_scc1 .LBB0_882
	s_barrier
	s_setprio 1

; #define PG8_STAGE(bufoff, gbase, voff) do { _Pragma("unroll") for (int _i = 0; _i < 2; ++_i) \
;         __builtin_amdgcn_global_load_lds((const unsigned*)((const char*)(gbase) + (voff)[_i]), (PG8_LAS unsigned*)(lds + (bufoff) + ldsw + _i * 8192), 16, 0, 0); } while (0)
; #define PG8_LDA(dst, b, h) do { _Pragma("unroll") for (int m = 0; m < 4; ++m) _Pragma("unroll") for (int k = 0; k < 2; ++k) dst[m][k] = *(const PG8_LAS bf16x8*)(lds + PG8_SA(b, h) + aoff + m * 2048 + k * 1024); } while (0)
; #define PG8_LDB(dst, b, h) do { _Pragma("unroll") for (int n = 0; n < 2; ++n) _Pragma("unroll") for (int k = 0; k < 2; ++k) dst[n][k] = *(const PG8_LAS bf16x8*)(lds + PG8_SB(b, h) + boff + n * 2048 + k * 1024); } while (0)
; #define PG8_MMA(ai, bj, At, Bt) do { __builtin_amdgcn_s_setprio(1); _Pragma("unroll") for (int m = 0; m < 4; ++m) _Pragma("unroll") for (int n = 0; n < 2; ++n) _Pragma("unroll") for (int k = 0; k < 2; ++k) \
;         acc[ai][bj][m][n] = __builtin_amdgcn_mfma_f32_16x16x32_bf16(Bt[n][k], At[m][k], acc[ai][bj][m][n], 0, 0, 0); __builtin_amdgcn_s_setprio(0); } while (0)
; #define PG8_WAIT_V(n) asm volatile("s_waitcnt vmcnt(" #n ")" ::: "memory")
; #define PG8_WAIT_L(n) asm volatile("s_waitcnt lgkmcnt(" #n ")" ::: "memory")
; #define PG8_BAR __builtin_amdgcn_s_barrier()
; #define PG8_SCHED __builtin_amdgcn_sched_barrier(0)
; template <class Epi, class Sched, bool ALIGN_EPI = false, bool SP2 = false>
; __device__ __forceinline__ void gemm_phase(PG8_LAS unsigned char* lds, const Gemm g, const Sched& S, const Epi& E) {
;     ...
;         for (int t = 0; t < nt; t += 2) {
;             const bool last = (t == nt - 2);
;             const char* a1 = cA + (size_t)(t + 1) * kstep;
;             const char* a2 = last ? nA : cA + (size_t)(t + 2) * kstep; const char* b2 = last ? nB : cB + (size_t)(t + 2) * kstep;
;             const char* a3 = a2 + kstep; const char* b3 = b2 + kstep;
;             if (last && has_next) S.a_ready(nxt);
;             if constexpr (SP2) {
;             PG8_LDB(B0, 0, 0); PG8_LDB(B1, 0, 1); PG8_SCHED; PG8_LDA(At, 0, 0); PG8_STAGE(PG8_SA(1, 1), a1 + hstep, voffA);
;             PG8_WAIT_V(8); PG8_WAIT_L(0); PG8_BAR; PG8_MMA(0, 0, At, B0); PG8_MMA(0, 1, At, B1); PG8_BAR; PG8_SCHED;
;             PG8_LDA(At, 0, 1); PG8_STAGE(PG8_SB(0, 0), b2, voffB); PG8_STAGE(PG8_SB(0, 1), b2 + hstep, voffB); PG8_STAGE(PG8_SA(0, 0), a2, voffA);
.LBB0_892:
	s_add_u32 s12, s58, 0xfff80080
	s_addc_u32 s13, s59, -1
	s_add_i32 s84, 0, 0x10000
	s_cmp_eq_u32 s73, 28
	s_cselect_b32 s63, s18, s13
	s_cselect_b32 s62, s19, s12
	s_cselect_b32 s61, s26, s55
	s_cselect_b32 s60, s47, s49
	s_add_i32 s85, 0, 0x14000
	v_add_u32_e32 v130, s84, v247
	v_add_u32_e32 v158, s85, v247
	ds_read_b128 v[114:117], v130
	ds_read_b128 v[118:121], v130 offset:1024
	ds_read_b128 v[126:129], v130 offset:2048
	ds_read_b128 v[130:133], v130 offset:3072
	ds_read_b128 v[138:141], v158
	ds_read_b128 v[142:145], v158 offset:1024
	ds_read_b128 v[146:149], v158 offset:2048
	ds_read_b128 v[158:161], v158 offset:3072
	v_lshl_add_u64 v[214:215], s[58:59], 0, v[212:213]
	s_add_i32 m0, s57, 0xc000
	ds_read_b128 v[162:165], v249
	ds_read_b128 v[166:169], v249 offset:1024
	ds_read_b128 v[170:173], v249 offset:2048
	ds_read_b128 v[174:177], v249 offset:3072
	ds_read_b128 v[178:181], v249 offset:4096
	ds_read_b128 v[182:185], v249 offset:5120
	ds_read_b128 v[186:189], v249 offset:6144
	ds_read_b128 v[190:193], v249 offset:7168
	global_load_lds_dwordx4 v[214:215], off
	v_lshl_add_u64 v[214:215], s[58:59], 0, v[210:211]
	s_add_i32 m0, s57, 0xe000
	s_nop 0
	global_load_lds_dwordx4 v[214:215], off
	s_waitcnt vmcnt(8)
	s_waitcnt lgkmcnt(0)
	s_barrier
	s_waitcnt lgkmcnt(0)
	v_mfma_f32_16x16x32_bf16 v[154:157], v[114:117], v[162:165], v[154:157]
	v_mfma_f32_16x16x32_bf16 v[150:153], v[126:129], v[162:165], v[150:153]
	v_mfma_f32_16x16x32_bf16 v[110:113], v[114:117], v[170:173], v[110:113]
	v_mfma_f32_16x16x32_bf16 v[106:109], v[126:129], v[170:173], v[106:109]
	v_mfma_f32_16x16x32_bf16 v[92:95], v[114:117], v[178:181], v[92:95]
	v_mfma_f32_16x16x32_bf16 v[88:91], v[126:129], v[178:181], v[88:91]
	v_mfma_f32_16x16x32_bf16 v[76:79], v[114:117], v[186:189], v[76:79]
	v_mfma_f32_16x16x32_bf16 v[72:75], v[126:129], v[186:189], v[72:75]
	v_mfma_f32_16x16x32_bf16 v[154:157], v[118:121], v[166:169], v[154:157]
	v_mfma_f32_16x16x32_bf16 v[150:153], v[130:133], v[166:169], v[150:153]
	v_mfma_f32_16x16x32_bf16 v[110:113], v[118:121], v[174:177], v[110:113]
	v_mfma_f32_16x16x32_bf16 v[106:109], v[130:133], v[174:177], v[106:109]
	v_mfma_f32_16x16x32_bf16 v[92:95], v[118:121], v[182:185], v[92:95]
	v_mfma_f32_16x16x32_bf16 v[88:91], v[130:133], v[182:185], v[88:91]
	v_mfma_f32_16x16x32_bf16 v[76:79], v[118:121], v[190:193], v[76:79]
	v_mfma_f32_16x16x32_bf16 v[72:75], v[130:133], v[190:193], v[72:75]
	v_mfma_f32_16x16x32_bf16 v[134:137], v[138:141], v[162:165], v[134:137]
	v_mfma_f32_16x16x32_bf16 v[122:125], v[146:149], v[162:165], v[122:125]
	v_mfma_f32_16x16x32_bf16 v[102:105], v[138:141], v[170:173], v[102:105]
	v_mfma_f32_16x16x32_bf16 v[98:101], v[146:149], v[170:173], v[98:101]
	v_mfma_f32_16x16x32_bf16 v[84:87], v[138:141], v[178:181], v[84:87]
	v_mfma_f32_16x16x32_bf16 v[80:83], v[146:149], v[178:181], v[80:83]
	v_mfma_f32_16x16x32_bf16 v[68:71], v[138:141], v[186:189], v[68:71]
	v_mfma_f32_16x16x32_bf16 v[64:67], v[146:149], v[186:189], v[64:67]
	v_mfma_f32_16x16x32_bf16 v[134:137], v[142:145], v[166:169], v[134:137]
	v_mfma_f32_16x16x32_bf16 v[122:125], v[158:161], v[166:169], v[122:125]
	v_mfma_f32_16x16x32_bf16 v[102:105], v[142:145], v[174:177], v[102:105]
	v_mfma_f32_16x16x32_bf16 v[98:101], v[158:161], v[174:177], v[98:101]
	v_mfma_f32_16x16x32_bf16 v[84:87], v[142:145], v[182:185], v[84:87]
	v_mfma_f32_16x16x32_bf16 v[80:83], v[158:161], v[182:185], v[80:83]
	v_mfma_f32_16x16x32_bf16 v[68:71], v[142:145], v[190:193], v[68:71]
	v_mfma_f32_16x16x32_bf16 v[64:67], v[158:161], v[190:193], v[64:67]
	s_barrier
	s_add_i32 s12, s84, s11
	v_lshl_add_u64 v[214:215], s[60:61], 0, v[204:205]
	s_mov_b32 m0, s12
	ds_read_b128 v[162:165], v249 offset:16384
	ds_read_b128 v[166:169], v249 offset:17408
	ds_read_b128 v[170:173], v249 offset:18432
	ds_read_b128 v[174:177], v249 offset:19456
	ds_read_b128 v[178:181], v249 offset:20480
	ds_read_b128 v[182:185], v249 offset:21504
	ds_read_b128 v[186:189], v249 offset:22528
	ds_read_b128 v[190:193], v249 offset:23552
	global_load_lds_dwordx4 v[214:215], off
	s_add_i32 m0, s12, 0x2000
	s_add_u32 s12, s60, 0x80000
	v_lshl_add_u64 v[216:217], s[60:61], 0, v[208:209]
	s_addc_u32 s13, s61, 0
	s_add_i32 s84, s85, s11
	global_load_lds_dwordx4 v[216:217], off
	v_lshl_add_u64 v[218:219], s[12:13], 0, v[204:205]
	s_mov_b32 m0, s84
	v_lshl_add_u64 v[220:221], s[62:63], 0, v[206:207]
	global_load_lds_dwordx4 v[218:219], off
	v_lshl_add_u64 v[218:219], s[12:13], 0, v[208:209]
	s_add_i32 m0, s84, 0x2000
	s_nop 0
	global_load_lds_dwordx4 v[218:219], off
	v_lshl_add_u64 v[218:219], s[62:63], 0, v[202:203]
	s_mov_b32 m0, s57
	s_nop 0
	global_load_lds_dwordx4 v[218:219], off
	s_mov_b32 m0, s65
	s_nop 0
	global_load_lds_dwordx4 v[220:221], off
	s_waitcnt vmcnt(8)
	s_waitcnt lgkmcnt(0)
	s_barrier
; #define PG8_STAGE(bufoff, gbase, voff) do { _Pragma("unroll") for (int _i = 0; _i < 2; ++_i) \
;         __builtin_amdgcn_global_load_lds((const unsigned*)((const char*)(gbase) + (voff)[_i]), (PG8_LAS unsigned*)(lds + (bufoff) + ldsw + _i * 8192), 16, 0, 0); } while (0)
; #define PG8_LDA(dst, b, h) do { _Pragma("unroll") for (int m = 0; m < 4; ++m) _Pragma("unroll") for (int k = 0; k < 2; ++k) dst[m][k] = *(const PG8_LAS bf16x8*)(lds + PG8_SA(b, h) + aoff + m * 2048 + k * 1024); } while (0)
; #define PG8_LDB(dst, b, h) do { _Pragma("unroll") for (int n = 0; n < 2; ++n) _Pragma("unroll") for (int k = 0; k < 2; ++k) dst[n][k] = *(const PG8_LAS bf16x8*)(lds + PG8_SB(b, h) + boff + n * 2048 + k * 1024); } while (0)
; #define PG8_MMA(ai, bj, At, Bt) do { __builtin_amdgcn_s_setprio(1); _Pragma("unroll") for (int m = 0; m < 4; ++m) _Pragma("unroll") for (int n = 0; n < 2; ++n) _Pragma("unroll") for (int k = 0; k < 2; ++k) \
;         acc[ai][bj][m][n] = __builtin_amdgcn_mfma_f32_16x16x32_bf16(Bt[n][k], At[m][k], acc[ai][bj][m][n], 0, 0, 0); __builtin_amdgcn_s_setprio(0); } while (0)
; #define PG8_WAIT_V(n) asm volatile("s_waitcnt vmcnt(" #n ")" ::: "memory")
; #define PG8_WAIT_L(n) asm volatile("s_waitcnt lgkmcnt(" #n ")" ::: "memory")
; #define PG8_BAR __builtin_amdgcn_s_barrier()
; #define PG8_SCHED __builtin_amdgcn_sched_barrier(0)
; template <class Epi, class Sched, bool ALIGN_EPI = false, bool SP2 = false>
; __device__ __forceinline__ void gemm_phase(PG8_LAS unsigned char* lds, const Gemm g, const Sched& S, const Epi& E) {
;     ...
;             PG8_WAIT_V(8); PG8_WAIT_L(0); PG8_BAR; PG8_MMA(1, 0, At, B0); PG8_MMA(1, 1, At, B1); PG8_BAR; PG8_SCHED;
;             PG8_LDB(B0, 1, 0); PG8_LDB(B1, 1, 1); PG8_SCHED; PG8_LDA(At, 1, 0); PG8_STAGE(PG8_SA(0, 1), a2 + hstep, voffA);
;             PG8_WAIT_V(8); PG8_WAIT_L(0); PG8_BAR; PG8_MMA(0, 0, At, B0); PG8_MMA(0, 1, At, B1); PG8_BAR; PG8_SCHED;
	s_waitcnt lgkmcnt(0)
	v_mfma_f32_16x16x32_bf16 v[60:63], v[114:117], v[162:165], v[60:63]
	v_mfma_f32_16x16x32_bf16 v[56:59], v[126:129], v[162:165], v[56:59]
	v_mfma_f32_16x16x32_bf16 v[44:47], v[114:117], v[170:173], v[44:47]
	v_mfma_f32_16x16x32_bf16 v[40:43], v[126:129], v[170:173], v[40:43]
	v_mfma_f32_16x16x32_bf16 v[28:31], v[114:117], v[178:181], v[28:31]
	v_mfma_f32_16x16x32_bf16 v[24:27], v[126:129], v[178:181], v[24:27]
	v_mfma_f32_16x16x32_bf16 v[12:15], v[114:117], v[186:189], v[12:15]
	v_mfma_f32_16x16x32_bf16 v[8:11], v[126:129], v[186:189], v[8:11]
	v_mfma_f32_16x16x32_bf16 v[60:63], v[118:121], v[166:169], v[60:63]
	v_mfma_f32_16x16x32_bf16 v[56:59], v[130:133], v[166:169], v[56:59]
	v_mfma_f32_16x16x32_bf16 v[44:47], v[118:121], v[174:177], v[44:47]
	v_mfma_f32_16x16x32_bf16 v[40:43], v[130:133], v[174:177], v[40:43]
	v_mfma_f32_16x16x32_bf16 v[28:31], v[118:121], v[182:185], v[28:31]
	v_mfma_f32_16x16x32_bf16 v[24:27], v[130:133], v[182:185], v[24:27]
	v_mfma_f32_16x16x32_bf16 v[12:15], v[118:121], v[190:193], v[12:15]
	v_mfma_f32_16x16x32_bf16 v[8:11], v[130:133], v[190:193], v[8:11]
	v_mfma_f32_16x16x32_bf16 v[52:55], v[138:141], v[162:165], v[52:55]
	v_mfma_f32_16x16x32_bf16 v[48:51], v[146:149], v[162:165], v[48:51]
	v_mfma_f32_16x16x32_bf16 v[36:39], v[138:141], v[170:173], v[36:39]
	v_mfma_f32_16x16x32_bf16 v[32:35], v[146:149], v[170:173], v[32:35]
	v_mfma_f32_16x16x32_bf16 v[20:23], v[138:141], v[178:181], v[20:23]
	v_mfma_f32_16x16x32_bf16 v[16:19], v[146:149], v[178:181], v[16:19]
	v_mfma_f32_16x16x32_bf16 v[4:7], v[138:141], v[186:189], v[4:7]
	v_mfma_f32_16x16x32_bf16 v[0:3], v[146:149], v[186:189], v[0:3]
	v_mfma_f32_16x16x32_bf16 v[52:55], v[142:145], v[166:169], v[52:55]
	v_mfma_f32_16x16x32_bf16 v[48:51], v[158:161], v[166:169], v[48:51]
	v_mfma_f32_16x16x32_bf16 v[36:39], v[142:145], v[174:177], v[36:39]
	v_mfma_f32_16x16x32_bf16 v[32:35], v[158:161], v[174:177], v[32:35]
	v_mfma_f32_16x16x32_bf16 v[20:23], v[142:145], v[182:185], v[20:23]
	v_mfma_f32_16x16x32_bf16 v[16:19], v[158:161], v[182:185], v[16:19]
	v_mfma_f32_16x16x32_bf16 v[4:7], v[142:145], v[190:193], v[4:7]
	v_mfma_f32_16x16x32_bf16 v[0:3], v[158:161], v[190:193], v[0:3]
	s_barrier
	s_add_i32 s84, 0, 0x18000
	s_add_i32 s85, 0, 0x1c000
	v_add_u32_e32 v130, s84, v247
	v_add_u32_e32 v158, s85, v247
	ds_read_b128 v[114:117], v130
	ds_read_b128 v[118:121], v130 offset:1024
	ds_read_b128 v[126:129], v130 offset:2048
	ds_read_b128 v[130:133], v130 offset:3072
	ds_read_b128 v[138:141], v158
	ds_read_b128 v[142:145], v158 offset:1024
	ds_read_b128 v[146:149], v158 offset:2048
	ds_read_b128 v[158:161], v158 offset:3072
	s_add_u32 s12, s62, 0x80000
	s_addc_u32 s13, s63, 0
	s_mov_b32 m0, s66
	v_lshl_add_u64 v[222:223], s[12:13], 0, v[202:203]
	ds_read_b128 v[162:165], v249 offset:32768
	ds_read_b128 v[166:169], v249 offset:33792
	ds_read_b128 v[170:173], v249 offset:34816
	ds_read_b128 v[174:177], v249 offset:35840
	ds_read_b128 v[178:181], v249 offset:36864
	ds_read_b128 v[182:185], v249 offset:37888
	ds_read_b128 v[186:189], v249 offset:38912
	ds_read_b128 v[190:193], v249 offset:39936
	global_load_lds_dwordx4 v[222:223], off
	v_lshl_add_u64 v[222:223], s[12:13], 0, v[206:207]
	s_mov_b32 m0, s67
	s_nop 0
	global_load_lds_dwordx4 v[222:223], off
	s_waitcnt vmcnt(8)
	s_waitcnt lgkmcnt(0)
	s_barrier
	s_waitcnt lgkmcnt(0)
	v_mfma_f32_16x16x32_bf16 v[154:157], v[114:117], v[162:165], v[154:157]
	v_mfma_f32_16x16x32_bf16 v[150:153], v[126:129], v[162:165], v[150:153]
	v_mfma_f32_16x16x32_bf16 v[110:113], v[114:117], v[170:173], v[110:113]
	v_mfma_f32_16x16x32_bf16 v[106:109], v[126:129], v[170:173], v[106:109]
	v_mfma_f32_16x16x32_bf16 v[92:95], v[114:117], v[178:181], v[92:95]
	v_mfma_f32_16x16x32_bf16 v[88:91], v[126:129], v[178:181], v[88:91]
	v_mfma_f32_16x16x32_bf16 v[76:79], v[114:117], v[186:189], v[76:79]
	v_mfma_f32_16x16x32_bf16 v[72:75], v[126:129], v[186:189], v[72:75]
	v_mfma_f32_16x16x32_bf16 v[154:157], v[118:121], v[166:169], v[154:157]
	v_mfma_f32_16x16x32_bf16 v[150:153], v[130:133], v[166:169], v[150:153]
	v_mfma_f32_16x16x32_bf16 v[110:113], v[118:121], v[174:177], v[110:113]
	v_mfma_f32_16x16x32_bf16 v[106:109], v[130:133], v[174:177], v[106:109]
	v_mfma_f32_16x16x32_bf16 v[92:95], v[118:121], v[182:185], v[92:95]
	v_mfma_f32_16x16x32_bf16 v[88:91], v[130:133], v[182:185], v[88:91]
	v_mfma_f32_16x16x32_bf16 v[76:79], v[118:121], v[190:193], v[76:79]
	v_mfma_f32_16x16x32_bf16 v[72:75], v[130:133], v[190:193], v[72:75]
	v_mfma_f32_16x16x32_bf16 v[134:137], v[138:141], v[162:165], v[134:137]
	v_mfma_f32_16x16x32_bf16 v[122:125], v[146:149], v[162:165], v[122:125]
	v_mfma_f32_16x16x32_bf16 v[102:105], v[138:141], v[170:173], v[102:105]
	v_mfma_f32_16x16x32_bf16 v[98:101], v[146:149], v[170:173], v[98:101]
	v_mfma_f32_16x16x32_bf16 v[84:87], v[138:141], v[178:181], v[84:87]
	v_mfma_f32_16x16x32_bf16 v[80:83], v[146:149], v[178:181], v[80:83]
	v_mfma_f32_16x16x32_bf16 v[68:71], v[138:141], v[186:189], v[68:71]
	v_mfma_f32_16x16x32_bf16 v[64:67], v[146:149], v[186:189], v[64:67]
	v_mfma_f32_16x16x32_bf16 v[134:137], v[142:145], v[166:169], v[134:137]
	v_mfma_f32_16x16x32_bf16 v[122:125], v[158:161], v[166:169], v[122:125]
	v_mfma_f32_16x16x32_bf16 v[102:105], v[142:145], v[174:177], v[102:105]
	v_mfma_f32_16x16x32_bf16 v[98:101], v[158:161], v[174:177], v[98:101]
	v_mfma_f32_16x16x32_bf16 v[84:87], v[142:145], v[182:185], v[84:87]
	v_mfma_f32_16x16x32_bf16 v[80:83], v[158:161], v[182:185], v[80:83]
	v_mfma_f32_16x16x32_bf16 v[68:71], v[142:145], v[190:193], v[68:71]
	v_mfma_f32_16x16x32_bf16 v[64:67], v[158:161], v[190:193], v[64:67]
	s_barrier
; #define PG8_STAGE(bufoff, gbase, voff) do { _Pragma("unroll") for (int _i = 0; _i < 2; ++_i) \
;         __builtin_amdgcn_global_load_lds((const unsigned*)((const char*)(gbase) + (voff)[_i]), (PG8_LAS unsigned*)(lds + (bufoff) + ldsw + _i * 8192), 16, 0, 0); } while (0)
; #define PG8_LDA(dst, b, h) do { _Pragma("unroll") for (int m = 0; m < 4; ++m) _Pragma("unroll") for (int k = 0; k < 2; ++k) dst[m][k] = *(const PG8_LAS bf16x8*)(lds + PG8_SA(b, h) + aoff + m * 2048 + k * 1024); } while (0)
; #define PG8_MMA(ai, bj, At, Bt) do { __builtin_amdgcn_s_setprio(1); _Pragma("unroll") for (int m = 0; m < 4; ++m) _Pragma("unroll") for (int n = 0; n < 2; ++n) _Pragma("unroll") for (int k = 0; k < 2; ++k) \
;         acc[ai][bj][m][n] = __builtin_amdgcn_mfma_f32_16x16x32_bf16(Bt[n][k], At[m][k], acc[ai][bj][m][n], 0, 0, 0); __builtin_amdgcn_s_setprio(0); } while (0)
; #define PG8_WAIT_V(n) asm volatile("s_waitcnt vmcnt(" #n ")" ::: "memory")
; #define PG8_WAIT_L(n) asm volatile("s_waitcnt lgkmcnt(" #n ")" ::: "memory")
; #define PG8_BAR __builtin_amdgcn_s_barrier()
; #define PG8_SCHED __builtin_amdgcn_sched_barrier(0)
; template <class Epi, class Sched, bool ALIGN_EPI = false, bool SP2 = false>
; __device__ __forceinline__ void gemm_phase(PG8_LAS unsigned char* lds, const Gemm g, const Sched& S, const Epi& E) {
;     ...
;             PG8_LDA(At, 1, 1); PG8_STAGE(PG8_SB(1, 0), b3, voffB); PG8_STAGE(PG8_SB(1, 1), b3 + hstep, voffB); PG8_STAGE(PG8_SA(1, 0), a3, voffA);
;             PG8_WAIT_V(8); PG8_WAIT_L(0); PG8_BAR; PG8_MMA(1, 0, At, B0); PG8_MMA(1, 1, At, B1); PG8_BAR; PG8_SCHED;
	s_add_i32 s12, s84, s11
	v_lshl_add_u64 v[214:215], v[214:215], 0, s[36:37]
	s_mov_b32 m0, s12
	ds_read_b128 v[162:165], v249 offset:49152
	ds_read_b128 v[166:169], v249 offset:50176
	ds_read_b128 v[170:173], v249 offset:51200
	ds_read_b128 v[174:177], v249 offset:52224
	ds_read_b128 v[178:181], v249 offset:53248
	ds_read_b128 v[182:185], v249 offset:54272
	ds_read_b128 v[186:189], v249 offset:55296
	ds_read_b128 v[190:193], v249 offset:56320
	global_load_lds_dwordx4 v[214:215], off
	s_add_i32 m0, s12, 0x2000
	s_add_u32 s12, s60, 0x80080
	v_lshl_add_u64 v[214:215], v[216:217], 0, s[36:37]
	s_addc_u32 s13, s61, 0
	s_add_i32 s60, s85, s11
	global_load_lds_dwordx4 v[214:215], off
	v_lshl_add_u64 v[214:215], s[12:13], 0, v[204:205]
	s_mov_b32 m0, s60
	s_nop 0
	global_load_lds_dwordx4 v[214:215], off
	v_lshl_add_u64 v[214:215], s[12:13], 0, v[208:209]
	s_add_i32 m0, s60, 0x2000
	s_nop 0
	global_load_lds_dwordx4 v[214:215], off
	v_lshl_add_u64 v[214:215], v[218:219], 0, s[36:37]
	s_mov_b32 m0, s69
	s_nop 0
	global_load_lds_dwordx4 v[214:215], off
	v_lshl_add_u64 v[214:215], v[220:221], 0, s[36:37]
	s_mov_b32 m0, s70
	s_nop 0
	global_load_lds_dwordx4 v[214:215], off
	s_waitcnt vmcnt(8)
	s_waitcnt lgkmcnt(0)
	s_barrier
	s_waitcnt lgkmcnt(0)
	v_mfma_f32_16x16x32_bf16 v[60:63], v[114:117], v[162:165], v[60:63]
	v_mfma_f32_16x16x32_bf16 v[56:59], v[126:129], v[162:165], v[56:59]
	v_mfma_f32_16x16x32_bf16 v[44:47], v[114:117], v[170:173], v[44:47]
	v_mfma_f32_16x16x32_bf16 v[40:43], v[126:129], v[170:173], v[40:43]
	v_mfma_f32_16x16x32_bf16 v[28:31], v[114:117], v[178:181], v[28:31]
	v_mfma_f32_16x16x32_bf16 v[24:27], v[126:129], v[178:181], v[24:27]
	v_mfma_f32_16x16x32_bf16 v[12:15], v[114:117], v[186:189], v[12:15]
	v_mfma_f32_16x16x32_bf16 v[8:11], v[126:129], v[186:189], v[8:11]
	v_mfma_f32_16x16x32_bf16 v[60:63], v[118:121], v[166:169], v[60:63]
	v_mfma_f32_16x16x32_bf16 v[56:59], v[130:133], v[166:169], v[56:59]
	v_mfma_f32_16x16x32_bf16 v[44:47], v[118:121], v[174:177], v[44:47]
	v_mfma_f32_16x16x32_bf16 v[40:43], v[130:133], v[174:177], v[40:43]
	v_mfma_f32_16x16x32_bf16 v[28:31], v[118:121], v[182:185], v[28:31]
	v_mfma_f32_16x16x32_bf16 v[24:27], v[130:133], v[182:185], v[24:27]
	v_mfma_f32_16x16x32_bf16 v[12:15], v[118:121], v[190:193], v[12:15]
	v_mfma_f32_16x16x32_bf16 v[8:11], v[130:133], v[190:193], v[8:11]
	v_mfma_f32_16x16x32_bf16 v[52:55], v[138:141], v[162:165], v[52:55]
	v_mfma_f32_16x16x32_bf16 v[48:51], v[146:149], v[162:165], v[48:51]
	v_mfma_f32_16x16x32_bf16 v[36:39], v[138:141], v[170:173], v[36:39]
	v_mfma_f32_16x16x32_bf16 v[32:35], v[146:149], v[170:173], v[32:35]
	v_mfma_f32_16x16x32_bf16 v[20:23], v[138:141], v[178:181], v[20:23]
	v_mfma_f32_16x16x32_bf16 v[16:19], v[146:149], v[178:181], v[16:19]
	v_mfma_f32_16x16x32_bf16 v[4:7], v[138:141], v[186:189], v[4:7]
	v_mfma_f32_16x16x32_bf16 v[0:3], v[146:149], v[186:189], v[0:3]
	v_mfma_f32_16x16x32_bf16 v[52:55], v[142:145], v[166:169], v[52:55]
	v_mfma_f32_16x16x32_bf16 v[48:51], v[158:161], v[166:169], v[48:51]
	v_mfma_f32_16x16x32_bf16 v[36:39], v[142:145], v[174:177], v[36:39]
	v_mfma_f32_16x16x32_bf16 v[32:35], v[158:161], v[174:177], v[32:35]
	v_mfma_f32_16x16x32_bf16 v[20:23], v[142:145], v[182:185], v[20:23]
	v_mfma_f32_16x16x32_bf16 v[16:19], v[158:161], v[182:185], v[16:19]
	v_mfma_f32_16x16x32_bf16 v[4:7], v[142:145], v[190:193], v[4:7]
	v_mfma_f32_16x16x32_bf16 v[0:3], v[158:161], v[190:193], v[0:3]
	s_barrier
	s_add_i32 s73, s73, 2
	s_add_u32 s49, s49, 0x100
	s_addc_u32 s55, s55, 0
	s_add_u32 s58, s58, 0x100
	s_addc_u32 s59, s59, 0
	s_cmp_gt_u32 s73, 29
	s_cbranch_scc0 .LBB0_892
	s_and_b64 vcc, exec, s[14:15]
	s_cbranch_vccz .LBB0_895
	s_barrier

; #define PG8_WAIT_V(n) asm volatile("s_waitcnt vmcnt(" #n ")" ::: "memory")
; #define PG8_BAR __builtin_amdgcn_s_barrier()
; template <class Epi, class Sched, bool ALIGN_EPI = false, bool SP2 = false>
; __device__ __forceinline__ void gemm_phase(PG8_LAS unsigned char* lds, const Gemm g, const Sched& S, const Epi& E) {
;     ...
;     PG8_WAIT_V(0);
;     if constexpr (!ALIGN_EPI) { if (wr == 0) PG8_BAR; }
;     PG8_BAR;
.LBB0_914:
	s_setprio 0
	s_waitcnt vmcnt(0)
	v_readlane_b32 s58, v255, 18
	v_readlane_b32 s60, v255, 21
	v_readlane_b32 s59, v255, 19
	v_readlane_b32 s61, v255, 22
	s_barrier
	s_add_i32 s6, s64, 1
	s_cmp_ge_i32 s6, s81
	s_cbranch_scc1 .LBB0_981

; #define PG8_STAGE(bufoff, gbase, voff) do { _Pragma("unroll") for (int _i = 0; _i < 2; ++_i) \
;         __builtin_amdgcn_global_load_lds((const unsigned*)((const char*)(gbase) + (voff)[_i]), (PG8_LAS unsigned*)(lds + (bufoff) + ldsw + _i * 8192), 16, 0, 0); } while (0)
; #define PG8_BAR __builtin_amdgcn_s_barrier()
; template <class Epi, class Sched, bool ALIGN_EPI = false, bool SP2 = false>
; __device__ __forceinline__ void gemm_phase(PG8_LAS unsigned char* lds, const Gemm g, const Sched& S, const Epi& E) {
;     ...
;     for (int i = 0; i < 2; ++i) { int R, C; stage_rc(tid * 16 + i * 8192, R, C); const int Rb = Epi::PERM ? ((R & ~31) + perm32(R & 31)) : R;
;         voffA[i] = (unsigned)(R * K + C) * 2u; voffB[i] = (unsigned)(Rb * K + C) * 2u; }
;     ...
;         PG8_STAGE(PG8_SB(0, 0), cB, voffB); PG8_STAGE(PG8_SB(0, 1), cB + hstep, voffB); PG8_STAGE(PG8_SA(0, 0), cA, voffA); PG8_STAGE(PG8_SA(0, 1), cA + hstep, voffA);
;         if (wr == 1) PG8_BAR;
.LBB0_1004:
	v_ashrrev_i32_e32 v1, 31, v11
	v_lshrrev_b32_e32 v1, 26, v1
	v_add_u32_e32 v1, v11, v1
	v_ashrrev_i32_e32 v8, 6, v1
	v_bfe_i32 v1, v11, 27, 1
	v_lshlrev_b32_e32 v0, 4, v11
	v_lshrrev_b32_e32 v1, 22, v1
	v_add_u32_e32 v1, v0, v1
	v_and_b32_e32 v1, 0xfffffc00, v1
	v_sub_u32_e32 v1, v0, v1
	v_lshrrev_b32_e32 v2, 4, v1
	v_bitop3_b32 v1, v2, v1, 32 bitop3:0x6c
	v_ashrrev_i32_e32 v3, 31, v1
	v_lshrrev_b32_e32 v3, 26, v3
	v_add_u32_e32 v3, v1, v3
	v_lshlrev_b32_e32 v2, 3, v8
	v_ashrrev_i32_e32 v9, 6, v3
	v_and_b32_e32 v3, 0xc0, v3
	v_and_b32_e32 v2, -16, v2
	v_sub_u32_e32 v1, v1, v3
	v_add_u32_e32 v2, v9, v2
	v_ashrrev_i16_sdwa v1, v240, sext(v1) dst_sel:DWORD dst_unused:UNUSED_PAD src0_sel:DWORD src1_sel:BYTE_0
	v_lshlrev_b32_e32 v4, 5, v8
	v_bfe_i32 v10, v1, 0, 16
	v_lshlrev_b32_e32 v1, 1, v2
	v_lshrrev_b32_e32 v3, 2, v2
	v_and_b32_e32 v5, 3, v9
	s_mov_b32 s1, 0xfffe0
	v_and_b32_e32 v4, 32, v4
	v_and_b32_e32 v1, 24, v1
	v_and_b32_e32 v3, 4, v3
	v_and_or_b32 v5, v2, s1, v5
	v_or3_b32 v1, v5, v3, v1
	v_add_lshl_u32 v3, v4, v10, 1
	v_add_u32_e32 v0, 0x2000, v0
	v_lshl_add_u32 v132, v1, 12, v3
	v_ashrrev_i32_e32 v1, 31, v0
	v_lshrrev_b32_e32 v1, 22, v1
	v_add_u32_e32 v1, v0, v1
	v_ashrrev_i32_e32 v12, 10, v1
	v_mul_i32_i24_e32 v1, 0x400, v12
	v_sub_u32_e32 v0, v0, v1
	v_lshrrev_b32_e32 v1, 4, v0
	v_bitop3_b32 v0, v1, v0, 32 bitop3:0x6c
	v_lshl_add_u32 v130, v2, 12, v3
	v_ashrrev_i32_e32 v2, 31, v0
	v_lshrrev_b32_e32 v2, 26, v2
	v_lshlrev_b32_e32 v1, 3, v12
	v_add_u32_e32 v2, v0, v2
	s_ashr_i32 s12, s10, 6
	s_ashr_i32 s11, s10, 8
	v_and_b32_e32 v1, -16, v1
	v_ashrrev_i32_e32 v13, 6, v2
	s_lshl_b32 s9, s12, 10
	v_add_u32_e32 v1, v13, v1
	v_and_b32_e32 v4, 3, v13
	s_add_u32 s18, s14, 0x17300000
	v_and_or_b32 v4, v1, s1, v4
	s_addc_u32 s19, s15, 0
	s_lshl_b32 s1, s33, 25
	s_add_u32 s1, s14, s1
	s_addc_u32 s5, s15, 0
	s_add_u32 s26, s1, 0x7300000
	v_and_b32_e32 v2, 0xc0, v2
	s_addc_u32 s60, s5, 0
	s_ashr_i32 s1, s0, 31
	s_ashr_i32 s5, s4, 31
	v_sub_u32_e32 v0, v0, v2
	s_lshl_b64 s[40:41], s[0:1], 20
	s_lshl_b64 s[42:43], s[4:5], 20
	v_ashrrev_i16_sdwa v0, v240, sext(v0) dst_sel:DWORD dst_unused:UNUSED_PAD src0_sel:DWORD src1_sel:BYTE_0
	s_add_u32 s42, s26, s42
	v_lshlrev_b32_e32 v3, 5, v12
	v_bfe_i32 v14, v0, 0, 16
	v_lshlrev_b32_e32 v0, 1, v1
	v_lshrrev_b32_e32 v2, 2, v1
	s_addc_u32 s43, s60, s43
	s_add_i32 s61, s9, 0
	v_and_b32_e32 v3, 32, v3
	v_and_b32_e32 v0, 24, v0
	v_and_b32_e32 v2, 4, v2
	s_add_i32 m0, s61, 0x10000
	v_or3_b32 v0, v4, v2, v0
	v_add_lshl_u32 v2, v3, v14, 1
	global_load_lds_dwordx4 v132, s[42:43]
	s_add_i32 m0, s61, 0x12000
	v_lshl_add_u32 v136, v0, 12, v2
	s_add_u32 s44, s42, 0x80000
	global_load_lds_dwordx4 v136, s[42:43]
	s_addc_u32 s45, s43, 0
	s_add_i32 m0, s61, 0x14000
	v_lshl_add_u32 v134, v1, 12, v2
	global_load_lds_dwordx4 v132, s[44:45]
	s_add_i32 m0, s61, 0x16000
	s_add_u32 s58, s18, s40
	s_addc_u32 s59, s19, s41
	s_add_i32 s62, s61, 0x2000
	global_load_lds_dwordx4 v136, s[44:45]
	s_mov_b32 m0, s61
	s_add_u32 s40, s58, 0x80000
	global_load_lds_dwordx4 v130, s[58:59]
	s_mov_b32 m0, s62
	s_addc_u32 s41, s59, 0
	s_add_i32 s63, s61, 0x4000
	global_load_lds_dwordx4 v134, s[58:59]
	s_mov_b32 m0, s63
	s_add_i32 s65, s61, 0x6000
	global_load_lds_dwordx4 v130, s[40:41]
	s_mov_b32 m0, s65
	v_mov_b32_e32 v133, v96
	global_load_lds_dwordx4 v134, s[40:41]
	v_mov_b32_e32 v137, v96
	v_mov_b32_e32 v131, v96
	v_mov_b32_e32 v135, v96
	s_cmp_eq_u32 s11, 1
	v_lshl_add_u64 v[6:7], s[42:43], 0, v[132:133]
	v_lshl_add_u64 v[4:5], s[42:43], 0, v[136:137]
	v_lshl_add_u64 v[0:1], s[58:59], 0, v[130:131]
	s_cselect_b64 s[44:45], -1, 0
	s_cmp_lg_u32 s11, 1
	v_lshl_add_u64 v[2:3], s[58:59], 0, v[134:135]
	s_cbranch_scc1 .LBB0_1006
	s_barrier
	s_setprio 1

; #define PG8_STAGE(bufoff, gbase, voff) do { _Pragma("unroll") for (int _i = 0; _i < 2; ++_i) \
;         __builtin_amdgcn_global_load_lds((const unsigned*)((const char*)(gbase) + (voff)[_i]), (PG8_LAS unsigned*)(lds + (bufoff) + ldsw + _i * 8192), 16, 0, 0); } while (0)
; #define PG8_LDA(dst, b, h) do { _Pragma("unroll") for (int m = 0; m < 4; ++m) _Pragma("unroll") for (int k = 0; k < 2; ++k) dst[m][k] = *(const PG8_LAS bf16x8*)(lds + PG8_SA(b, h) + aoff + m * 2048 + k * 1024); } while (0)
; #define PG8_LDB(dst, b, h) do { _Pragma("unroll") for (int n = 0; n < 2; ++n) _Pragma("unroll") for (int k = 0; k < 2; ++k) dst[n][k] = *(const PG8_LAS bf16x8*)(lds + PG8_SB(b, h) + boff + n * 2048 + k * 1024); } while (0)
; #define PG8_MMA(ai, bj, At, Bt) do { __builtin_amdgcn_s_setprio(1); _Pragma("unroll") for (int m = 0; m < 4; ++m) _Pragma("unroll") for (int n = 0; n < 2; ++n) _Pragma("unroll") for (int k = 0; k < 2; ++k) \
;         acc[ai][bj][m][n] = __builtin_amdgcn_mfma_f32_16x16x32_bf16(Bt[n][k], At[m][k], acc[ai][bj][m][n], 0, 0, 0); __builtin_amdgcn_s_setprio(0); } while (0)
; #define PG8_WAIT_V(n) asm volatile("s_waitcnt vmcnt(" #n ")" ::: "memory")
; #define PG8_WAIT_L(n) asm volatile("s_waitcnt lgkmcnt(" #n ")" ::: "memory")
; #define PG8_BAR __builtin_amdgcn_s_barrier()
; #define PG8_SCHED __builtin_amdgcn_sched_barrier(0)
; template <class Epi, class Sched, bool ALIGN_EPI = false, bool SP2 = false>
; __device__ __forceinline__ void gemm_phase(PG8_LAS unsigned char* lds, const Gemm g, const Sched& S, const Epi& E) {
;     ...
;         for (int t = 0; t < nt; t += 2) {
;             const bool last = (t == nt - 2);
;             const char* a1 = cA + (size_t)(t + 1) * kstep;
;             const char* a2 = last ? nA : cA + (size_t)(t + 2) * kstep; const char* b2 = last ? nB : cB + (size_t)(t + 2) * kstep;
;             const char* a3 = a2 + kstep; const char* b3 = b2 + kstep;
;             if (last && has_next) S.a_ready(nxt);
;             if constexpr (SP2) {
;             PG8_LDB(B0, 0, 0); PG8_LDB(B1, 0, 1); PG8_SCHED; PG8_LDA(At, 0, 0); PG8_STAGE(PG8_SA(1, 1), a1 + hstep, voffA);
;             PG8_WAIT_V(8); PG8_WAIT_L(0); PG8_BAR; PG8_MMA(0, 0, At, B0); PG8_MMA(0, 1, At, B1); PG8_BAR; PG8_SCHED;
;             PG8_LDA(At, 0, 1); PG8_STAGE(PG8_SB(0, 0), b2, voffB); PG8_STAGE(PG8_SB(0, 1), b2 + hstep, voffB); PG8_STAGE(PG8_SA(0, 0), a2, voffA);
.LBB0_1016:
	s_add_u32 s12, s14, 0xfff80080
	s_addc_u32 s13, s15, -1
	s_add_i32 s70, 0, 0x10000
	s_cmp_eq_u32 s69, 28
	s_cselect_b32 s59, s1, s13
	s_cselect_b32 s58, s5, s12
	v_add_u32_e32 v148, s70, v149
	s_cselect_b32 s43, s10, s53
	s_cselect_b32 s42, s11, s51
	s_add_i32 s71, 0, 0x14000
	ds_read_b128 v[144:147], v148
	ds_read_b128 v[154:157], v148 offset:1024
	ds_read_b128 v[158:161], v148 offset:2048
	ds_read_b128 v[162:165], v148 offset:3072
	v_add_u32_e32 v148, s71, v149
	ds_read_b128 v[166:169], v148
	ds_read_b128 v[170:173], v148 offset:1024
	ds_read_b128 v[174:177], v148 offset:2048
	ds_read_b128 v[178:181], v148 offset:3072
	v_lshl_add_u64 v[222:223], s[14:15], 0, v[142:143]
	s_add_i32 m0, s61, 0xc000
	ds_read_b128 v[182:185], v152
	ds_read_b128 v[186:189], v152 offset:1024
	ds_read_b128 v[190:193], v152 offset:2048
	ds_read_b128 v[202:205], v152 offset:3072
	ds_read_b128 v[206:209], v152 offset:4096
	ds_read_b128 v[210:213], v152 offset:5120
	ds_read_b128 v[214:217], v152 offset:6144
	ds_read_b128 v[218:221], v152 offset:7168
	global_load_lds_dwordx4 v[222:223], off
	v_lshl_add_u64 v[222:223], s[14:15], 0, v[140:141]
	s_add_i32 m0, s61, 0xe000
	s_nop 0
	global_load_lds_dwordx4 v[222:223], off
	s_waitcnt vmcnt(8)
	s_waitcnt lgkmcnt(0)
	s_barrier
	s_waitcnt lgkmcnt(0)
	v_mfma_f32_16x16x32_bf16 v[126:129], v[144:147], v[182:185], v[126:129]
	v_mfma_f32_16x16x32_bf16 v[122:125], v[158:161], v[182:185], v[122:125]
	v_mfma_f32_16x16x32_bf16 v[110:113], v[144:147], v[190:193], v[110:113]
	v_mfma_f32_16x16x32_bf16 v[106:109], v[158:161], v[190:193], v[106:109]
	v_mfma_f32_16x16x32_bf16 v[92:95], v[144:147], v[206:209], v[92:95]
	v_mfma_f32_16x16x32_bf16 v[88:91], v[158:161], v[206:209], v[88:91]
	v_mfma_f32_16x16x32_bf16 v[76:79], v[144:147], v[214:217], v[76:79]
	v_mfma_f32_16x16x32_bf16 v[72:75], v[158:161], v[214:217], v[72:75]
	v_mfma_f32_16x16x32_bf16 v[126:129], v[154:157], v[186:189], v[126:129]
	v_mfma_f32_16x16x32_bf16 v[122:125], v[162:165], v[186:189], v[122:125]
	v_mfma_f32_16x16x32_bf16 v[110:113], v[154:157], v[202:205], v[110:113]
	v_mfma_f32_16x16x32_bf16 v[106:109], v[162:165], v[202:205], v[106:109]
	v_mfma_f32_16x16x32_bf16 v[92:95], v[154:157], v[210:213], v[92:95]
	v_mfma_f32_16x16x32_bf16 v[88:91], v[162:165], v[210:213], v[88:91]
	v_mfma_f32_16x16x32_bf16 v[76:79], v[154:157], v[218:221], v[76:79]
	v_mfma_f32_16x16x32_bf16 v[72:75], v[162:165], v[218:221], v[72:75]
	v_mfma_f32_16x16x32_bf16 v[118:121], v[166:169], v[182:185], v[118:121]
	v_mfma_f32_16x16x32_bf16 v[114:117], v[174:177], v[182:185], v[114:117]
	v_mfma_f32_16x16x32_bf16 v[102:105], v[166:169], v[190:193], v[102:105]
	v_mfma_f32_16x16x32_bf16 v[98:101], v[174:177], v[190:193], v[98:101]
	v_mfma_f32_16x16x32_bf16 v[84:87], v[166:169], v[206:209], v[84:87]
	v_mfma_f32_16x16x32_bf16 v[80:83], v[174:177], v[206:209], v[80:83]
	v_mfma_f32_16x16x32_bf16 v[68:71], v[166:169], v[214:217], v[68:71]
	v_mfma_f32_16x16x32_bf16 v[64:67], v[174:177], v[214:217], v[64:67]
	v_mfma_f32_16x16x32_bf16 v[118:121], v[170:173], v[186:189], v[118:121]
	v_mfma_f32_16x16x32_bf16 v[114:117], v[178:181], v[186:189], v[114:117]
	v_mfma_f32_16x16x32_bf16 v[102:105], v[170:173], v[202:205], v[102:105]
	v_mfma_f32_16x16x32_bf16 v[98:101], v[178:181], v[202:205], v[98:101]
	v_mfma_f32_16x16x32_bf16 v[84:87], v[170:173], v[210:213], v[84:87]
	v_mfma_f32_16x16x32_bf16 v[80:83], v[178:181], v[210:213], v[80:83]
	v_mfma_f32_16x16x32_bf16 v[68:71], v[170:173], v[218:221], v[68:71]
	v_mfma_f32_16x16x32_bf16 v[64:67], v[178:181], v[218:221], v[64:67]
	s_barrier
	s_add_i32 s12, s70, s9
	v_lshl_add_u64 v[222:223], s[42:43], 0, v[132:133]
	s_mov_b32 m0, s12
	ds_read_b128 v[182:185], v152 offset:16384
	ds_read_b128 v[186:189], v152 offset:17408
	ds_read_b128 v[190:193], v152 offset:18432
	ds_read_b128 v[202:205], v152 offset:19456
	ds_read_b128 v[206:209], v152 offset:20480
	ds_read_b128 v[210:213], v152 offset:21504
	ds_read_b128 v[214:217], v152 offset:22528
	ds_read_b128 v[218:221], v152 offset:23552
	global_load_lds_dwordx4 v[222:223], off
	s_add_i32 m0, s12, 0x2000
	s_add_u32 s12, s42, 0x80000
	v_lshl_add_u64 v[224:225], s[42:43], 0, v[136:137]
	s_addc_u32 s13, s43, 0
	s_add_i32 s70, s71, s9
	global_load_lds_dwordx4 v[224:225], off
	v_lshl_add_u64 v[226:227], s[12:13], 0, v[132:133]
	s_mov_b32 m0, s70
	v_lshl_add_u64 v[228:229], s[58:59], 0, v[134:135]
	global_load_lds_dwordx4 v[226:227], off
	v_lshl_add_u64 v[226:227], s[12:13], 0, v[136:137]
	s_add_i32 m0, s70, 0x2000
	s_nop 0
	global_load_lds_dwordx4 v[226:227], off
	v_lshl_add_u64 v[226:227], s[58:59], 0, v[130:131]
	s_mov_b32 m0, s61
	s_nop 0
	global_load_lds_dwordx4 v[226:227], off
	s_mov_b32 m0, s62
	s_nop 0
	global_load_lds_dwordx4 v[228:229], off
	s_waitcnt vmcnt(8)
	s_waitcnt lgkmcnt(0)
	s_barrier
; #define PG8_STAGE(bufoff, gbase, voff) do { _Pragma("unroll") for (int _i = 0; _i < 2; ++_i) \
;         __builtin_amdgcn_global_load_lds((const unsigned*)((const char*)(gbase) + (voff)[_i]), (PG8_LAS unsigned*)(lds + (bufoff) + ldsw + _i * 8192), 16, 0, 0); } while (0)
; #define PG8_LDA(dst, b, h) do { _Pragma("unroll") for (int m = 0; m < 4; ++m) _Pragma("unroll") for (int k = 0; k < 2; ++k) dst[m][k] = *(const PG8_LAS bf16x8*)(lds + PG8_SA(b, h) + aoff + m * 2048 + k * 1024); } while (0)
; #define PG8_LDB(dst, b, h) do { _Pragma("unroll") for (int n = 0; n < 2; ++n) _Pragma("unroll") for (int k = 0; k < 2; ++k) dst[n][k] = *(const PG8_LAS bf16x8*)(lds + PG8_SB(b, h) + boff + n * 2048 + k * 1024); } while (0)
; #define PG8_MMA(ai, bj, At, Bt) do { __builtin_amdgcn_s_setprio(1); _Pragma("unroll") for (int m = 0; m < 4; ++m) _Pragma("unroll") for (int n = 0; n < 2; ++n) _Pragma("unroll") for (int k = 0; k < 2; ++k) \
;         acc[ai][bj][m][n] = __builtin_amdgcn_mfma_f32_16x16x32_bf16(Bt[n][k], At[m][k], acc[ai][bj][m][n], 0, 0, 0); __builtin_amdgcn_s_setprio(0); } while (0)
; #define PG8_WAIT_V(n) asm volatile("s_waitcnt vmcnt(" #n ")" ::: "memory")
; #define PG8_WAIT_L(n) asm volatile("s_waitcnt lgkmcnt(" #n ")" ::: "memory")
; #define PG8_BAR __builtin_amdgcn_s_barrier()
; #define PG8_SCHED __builtin_amdgcn_sched_barrier(0)
; template <class Epi, class Sched, bool ALIGN_EPI = false, bool SP2 = false>
; __device__ __forceinline__ void gemm_phase(PG8_LAS unsigned char* lds, const Gemm g, const Sched& S, const Epi& E) {
;     ...
;             PG8_WAIT_V(8); PG8_WAIT_L(0); PG8_BAR; PG8_MMA(1, 0, At, B0); PG8_MMA(1, 1, At, B1); PG8_BAR; PG8_SCHED;
;             PG8_LDB(B0, 1, 0); PG8_LDB(B1, 1, 1); PG8_SCHED; PG8_LDA(At, 1, 0); PG8_STAGE(PG8_SA(0, 1), a2 + hstep, voffA);
;             PG8_WAIT_V(8); PG8_WAIT_L(0); PG8_BAR; PG8_MMA(0, 0, At, B0); PG8_MMA(0, 1, At, B1); PG8_BAR; PG8_SCHED;
	s_waitcnt lgkmcnt(0)
	v_mfma_f32_16x16x32_bf16 v[60:63], v[144:147], v[182:185], v[60:63]
	v_mfma_f32_16x16x32_bf16 v[56:59], v[158:161], v[182:185], v[56:59]
	v_mfma_f32_16x16x32_bf16 v[44:47], v[144:147], v[190:193], v[44:47]
	v_mfma_f32_16x16x32_bf16 v[40:43], v[158:161], v[190:193], v[40:43]
	v_mfma_f32_16x16x32_bf16 v[28:31], v[144:147], v[206:209], v[28:31]
	v_mfma_f32_16x16x32_bf16 v[24:27], v[158:161], v[206:209], v[24:27]
	v_mfma_f32_16x16x32_bf16 v[12:15], v[144:147], v[214:217], v[12:15]
	v_mfma_f32_16x16x32_bf16 v[8:11], v[158:161], v[214:217], v[8:11]
	v_mfma_f32_16x16x32_bf16 v[60:63], v[154:157], v[186:189], v[60:63]
	v_mfma_f32_16x16x32_bf16 v[56:59], v[162:165], v[186:189], v[56:59]
	v_mfma_f32_16x16x32_bf16 v[44:47], v[154:157], v[202:205], v[44:47]
	v_mfma_f32_16x16x32_bf16 v[40:43], v[162:165], v[202:205], v[40:43]
	v_mfma_f32_16x16x32_bf16 v[28:31], v[154:157], v[210:213], v[28:31]
	v_mfma_f32_16x16x32_bf16 v[24:27], v[162:165], v[210:213], v[24:27]
	v_mfma_f32_16x16x32_bf16 v[12:15], v[154:157], v[218:221], v[12:15]
	v_mfma_f32_16x16x32_bf16 v[8:11], v[162:165], v[218:221], v[8:11]
	v_mfma_f32_16x16x32_bf16 v[52:55], v[166:169], v[182:185], v[52:55]
	v_mfma_f32_16x16x32_bf16 v[48:51], v[174:177], v[182:185], v[48:51]
	v_mfma_f32_16x16x32_bf16 v[36:39], v[166:169], v[190:193], v[36:39]
	v_mfma_f32_16x16x32_bf16 v[32:35], v[174:177], v[190:193], v[32:35]
	v_mfma_f32_16x16x32_bf16 v[20:23], v[166:169], v[206:209], v[20:23]
	v_mfma_f32_16x16x32_bf16 v[16:19], v[174:177], v[206:209], v[16:19]
	v_mfma_f32_16x16x32_bf16 v[4:7], v[166:169], v[214:217], v[4:7]
	v_mfma_f32_16x16x32_bf16 v[0:3], v[174:177], v[214:217], v[0:3]
	v_mfma_f32_16x16x32_bf16 v[52:55], v[170:173], v[186:189], v[52:55]
	v_mfma_f32_16x16x32_bf16 v[48:51], v[178:181], v[186:189], v[48:51]
	v_mfma_f32_16x16x32_bf16 v[36:39], v[170:173], v[202:205], v[36:39]
	v_mfma_f32_16x16x32_bf16 v[32:35], v[178:181], v[202:205], v[32:35]
	v_mfma_f32_16x16x32_bf16 v[20:23], v[170:173], v[210:213], v[20:23]
	v_mfma_f32_16x16x32_bf16 v[16:19], v[178:181], v[210:213], v[16:19]
	v_mfma_f32_16x16x32_bf16 v[4:7], v[170:173], v[218:221], v[4:7]
	v_mfma_f32_16x16x32_bf16 v[0:3], v[178:181], v[218:221], v[0:3]
	s_barrier
	s_add_i32 s70, 0, 0x18000
	v_add_u32_e32 v148, s70, v149
	s_add_i32 s71, 0, 0x1c000
	ds_read_b128 v[144:147], v148
	ds_read_b128 v[154:157], v148 offset:1024
	ds_read_b128 v[158:161], v148 offset:2048
	ds_read_b128 v[162:165], v148 offset:3072
	v_add_u32_e32 v148, s71, v149
	ds_read_b128 v[166:169], v148
	ds_read_b128 v[170:173], v148 offset:1024
	ds_read_b128 v[174:177], v148 offset:2048
	ds_read_b128 v[178:181], v148 offset:3072
	s_add_u32 s12, s58, 0x80000
	s_addc_u32 s13, s59, 0
	s_mov_b32 m0, s63
	v_lshl_add_u64 v[230:231], s[12:13], 0, v[130:131]
	ds_read_b128 v[182:185], v152 offset:32768
	ds_read_b128 v[186:189], v152 offset:33792
	ds_read_b128 v[190:193], v152 offset:34816
	ds_read_b128 v[202:205], v152 offset:35840
	ds_read_b128 v[206:209], v152 offset:36864
	ds_read_b128 v[210:213], v152 offset:37888
	ds_read_b128 v[214:217], v152 offset:38912
	ds_read_b128 v[218:221], v152 offset:39936
	global_load_lds_dwordx4 v[230:231], off
	v_lshl_add_u64 v[230:231], s[12:13], 0, v[134:135]
	s_mov_b32 m0, s65
	s_nop 0
	global_load_lds_dwordx4 v[230:231], off
	s_waitcnt vmcnt(8)
	s_waitcnt lgkmcnt(0)
	s_barrier
	s_waitcnt lgkmcnt(0)
	v_mfma_f32_16x16x32_bf16 v[126:129], v[144:147], v[182:185], v[126:129]
	v_mfma_f32_16x16x32_bf16 v[122:125], v[158:161], v[182:185], v[122:125]
	v_mfma_f32_16x16x32_bf16 v[110:113], v[144:147], v[190:193], v[110:113]
	v_mfma_f32_16x16x32_bf16 v[106:109], v[158:161], v[190:193], v[106:109]
	v_mfma_f32_16x16x32_bf16 v[92:95], v[144:147], v[206:209], v[92:95]
	v_mfma_f32_16x16x32_bf16 v[88:91], v[158:161], v[206:209], v[88:91]
	v_mfma_f32_16x16x32_bf16 v[76:79], v[144:147], v[214:217], v[76:79]
	v_mfma_f32_16x16x32_bf16 v[72:75], v[158:161], v[214:217], v[72:75]
	v_mfma_f32_16x16x32_bf16 v[126:129], v[154:157], v[186:189], v[126:129]
	v_mfma_f32_16x16x32_bf16 v[122:125], v[162:165], v[186:189], v[122:125]
	v_mfma_f32_16x16x32_bf16 v[110:113], v[154:157], v[202:205], v[110:113]
	v_mfma_f32_16x16x32_bf16 v[106:109], v[162:165], v[202:205], v[106:109]
	v_mfma_f32_16x16x32_bf16 v[92:95], v[154:157], v[210:213], v[92:95]
	v_mfma_f32_16x16x32_bf16 v[88:91], v[162:165], v[210:213], v[88:91]
	v_mfma_f32_16x16x32_bf16 v[76:79], v[154:157], v[218:221], v[76:79]
	v_mfma_f32_16x16x32_bf16 v[72:75], v[162:165], v[218:221], v[72:75]
	v_mfma_f32_16x16x32_bf16 v[118:121], v[166:169], v[182:185], v[118:121]
	v_mfma_f32_16x16x32_bf16 v[114:117], v[174:177], v[182:185], v[114:117]
	v_mfma_f32_16x16x32_bf16 v[102:105], v[166:169], v[190:193], v[102:105]
	v_mfma_f32_16x16x32_bf16 v[98:101], v[174:177], v[190:193], v[98:101]
	v_mfma_f32_16x16x32_bf16 v[84:87], v[166:169], v[206:209], v[84:87]
	v_mfma_f32_16x16x32_bf16 v[80:83], v[174:177], v[206:209], v[80:83]
	v_mfma_f32_16x16x32_bf16 v[68:71], v[166:169], v[214:217], v[68:71]
	v_mfma_f32_16x16x32_bf16 v[64:67], v[174:177], v[214:217], v[64:67]
	v_mfma_f32_16x16x32_bf16 v[118:121], v[170:173], v[186:189], v[118:121]
	v_mfma_f32_16x16x32_bf16 v[114:117], v[178:181], v[186:189], v[114:117]
	v_mfma_f32_16x16x32_bf16 v[102:105], v[170:173], v[202:205], v[102:105]
	v_mfma_f32_16x16x32_bf16 v[98:101], v[178:181], v[202:205], v[98:101]
	v_mfma_f32_16x16x32_bf16 v[84:87], v[170:173], v[210:213], v[84:87]
	v_mfma_f32_16x16x32_bf16 v[80:83], v[178:181], v[210:213], v[80:83]
	v_mfma_f32_16x16x32_bf16 v[68:71], v[170:173], v[218:221], v[68:71]
	v_mfma_f32_16x16x32_bf16 v[64:67], v[178:181], v[218:221], v[64:67]
	s_barrier
; #define PG8_STAGE(bufoff, gbase, voff) do { _Pragma("unroll") for (int _i = 0; _i < 2; ++_i) \
;         __builtin_amdgcn_global_load_lds((const unsigned*)((const char*)(gbase) + (voff)[_i]), (PG8_LAS unsigned*)(lds + (bufoff) + ldsw + _i * 8192), 16, 0, 0); } while (0)
; #define PG8_LDA(dst, b, h) do { _Pragma("unroll") for (int m = 0; m < 4; ++m) _Pragma("unroll") for (int k = 0; k < 2; ++k) dst[m][k] = *(const PG8_LAS bf16x8*)(lds + PG8_SA(b, h) + aoff + m * 2048 + k * 1024); } while (0)
; #define PG8_MMA(ai, bj, At, Bt) do { __builtin_amdgcn_s_setprio(1); _Pragma("unroll") for (int m = 0; m < 4; ++m) _Pragma("unroll") for (int n = 0; n < 2; ++n) _Pragma("unroll") for (int k = 0; k < 2; ++k) \
;         acc[ai][bj][m][n] = __builtin_amdgcn_mfma_f32_16x16x32_bf16(Bt[n][k], At[m][k], acc[ai][bj][m][n], 0, 0, 0); __builtin_amdgcn_s_setprio(0); } while (0)
; #define PG8_WAIT_V(n) asm volatile("s_waitcnt vmcnt(" #n ")" ::: "memory")
; #define PG8_WAIT_L(n) asm volatile("s_waitcnt lgkmcnt(" #n ")" ::: "memory")
; #define PG8_BAR __builtin_amdgcn_s_barrier()
; #define PG8_SCHED __builtin_amdgcn_sched_barrier(0)
; template <class Epi, class Sched, bool ALIGN_EPI = false, bool SP2 = false>
; __device__ __forceinline__ void gemm_phase(PG8_LAS unsigned char* lds, const Gemm g, const Sched& S, const Epi& E) {
;     ...
;             PG8_LDA(At, 1, 1); PG8_STAGE(PG8_SB(1, 0), b3, voffB); PG8_STAGE(PG8_SB(1, 1), b3 + hstep, voffB); PG8_STAGE(PG8_SA(1, 0), a3, voffA);
;             PG8_WAIT_V(8); PG8_WAIT_L(0); PG8_BAR; PG8_MMA(1, 0, At, B0); PG8_MMA(1, 1, At, B1); PG8_BAR; PG8_SCHED;
	s_add_i32 s12, s70, s9
	v_lshl_add_u64 v[222:223], v[222:223], 0, s[36:37]
	s_mov_b32 m0, s12
	ds_read_b128 v[182:185], v152 offset:49152
	ds_read_b128 v[186:189], v152 offset:50176
	ds_read_b128 v[190:193], v152 offset:51200
	ds_read_b128 v[202:205], v152 offset:52224
	ds_read_b128 v[206:209], v152 offset:53248
	ds_read_b128 v[210:213], v152 offset:54272
	ds_read_b128 v[214:217], v152 offset:55296
	ds_read_b128 v[218:221], v152 offset:56320
	global_load_lds_dwordx4 v[222:223], off
	s_add_i32 m0, s12, 0x2000
	s_add_u32 s12, s42, 0x80080
	v_lshl_add_u64 v[222:223], v[224:225], 0, s[36:37]
	s_addc_u32 s13, s43, 0
	s_add_i32 s42, s71, s9
	global_load_lds_dwordx4 v[222:223], off
	v_lshl_add_u64 v[222:223], s[12:13], 0, v[132:133]
	s_mov_b32 m0, s42
	s_nop 0
	global_load_lds_dwordx4 v[222:223], off
	v_lshl_add_u64 v[222:223], s[12:13], 0, v[136:137]
	s_add_i32 m0, s42, 0x2000
	s_nop 0
	global_load_lds_dwordx4 v[222:223], off
	v_lshl_add_u64 v[222:223], v[226:227], 0, s[36:37]
	s_mov_b32 m0, s66
	s_nop 0
	global_load_lds_dwordx4 v[222:223], off
	v_lshl_add_u64 v[222:223], v[228:229], 0, s[36:37]
	s_mov_b32 m0, s67
	s_nop 0
	global_load_lds_dwordx4 v[222:223], off
	s_waitcnt vmcnt(8)
	s_waitcnt lgkmcnt(0)
	s_barrier
	s_waitcnt lgkmcnt(0)
	v_mfma_f32_16x16x32_bf16 v[60:63], v[144:147], v[182:185], v[60:63]
	v_mfma_f32_16x16x32_bf16 v[56:59], v[158:161], v[182:185], v[56:59]
	v_mfma_f32_16x16x32_bf16 v[44:47], v[144:147], v[190:193], v[44:47]
	v_mfma_f32_16x16x32_bf16 v[40:43], v[158:161], v[190:193], v[40:43]
	v_mfma_f32_16x16x32_bf16 v[28:31], v[144:147], v[206:209], v[28:31]
	v_mfma_f32_16x16x32_bf16 v[24:27], v[158:161], v[206:209], v[24:27]
	v_mfma_f32_16x16x32_bf16 v[12:15], v[144:147], v[214:217], v[12:15]
	v_mfma_f32_16x16x32_bf16 v[8:11], v[158:161], v[214:217], v[8:11]
	v_mfma_f32_16x16x32_bf16 v[60:63], v[154:157], v[186:189], v[60:63]
	v_mfma_f32_16x16x32_bf16 v[56:59], v[162:165], v[186:189], v[56:59]
	v_mfma_f32_16x16x32_bf16 v[44:47], v[154:157], v[202:205], v[44:47]
	v_mfma_f32_16x16x32_bf16 v[40:43], v[162:165], v[202:205], v[40:43]
	v_mfma_f32_16x16x32_bf16 v[28:31], v[154:157], v[210:213], v[28:31]
	v_mfma_f32_16x16x32_bf16 v[24:27], v[162:165], v[210:213], v[24:27]
	v_mfma_f32_16x16x32_bf16 v[12:15], v[154:157], v[218:221], v[12:15]
	v_mfma_f32_16x16x32_bf16 v[8:11], v[162:165], v[218:221], v[8:11]
	v_mfma_f32_16x16x32_bf16 v[52:55], v[166:169], v[182:185], v[52:55]
	v_mfma_f32_16x16x32_bf16 v[48:51], v[174:177], v[182:185], v[48:51]
	v_mfma_f32_16x16x32_bf16 v[36:39], v[166:169], v[190:193], v[36:39]
	v_mfma_f32_16x16x32_bf16 v[32:35], v[174:177], v[190:193], v[32:35]
	v_mfma_f32_16x16x32_bf16 v[20:23], v[166:169], v[206:209], v[20:23]
	v_mfma_f32_16x16x32_bf16 v[16:19], v[174:177], v[206:209], v[16:19]
	v_mfma_f32_16x16x32_bf16 v[4:7], v[166:169], v[214:217], v[4:7]
	v_mfma_f32_16x16x32_bf16 v[0:3], v[174:177], v[214:217], v[0:3]
	v_mfma_f32_16x16x32_bf16 v[52:55], v[170:173], v[186:189], v[52:55]
	v_mfma_f32_16x16x32_bf16 v[48:51], v[178:181], v[186:189], v[48:51]
	v_mfma_f32_16x16x32_bf16 v[36:39], v[170:173], v[202:205], v[36:39]
	v_mfma_f32_16x16x32_bf16 v[32:35], v[178:181], v[202:205], v[32:35]
	v_mfma_f32_16x16x32_bf16 v[20:23], v[170:173], v[210:213], v[20:23]
	v_mfma_f32_16x16x32_bf16 v[16:19], v[178:181], v[210:213], v[16:19]
	v_mfma_f32_16x16x32_bf16 v[4:7], v[170:173], v[218:221], v[4:7]
	v_mfma_f32_16x16x32_bf16 v[0:3], v[178:181], v[218:221], v[0:3]
	s_barrier
	s_add_i32 s69, s69, 2
	s_add_u32 s51, s51, 0x100
	s_addc_u32 s53, s53, 0
	s_add_u32 s14, s14, 0x100
	s_addc_u32 s15, s15, 0
	s_cmp_gt_u32 s69, 29
	s_cbranch_scc0 .LBB0_1016
	s_and_b64 vcc, exec, s[48:49]
	s_cbranch_vccz .LBB0_1019
	s_barrier

; #define PG8_WAIT_V(n) asm volatile("s_waitcnt vmcnt(" #n ")" ::: "memory")
; #define PG8_BAR __builtin_amdgcn_s_barrier()
; template <class Epi, class Sched, bool ALIGN_EPI = false, bool SP2 = false>
; __device__ __forceinline__ void gemm_phase(PG8_LAS unsigned char* lds, const Gemm g, const Sched& S, const Epi& E) {
;     ...
;     PG8_WAIT_V(0);
;     if constexpr (!ALIGN_EPI) { if (wr == 0) PG8_BAR; }
;     PG8_BAR;
.LBB0_1054:
	s_setprio 0
	s_waitcnt vmcnt(0)
	v_readlane_b32 s58, v255, 18
	v_readlane_b32 s60, v255, 21
	v_readlane_b32 s59, v255, 19
	v_readlane_b32 s61, v255, 22
	s_barrier
	s_add_i32 s6, s64, 2
	s_cmp_ge_i32 s6, s81
	s_cbranch_scc1 .LBB0_1121

; #define PG8_STAGE(bufoff, gbase, voff) do { _Pragma("unroll") for (int _i = 0; _i < 2; ++_i) \
;         __builtin_amdgcn_global_load_lds((const unsigned*)((const char*)(gbase) + (voff)[_i]), (PG8_LAS unsigned*)(lds + (bufoff) + ldsw + _i * 8192), 16, 0, 0); } while (0)
; #define PG8_BAR __builtin_amdgcn_s_barrier()
; template <class Epi, class Sched, bool ALIGN_EPI = false, bool SP2 = false>
; __device__ __forceinline__ void gemm_phase(PG8_LAS unsigned char* lds, const Gemm g, const Sched& S, const Epi& E) {
;     ...
;     for (int i = 0; i < 2; ++i) { int R, C; stage_rc(tid * 16 + i * 8192, R, C); const int Rb = Epi::PERM ? ((R & ~31) + perm32(R & 31)) : R;
;         voffA[i] = (unsigned)(R * K + C) * 2u; voffB[i] = (unsigned)(Rb * K + C) * 2u; }
;     ...
;         PG8_STAGE(PG8_SB(0, 0), cB, voffB); PG8_STAGE(PG8_SB(0, 1), cB + hstep, voffB); PG8_STAGE(PG8_SA(0, 0), cA, voffA); PG8_STAGE(PG8_SA(0, 1), cA + hstep, voffA);
;         if (wr == 1) PG8_BAR;
.LBB0_1132:
	s_waitcnt lgkmcnt(0)
	v_ashrrev_i32_e32 v1, 31, v11
	v_lshrrev_b32_e32 v1, 26, v1
	v_add_u32_e32 v1, v11, v1
	v_ashrrev_i32_e32 v8, 6, v1
	v_bfe_i32 v1, v11, 27, 1
	v_lshlrev_b32_e32 v0, 4, v11
	v_lshrrev_b32_e32 v1, 22, v1
	v_add_u32_e32 v1, v0, v1
	v_and_b32_e32 v1, 0xfffffc00, v1
	v_sub_u32_e32 v1, v0, v1
	v_lshrrev_b32_e32 v2, 4, v1
	v_bitop3_b32 v1, v2, v1, 32 bitop3:0x6c
	v_ashrrev_i32_e32 v3, 31, v1
	v_lshrrev_b32_e32 v3, 26, v3
	s_add_u32 s7, s14, 0x2b700000
	v_add_u32_e32 v3, v1, v3
	s_addc_u32 s8, s15, 0
	s_lshl_b32 s0, s33, 25
	v_lshlrev_b32_e32 v2, 3, v8
	v_ashrrev_i32_e32 v9, 6, v3
	v_and_b32_e32 v3, 0xc0, v3
	s_add_u32 s0, s14, s0
	v_and_b32_e32 v2, -16, v2
	v_sub_u32_e32 v1, v1, v3
	s_addc_u32 s1, s15, 0
	v_add_u32_e32 v2, v9, v2
	v_ashrrev_i16_sdwa v1, v240, sext(v1) dst_sel:DWORD dst_unused:UNUSED_PAD src0_sel:DWORD src1_sel:BYTE_0
	s_add_u32 s9, s0, 0xf300000
	v_lshlrev_b32_e32 v4, 5, v8
	v_bfe_i32 v10, v1, 0, 16
	v_lshlrev_b32_e32 v1, 1, v2
	v_lshrrev_b32_e32 v3, 2, v2
	v_and_b32_e32 v5, 3, v9
	s_mov_b32 s0, 0x3ffe0
	v_and_b32_e32 v4, 32, v4
	v_and_b32_e32 v1, 24, v1
	v_and_b32_e32 v3, 4, v3
	v_and_or_b32 v5, v2, s0, v5
	v_or3_b32 v1, v5, v3, v1
	v_add_lshl_u32 v3, v4, v10, 1
	v_add_u32_e32 v0, 0x2000, v0
	v_lshl_add_u32 v204, v1, 14, v3
	v_ashrrev_i32_e32 v1, 31, v0
	v_lshrrev_b32_e32 v1, 22, v1
	v_add_u32_e32 v1, v0, v1
	v_ashrrev_i32_e32 v12, 10, v1
	v_mul_i32_i24_e32 v1, 0x400, v12
	v_sub_u32_e32 v0, v0, v1
	v_lshrrev_b32_e32 v1, 4, v0
	v_bitop3_b32 v0, v1, v0, 32 bitop3:0x6c
	v_lshl_add_u32 v202, v2, 14, v3
	v_ashrrev_i32_e32 v2, 31, v0
	v_lshrrev_b32_e32 v2, 26, v2
	v_lshlrev_b32_e32 v1, 3, v12
	v_add_u32_e32 v2, v0, v2
	v_and_b32_e32 v1, -16, v1
	v_ashrrev_i32_e32 v13, 6, v2
	s_addc_u32 s10, s1, 0
	s_ashr_i32 s12, s18, 6
	v_add_u32_e32 v1, v13, v1
	v_and_b32_e32 v2, 0xc0, v2
	v_and_b32_e32 v4, 3, v13
	s_ashr_i32 s57, s56, 31
	s_ashr_i32 s55, s54, 31
	v_sub_u32_e32 v0, v0, v2
	v_and_or_b32 v4, v1, s0, v4
	s_ashr_i32 s13, s18, 8
	s_lshl_b32 s11, s12, 10
	s_lshl_b64 s[0:1], s[56:57], 22
	s_lshl_b64 s[4:5], s[54:55], 22
	v_ashrrev_i16_sdwa v0, v240, sext(v0) dst_sel:DWORD dst_unused:UNUSED_PAD src0_sel:DWORD src1_sel:BYTE_0
	s_add_u32 s58, s9, s4
	v_lshlrev_b32_e32 v3, 5, v12
	v_bfe_i32 v14, v0, 0, 16
	v_lshlrev_b32_e32 v0, 1, v1
	v_lshrrev_b32_e32 v2, 2, v1
	s_addc_u32 s59, s10, s5
	s_add_i32 s57, s11, 0
	v_and_b32_e32 v3, 32, v3
	v_and_b32_e32 v0, 24, v0
	v_and_b32_e32 v2, 4, v2
	s_add_i32 m0, s57, 0x10000
	v_or3_b32 v0, v4, v2, v0
	v_add_lshl_u32 v2, v3, v14, 1
	global_load_lds_dwordx4 v204, s[58:59]
	s_add_i32 m0, s57, 0x12000
	v_lshl_add_u32 v208, v0, 14, v2
	s_add_u32 s4, s58, 0x200000
	global_load_lds_dwordx4 v208, s[58:59]
	s_addc_u32 s5, s59, 0
	s_add_i32 m0, s57, 0x14000
	v_lshl_add_u32 v206, v1, 14, v2
	global_load_lds_dwordx4 v204, s[4:5]
	s_add_i32 m0, s57, 0x16000
	s_add_u32 s60, s7, s0
	s_addc_u32 s61, s8, s1
	s_add_i32 s65, s57, 0x2000
	global_load_lds_dwordx4 v208, s[4:5]
	s_mov_b32 m0, s57
	s_add_u32 s0, s60, 0x200000
	global_load_lds_dwordx4 v202, s[60:61]
	s_mov_b32 m0, s65
	s_addc_u32 s1, s61, 0
	s_add_i32 s66, s57, 0x4000
	global_load_lds_dwordx4 v206, s[60:61]
	s_mov_b32 m0, s66
	s_add_i32 s67, s57, 0x6000
	global_load_lds_dwordx4 v202, s[0:1]
	s_mov_b32 m0, s67
	v_mov_b32_e32 v205, v96
	global_load_lds_dwordx4 v206, s[0:1]
	v_mov_b32_e32 v209, v96
	v_mov_b32_e32 v203, v96
	v_mov_b32_e32 v207, v96
	s_cmp_eq_u32 s13, 1
	v_lshl_add_u64 v[6:7], s[58:59], 0, v[204:205]
	v_lshl_add_u64 v[4:5], s[58:59], 0, v[208:209]
	v_lshl_add_u64 v[0:1], s[60:61], 0, v[202:203]
	s_cselect_b64 s[0:1], -1, 0
	s_cmp_lg_u32 s13, 1
	v_lshl_add_u64 v[2:3], s[60:61], 0, v[206:207]
	s_cbranch_scc1 .LBB0_1134
	s_barrier
	s_setprio 1

; #define PG8_STAGE(bufoff, gbase, voff) do { _Pragma("unroll") for (int _i = 0; _i < 2; ++_i) \
;         __builtin_amdgcn_global_load_lds((const unsigned*)((const char*)(gbase) + (voff)[_i]), (PG8_LAS unsigned*)(lds + (bufoff) + ldsw + _i * 8192), 16, 0, 0); } while (0)
; #define PG8_LDA(dst, b, h) do { _Pragma("unroll") for (int m = 0; m < 4; ++m) _Pragma("unroll") for (int k = 0; k < 2; ++k) dst[m][k] = *(const PG8_LAS bf16x8*)(lds + PG8_SA(b, h) + aoff + m * 2048 + k * 1024); } while (0)
; #define PG8_LDB(dst, b, h) do { _Pragma("unroll") for (int n = 0; n < 2; ++n) _Pragma("unroll") for (int k = 0; k < 2; ++k) dst[n][k] = *(const PG8_LAS bf16x8*)(lds + PG8_SB(b, h) + boff + n * 2048 + k * 1024); } while (0)
; #define PG8_MMA(ai, bj, At, Bt) do { __builtin_amdgcn_s_setprio(1); _Pragma("unroll") for (int m = 0; m < 4; ++m) _Pragma("unroll") for (int n = 0; n < 2; ++n) _Pragma("unroll") for (int k = 0; k < 2; ++k) \
;         acc[ai][bj][m][n] = __builtin_amdgcn_mfma_f32_16x16x32_bf16(Bt[n][k], At[m][k], acc[ai][bj][m][n], 0, 0, 0); __builtin_amdgcn_s_setprio(0); } while (0)
; #define PG8_WAIT_V(n) asm volatile("s_waitcnt vmcnt(" #n ")" ::: "memory")
; #define PG8_WAIT_L(n) asm volatile("s_waitcnt lgkmcnt(" #n ")" ::: "memory")
; #define PG8_BAR __builtin_amdgcn_s_barrier()
; #define PG8_SCHED __builtin_amdgcn_sched_barrier(0)
; template <class Epi, class Sched, bool ALIGN_EPI = false, bool SP2 = false>
; __device__ __forceinline__ void gemm_phase(PG8_LAS unsigned char* lds, const Gemm g, const Sched& S, const Epi& E) {
;     ...
;         for (int t = 0; t < nt; t += 2) {
;             const bool last = (t == nt - 2);
;             const char* a1 = cA + (size_t)(t + 1) * kstep;
;             const char* a2 = last ? nA : cA + (size_t)(t + 2) * kstep; const char* b2 = last ? nB : cB + (size_t)(t + 2) * kstep;
;             const char* a3 = a2 + kstep; const char* b3 = b2 + kstep;
;             if (last && has_next) S.a_ready(nxt);
;             if constexpr (SP2) {
;             PG8_LDB(B0, 0, 0); PG8_LDB(B1, 0, 1); PG8_SCHED; PG8_LDA(At, 0, 0); PG8_STAGE(PG8_SA(1, 1), a1 + hstep, voffA);
;             PG8_WAIT_V(8); PG8_WAIT_L(0); PG8_BAR; PG8_MMA(0, 0, At, B0); PG8_MMA(0, 1, At, B1); PG8_BAR; PG8_SCHED;
;             PG8_LDA(At, 0, 1); PG8_STAGE(PG8_SB(0, 0), b2, voffB); PG8_STAGE(PG8_SB(0, 1), b2 + hstep, voffB); PG8_STAGE(PG8_SA(0, 0), a2, voffA);
.LBB0_1144:
	s_add_u32 s12, s58, 0xffe00080
	s_addc_u32 s13, s59, -1
	s_add_i32 s84, 0, 0x10000
	s_cmpk_eq_i32 s73, 0x7c
	s_cselect_b32 s63, s18, s13
	s_cselect_b32 s62, s19, s12
	s_cselect_b32 s61, s26, s55
	s_cselect_b32 s60, s47, s49
	s_add_i32 s85, 0, 0x14000
	v_add_u32_e32 v130, s84, v247
	v_add_u32_e32 v158, s85, v247
	ds_read_b128 v[114:117], v130
	ds_read_b128 v[118:121], v130 offset:1024
	ds_read_b128 v[126:129], v130 offset:2048
	ds_read_b128 v[130:133], v130 offset:3072
	ds_read_b128 v[138:141], v158
	ds_read_b128 v[142:145], v158 offset:1024
	ds_read_b128 v[146:149], v158 offset:2048
	ds_read_b128 v[158:161], v158 offset:3072
	v_lshl_add_u64 v[214:215], s[58:59], 0, v[212:213]
	s_add_i32 m0, s57, 0xc000
	ds_read_b128 v[162:165], v249
	ds_read_b128 v[166:169], v249 offset:1024
	ds_read_b128 v[170:173], v249 offset:2048
	ds_read_b128 v[174:177], v249 offset:3072
	ds_read_b128 v[178:181], v249 offset:4096
	ds_read_b128 v[182:185], v249 offset:5120
	ds_read_b128 v[186:189], v249 offset:6144
	ds_read_b128 v[190:193], v249 offset:7168
	global_load_lds_dwordx4 v[214:215], off
	v_lshl_add_u64 v[214:215], s[58:59], 0, v[210:211]
	s_add_i32 m0, s57, 0xe000
	s_nop 0
	global_load_lds_dwordx4 v[214:215], off
	s_waitcnt vmcnt(8)
	s_waitcnt lgkmcnt(0)
	s_barrier
	s_waitcnt lgkmcnt(0)
	v_mfma_f32_16x16x32_bf16 v[154:157], v[114:117], v[162:165], v[154:157]
	v_mfma_f32_16x16x32_bf16 v[150:153], v[126:129], v[162:165], v[150:153]
	v_mfma_f32_16x16x32_bf16 v[110:113], v[114:117], v[170:173], v[110:113]
	v_mfma_f32_16x16x32_bf16 v[106:109], v[126:129], v[170:173], v[106:109]
	v_mfma_f32_16x16x32_bf16 v[92:95], v[114:117], v[178:181], v[92:95]
	v_mfma_f32_16x16x32_bf16 v[88:91], v[126:129], v[178:181], v[88:91]
	v_mfma_f32_16x16x32_bf16 v[76:79], v[114:117], v[186:189], v[76:79]
	v_mfma_f32_16x16x32_bf16 v[72:75], v[126:129], v[186:189], v[72:75]
	v_mfma_f32_16x16x32_bf16 v[154:157], v[118:121], v[166:169], v[154:157]
	v_mfma_f32_16x16x32_bf16 v[150:153], v[130:133], v[166:169], v[150:153]
	v_mfma_f32_16x16x32_bf16 v[110:113], v[118:121], v[174:177], v[110:113]
	v_mfma_f32_16x16x32_bf16 v[106:109], v[130:133], v[174:177], v[106:109]
	v_mfma_f32_16x16x32_bf16 v[92:95], v[118:121], v[182:185], v[92:95]
	v_mfma_f32_16x16x32_bf16 v[88:91], v[130:133], v[182:185], v[88:91]
	v_mfma_f32_16x16x32_bf16 v[76:79], v[118:121], v[190:193], v[76:79]
	v_mfma_f32_16x16x32_bf16 v[72:75], v[130:133], v[190:193], v[72:75]
	v_mfma_f32_16x16x32_bf16 v[134:137], v[138:141], v[162:165], v[134:137]
	v_mfma_f32_16x16x32_bf16 v[122:125], v[146:149], v[162:165], v[122:125]
	v_mfma_f32_16x16x32_bf16 v[102:105], v[138:141], v[170:173], v[102:105]
	v_mfma_f32_16x16x32_bf16 v[98:101], v[146:149], v[170:173], v[98:101]
	v_mfma_f32_16x16x32_bf16 v[84:87], v[138:141], v[178:181], v[84:87]
	v_mfma_f32_16x16x32_bf16 v[80:83], v[146:149], v[178:181], v[80:83]
	v_mfma_f32_16x16x32_bf16 v[68:71], v[138:141], v[186:189], v[68:71]
	v_mfma_f32_16x16x32_bf16 v[64:67], v[146:149], v[186:189], v[64:67]
	v_mfma_f32_16x16x32_bf16 v[134:137], v[142:145], v[166:169], v[134:137]
	v_mfma_f32_16x16x32_bf16 v[122:125], v[158:161], v[166:169], v[122:125]
	v_mfma_f32_16x16x32_bf16 v[102:105], v[142:145], v[174:177], v[102:105]
	v_mfma_f32_16x16x32_bf16 v[98:101], v[158:161], v[174:177], v[98:101]
	v_mfma_f32_16x16x32_bf16 v[84:87], v[142:145], v[182:185], v[84:87]
	v_mfma_f32_16x16x32_bf16 v[80:83], v[158:161], v[182:185], v[80:83]
	v_mfma_f32_16x16x32_bf16 v[68:71], v[142:145], v[190:193], v[68:71]
	v_mfma_f32_16x16x32_bf16 v[64:67], v[158:161], v[190:193], v[64:67]
	s_barrier
	s_add_i32 s12, s84, s11
	v_lshl_add_u64 v[214:215], s[60:61], 0, v[204:205]
	s_mov_b32 m0, s12
	ds_read_b128 v[162:165], v249 offset:16384
	ds_read_b128 v[166:169], v249 offset:17408
	ds_read_b128 v[170:173], v249 offset:18432
	ds_read_b128 v[174:177], v249 offset:19456
	ds_read_b128 v[178:181], v249 offset:20480
	ds_read_b128 v[182:185], v249 offset:21504
	ds_read_b128 v[186:189], v249 offset:22528
	ds_read_b128 v[190:193], v249 offset:23552
	global_load_lds_dwordx4 v[214:215], off
	s_add_i32 m0, s12, 0x2000
	s_add_u32 s12, s60, 0x200000
	v_lshl_add_u64 v[216:217], s[60:61], 0, v[208:209]
	s_addc_u32 s13, s61, 0
	s_add_i32 s84, s85, s11
	global_load_lds_dwordx4 v[216:217], off
	v_lshl_add_u64 v[218:219], s[12:13], 0, v[204:205]
	s_mov_b32 m0, s84
	v_lshl_add_u64 v[220:221], s[62:63], 0, v[206:207]
	global_load_lds_dwordx4 v[218:219], off
	v_lshl_add_u64 v[218:219], s[12:13], 0, v[208:209]
	s_add_i32 m0, s84, 0x2000
	s_nop 0
	global_load_lds_dwordx4 v[218:219], off
	v_lshl_add_u64 v[218:219], s[62:63], 0, v[202:203]
	s_mov_b32 m0, s57
	s_nop 0
	global_load_lds_dwordx4 v[218:219], off
	s_mov_b32 m0, s65
	s_nop 0
	global_load_lds_dwordx4 v[220:221], off
	s_waitcnt vmcnt(8)
	s_waitcnt lgkmcnt(0)
	s_barrier
; #define PG8_STAGE(bufoff, gbase, voff) do { _Pragma("unroll") for (int _i = 0; _i < 2; ++_i) \
;         __builtin_amdgcn_global_load_lds((const unsigned*)((const char*)(gbase) + (voff)[_i]), (PG8_LAS unsigned*)(lds + (bufoff) + ldsw + _i * 8192), 16, 0, 0); } while (0)
; #define PG8_LDA(dst, b, h) do { _Pragma("unroll") for (int m = 0; m < 4; ++m) _Pragma("unroll") for (int k = 0; k < 2; ++k) dst[m][k] = *(const PG8_LAS bf16x8*)(lds + PG8_SA(b, h) + aoff + m * 2048 + k * 1024); } while (0)
; #define PG8_LDB(dst, b, h) do { _Pragma("unroll") for (int n = 0; n < 2; ++n) _Pragma("unroll") for (int k = 0; k < 2; ++k) dst[n][k] = *(const PG8_LAS bf16x8*)(lds + PG8_SB(b, h) + boff + n * 2048 + k * 1024); } while (0)
; #define PG8_MMA(ai, bj, At, Bt) do { __builtin_amdgcn_s_setprio(1); _Pragma("unroll") for (int m = 0; m < 4; ++m) _Pragma("unroll") for (int n = 0; n < 2; ++n) _Pragma("unroll") for (int k = 0; k < 2; ++k) \
;         acc[ai][bj][m][n] = __builtin_amdgcn_mfma_f32_16x16x32_bf16(Bt[n][k], At[m][k], acc[ai][bj][m][n], 0, 0, 0); __builtin_amdgcn_s_setprio(0); } while (0)
; #define PG8_WAIT_V(n) asm volatile("s_waitcnt vmcnt(" #n ")" ::: "memory")
; #define PG8_WAIT_L(n) asm volatile("s_waitcnt lgkmcnt(" #n ")" ::: "memory")
; #define PG8_BAR __builtin_amdgcn_s_barrier()
; #define PG8_SCHED __builtin_amdgcn_sched_barrier(0)
; template <class Epi, class Sched, bool ALIGN_EPI = false, bool SP2 = false>
; __device__ __forceinline__ void gemm_phase(PG8_LAS unsigned char* lds, const Gemm g, const Sched& S, const Epi& E) {
;     ...
;             PG8_WAIT_V(8); PG8_WAIT_L(0); PG8_BAR; PG8_MMA(1, 0, At, B0); PG8_MMA(1, 1, At, B1); PG8_BAR; PG8_SCHED;
;             PG8_LDB(B0, 1, 0); PG8_LDB(B1, 1, 1); PG8_SCHED; PG8_LDA(At, 1, 0); PG8_STAGE(PG8_SA(0, 1), a2 + hstep, voffA);
;             PG8_WAIT_V(8); PG8_WAIT_L(0); PG8_BAR; PG8_MMA(0, 0, At, B0); PG8_MMA(0, 1, At, B1); PG8_BAR; PG8_SCHED;
	s_waitcnt lgkmcnt(0)
	v_mfma_f32_16x16x32_bf16 v[60:63], v[114:117], v[162:165], v[60:63]
	v_mfma_f32_16x16x32_bf16 v[56:59], v[126:129], v[162:165], v[56:59]
	v_mfma_f32_16x16x32_bf16 v[44:47], v[114:117], v[170:173], v[44:47]
	v_mfma_f32_16x16x32_bf16 v[40:43], v[126:129], v[170:173], v[40:43]
	v_mfma_f32_16x16x32_bf16 v[28:31], v[114:117], v[178:181], v[28:31]
	v_mfma_f32_16x16x32_bf16 v[24:27], v[126:129], v[178:181], v[24:27]
	v_mfma_f32_16x16x32_bf16 v[12:15], v[114:117], v[186:189], v[12:15]
	v_mfma_f32_16x16x32_bf16 v[8:11], v[126:129], v[186:189], v[8:11]
	v_mfma_f32_16x16x32_bf16 v[60:63], v[118:121], v[166:169], v[60:63]
	v_mfma_f32_16x16x32_bf16 v[56:59], v[130:133], v[166:169], v[56:59]
	v_mfma_f32_16x16x32_bf16 v[44:47], v[118:121], v[174:177], v[44:47]
	v_mfma_f32_16x16x32_bf16 v[40:43], v[130:133], v[174:177], v[40:43]
	v_mfma_f32_16x16x32_bf16 v[28:31], v[118:121], v[182:185], v[28:31]
	v_mfma_f32_16x16x32_bf16 v[24:27], v[130:133], v[182:185], v[24:27]
	v_mfma_f32_16x16x32_bf16 v[12:15], v[118:121], v[190:193], v[12:15]
	v_mfma_f32_16x16x32_bf16 v[8:11], v[130:133], v[190:193], v[8:11]
	v_mfma_f32_16x16x32_bf16 v[52:55], v[138:141], v[162:165], v[52:55]
	v_mfma_f32_16x16x32_bf16 v[48:51], v[146:149], v[162:165], v[48:51]
	v_mfma_f32_16x16x32_bf16 v[36:39], v[138:141], v[170:173], v[36:39]
	v_mfma_f32_16x16x32_bf16 v[32:35], v[146:149], v[170:173], v[32:35]
	v_mfma_f32_16x16x32_bf16 v[20:23], v[138:141], v[178:181], v[20:23]
	v_mfma_f32_16x16x32_bf16 v[16:19], v[146:149], v[178:181], v[16:19]
	v_mfma_f32_16x16x32_bf16 v[4:7], v[138:141], v[186:189], v[4:7]
	v_mfma_f32_16x16x32_bf16 v[0:3], v[146:149], v[186:189], v[0:3]
	v_mfma_f32_16x16x32_bf16 v[52:55], v[142:145], v[166:169], v[52:55]
	v_mfma_f32_16x16x32_bf16 v[48:51], v[158:161], v[166:169], v[48:51]
	v_mfma_f32_16x16x32_bf16 v[36:39], v[142:145], v[174:177], v[36:39]
	v_mfma_f32_16x16x32_bf16 v[32:35], v[158:161], v[174:177], v[32:35]
	v_mfma_f32_16x16x32_bf16 v[20:23], v[142:145], v[182:185], v[20:23]
	v_mfma_f32_16x16x32_bf16 v[16:19], v[158:161], v[182:185], v[16:19]
	v_mfma_f32_16x16x32_bf16 v[4:7], v[142:145], v[190:193], v[4:7]
	v_mfma_f32_16x16x32_bf16 v[0:3], v[158:161], v[190:193], v[0:3]
	s_barrier
	s_add_i32 s84, 0, 0x18000
	s_add_i32 s85, 0, 0x1c000
	v_add_u32_e32 v130, s84, v247
	v_add_u32_e32 v158, s85, v247
	ds_read_b128 v[114:117], v130
	ds_read_b128 v[118:121], v130 offset:1024
	ds_read_b128 v[126:129], v130 offset:2048
	ds_read_b128 v[130:133], v130 offset:3072
	ds_read_b128 v[138:141], v158
	ds_read_b128 v[142:145], v158 offset:1024
	ds_read_b128 v[146:149], v158 offset:2048
	ds_read_b128 v[158:161], v158 offset:3072
	s_add_u32 s12, s62, 0x200000
	s_addc_u32 s13, s63, 0
	s_mov_b32 m0, s66
	v_lshl_add_u64 v[222:223], s[12:13], 0, v[202:203]
	ds_read_b128 v[162:165], v249 offset:32768
	ds_read_b128 v[166:169], v249 offset:33792
	ds_read_b128 v[170:173], v249 offset:34816
	ds_read_b128 v[174:177], v249 offset:35840
	ds_read_b128 v[178:181], v249 offset:36864
	ds_read_b128 v[182:185], v249 offset:37888
	ds_read_b128 v[186:189], v249 offset:38912
	ds_read_b128 v[190:193], v249 offset:39936
	global_load_lds_dwordx4 v[222:223], off
	v_lshl_add_u64 v[222:223], s[12:13], 0, v[206:207]
	s_mov_b32 m0, s67
	s_nop 0
	global_load_lds_dwordx4 v[222:223], off
	s_waitcnt vmcnt(8)
	s_waitcnt lgkmcnt(0)
	s_barrier
	s_waitcnt lgkmcnt(0)
	v_mfma_f32_16x16x32_bf16 v[154:157], v[114:117], v[162:165], v[154:157]
	v_mfma_f32_16x16x32_bf16 v[150:153], v[126:129], v[162:165], v[150:153]
	v_mfma_f32_16x16x32_bf16 v[110:113], v[114:117], v[170:173], v[110:113]
	v_mfma_f32_16x16x32_bf16 v[106:109], v[126:129], v[170:173], v[106:109]
	v_mfma_f32_16x16x32_bf16 v[92:95], v[114:117], v[178:181], v[92:95]
	v_mfma_f32_16x16x32_bf16 v[88:91], v[126:129], v[178:181], v[88:91]
	v_mfma_f32_16x16x32_bf16 v[76:79], v[114:117], v[186:189], v[76:79]
	v_mfma_f32_16x16x32_bf16 v[72:75], v[126:129], v[186:189], v[72:75]
	v_mfma_f32_16x16x32_bf16 v[154:157], v[118:121], v[166:169], v[154:157]
	v_mfma_f32_16x16x32_bf16 v[150:153], v[130:133], v[166:169], v[150:153]
	v_mfma_f32_16x16x32_bf16 v[110:113], v[118:121], v[174:177], v[110:113]
	v_mfma_f32_16x16x32_bf16 v[106:109], v[130:133], v[174:177], v[106:109]
	v_mfma_f32_16x16x32_bf16 v[92:95], v[118:121], v[182:185], v[92:95]
	v_mfma_f32_16x16x32_bf16 v[88:91], v[130:133], v[182:185], v[88:91]
	v_mfma_f32_16x16x32_bf16 v[76:79], v[118:121], v[190:193], v[76:79]
	v_mfma_f32_16x16x32_bf16 v[72:75], v[130:133], v[190:193], v[72:75]
	v_mfma_f32_16x16x32_bf16 v[134:137], v[138:141], v[162:165], v[134:137]
	v_mfma_f32_16x16x32_bf16 v[122:125], v[146:149], v[162:165], v[122:125]
	v_mfma_f32_16x16x32_bf16 v[102:105], v[138:141], v[170:173], v[102:105]
	v_mfma_f32_16x16x32_bf16 v[98:101], v[146:149], v[170:173], v[98:101]
	v_mfma_f32_16x16x32_bf16 v[84:87], v[138:141], v[178:181], v[84:87]
	v_mfma_f32_16x16x32_bf16 v[80:83], v[146:149], v[178:181], v[80:83]
	v_mfma_f32_16x16x32_bf16 v[68:71], v[138:141], v[186:189], v[68:71]
	v_mfma_f32_16x16x32_bf16 v[64:67], v[146:149], v[186:189], v[64:67]
	v_mfma_f32_16x16x32_bf16 v[134:137], v[142:145], v[166:169], v[134:137]
	v_mfma_f32_16x16x32_bf16 v[122:125], v[158:161], v[166:169], v[122:125]
	v_mfma_f32_16x16x32_bf16 v[102:105], v[142:145], v[174:177], v[102:105]
	v_mfma_f32_16x16x32_bf16 v[98:101], v[158:161], v[174:177], v[98:101]
	v_mfma_f32_16x16x32_bf16 v[84:87], v[142:145], v[182:185], v[84:87]
	v_mfma_f32_16x16x32_bf16 v[80:83], v[158:161], v[182:185], v[80:83]
	v_mfma_f32_16x16x32_bf16 v[68:71], v[142:145], v[190:193], v[68:71]
	v_mfma_f32_16x16x32_bf16 v[64:67], v[158:161], v[190:193], v[64:67]
	s_barrier
; #define PG8_STAGE(bufoff, gbase, voff) do { _Pragma("unroll") for (int _i = 0; _i < 2; ++_i) \
;         __builtin_amdgcn_global_load_lds((const unsigned*)((const char*)(gbase) + (voff)[_i]), (PG8_LAS unsigned*)(lds + (bufoff) + ldsw + _i * 8192), 16, 0, 0); } while (0)
; #define PG8_LDA(dst, b, h) do { _Pragma("unroll") for (int m = 0; m < 4; ++m) _Pragma("unroll") for (int k = 0; k < 2; ++k) dst[m][k] = *(const PG8_LAS bf16x8*)(lds + PG8_SA(b, h) + aoff + m * 2048 + k * 1024); } while (0)
; #define PG8_MMA(ai, bj, At, Bt) do { __builtin_amdgcn_s_setprio(1); _Pragma("unroll") for (int m = 0; m < 4; ++m) _Pragma("unroll") for (int n = 0; n < 2; ++n) _Pragma("unroll") for (int k = 0; k < 2; ++k) \
;         acc[ai][bj][m][n] = __builtin_amdgcn_mfma_f32_16x16x32_bf16(Bt[n][k], At[m][k], acc[ai][bj][m][n], 0, 0, 0); __builtin_amdgcn_s_setprio(0); } while (0)
; #define PG8_WAIT_V(n) asm volatile("s_waitcnt vmcnt(" #n ")" ::: "memory")
; #define PG8_WAIT_L(n) asm volatile("s_waitcnt lgkmcnt(" #n ")" ::: "memory")
; #define PG8_BAR __builtin_amdgcn_s_barrier()
; #define PG8_SCHED __builtin_amdgcn_sched_barrier(0)
; template <class Epi, class Sched, bool ALIGN_EPI = false, bool SP2 = false>
; __device__ __forceinline__ void gemm_phase(PG8_LAS unsigned char* lds, const Gemm g, const Sched& S, const Epi& E) {
;     ...
;             PG8_LDA(At, 1, 1); PG8_STAGE(PG8_SB(1, 0), b3, voffB); PG8_STAGE(PG8_SB(1, 1), b3 + hstep, voffB); PG8_STAGE(PG8_SA(1, 0), a3, voffA);
;             PG8_WAIT_V(8); PG8_WAIT_L(0); PG8_BAR; PG8_MMA(1, 0, At, B0); PG8_MMA(1, 1, At, B1); PG8_BAR; PG8_SCHED;
	s_add_i32 s12, s84, s11
	v_lshl_add_u64 v[214:215], v[214:215], 0, s[36:37]
	s_mov_b32 m0, s12
	ds_read_b128 v[162:165], v249 offset:49152
	ds_read_b128 v[166:169], v249 offset:50176
	ds_read_b128 v[170:173], v249 offset:51200
	ds_read_b128 v[174:177], v249 offset:52224
	ds_read_b128 v[178:181], v249 offset:53248
	ds_read_b128 v[182:185], v249 offset:54272
	ds_read_b128 v[186:189], v249 offset:55296
	ds_read_b128 v[190:193], v249 offset:56320
	global_load_lds_dwordx4 v[214:215], off
	s_add_i32 m0, s12, 0x2000
	s_add_u32 s12, s60, 0x200080
	v_lshl_add_u64 v[214:215], v[216:217], 0, s[36:37]
	s_addc_u32 s13, s61, 0
	s_add_i32 s60, s85, s11
	global_load_lds_dwordx4 v[214:215], off
	v_lshl_add_u64 v[214:215], s[12:13], 0, v[204:205]
	s_mov_b32 m0, s60
	s_nop 0
	global_load_lds_dwordx4 v[214:215], off
	v_lshl_add_u64 v[214:215], s[12:13], 0, v[208:209]
	s_add_i32 m0, s60, 0x2000
	s_nop 0
	global_load_lds_dwordx4 v[214:215], off
	v_lshl_add_u64 v[214:215], v[218:219], 0, s[36:37]
	s_mov_b32 m0, s69
	s_nop 0
	global_load_lds_dwordx4 v[214:215], off
	v_lshl_add_u64 v[214:215], v[220:221], 0, s[36:37]
	s_mov_b32 m0, s70
	s_nop 0
	global_load_lds_dwordx4 v[214:215], off
	s_waitcnt vmcnt(8)
	s_waitcnt lgkmcnt(0)
	s_barrier
	s_waitcnt lgkmcnt(0)
	v_mfma_f32_16x16x32_bf16 v[60:63], v[114:117], v[162:165], v[60:63]
	v_mfma_f32_16x16x32_bf16 v[56:59], v[126:129], v[162:165], v[56:59]
	v_mfma_f32_16x16x32_bf16 v[44:47], v[114:117], v[170:173], v[44:47]
	v_mfma_f32_16x16x32_bf16 v[40:43], v[126:129], v[170:173], v[40:43]
	v_mfma_f32_16x16x32_bf16 v[28:31], v[114:117], v[178:181], v[28:31]
	v_mfma_f32_16x16x32_bf16 v[24:27], v[126:129], v[178:181], v[24:27]
	v_mfma_f32_16x16x32_bf16 v[12:15], v[114:117], v[186:189], v[12:15]
	v_mfma_f32_16x16x32_bf16 v[8:11], v[126:129], v[186:189], v[8:11]
	v_mfma_f32_16x16x32_bf16 v[60:63], v[118:121], v[166:169], v[60:63]
	v_mfma_f32_16x16x32_bf16 v[56:59], v[130:133], v[166:169], v[56:59]
	v_mfma_f32_16x16x32_bf16 v[44:47], v[118:121], v[174:177], v[44:47]
	v_mfma_f32_16x16x32_bf16 v[40:43], v[130:133], v[174:177], v[40:43]
	v_mfma_f32_16x16x32_bf16 v[28:31], v[118:121], v[182:185], v[28:31]
	v_mfma_f32_16x16x32_bf16 v[24:27], v[130:133], v[182:185], v[24:27]
	v_mfma_f32_16x16x32_bf16 v[12:15], v[118:121], v[190:193], v[12:15]
	v_mfma_f32_16x16x32_bf16 v[8:11], v[130:133], v[190:193], v[8:11]
	v_mfma_f32_16x16x32_bf16 v[52:55], v[138:141], v[162:165], v[52:55]
	v_mfma_f32_16x16x32_bf16 v[48:51], v[146:149], v[162:165], v[48:51]
	v_mfma_f32_16x16x32_bf16 v[36:39], v[138:141], v[170:173], v[36:39]
	v_mfma_f32_16x16x32_bf16 v[32:35], v[146:149], v[170:173], v[32:35]
	v_mfma_f32_16x16x32_bf16 v[20:23], v[138:141], v[178:181], v[20:23]
	v_mfma_f32_16x16x32_bf16 v[16:19], v[146:149], v[178:181], v[16:19]
	v_mfma_f32_16x16x32_bf16 v[4:7], v[138:141], v[186:189], v[4:7]
	v_mfma_f32_16x16x32_bf16 v[0:3], v[146:149], v[186:189], v[0:3]
	v_mfma_f32_16x16x32_bf16 v[52:55], v[142:145], v[166:169], v[52:55]
	v_mfma_f32_16x16x32_bf16 v[48:51], v[158:161], v[166:169], v[48:51]
	v_mfma_f32_16x16x32_bf16 v[36:39], v[142:145], v[174:177], v[36:39]
	v_mfma_f32_16x16x32_bf16 v[32:35], v[158:161], v[174:177], v[32:35]
	v_mfma_f32_16x16x32_bf16 v[20:23], v[142:145], v[182:185], v[20:23]
	v_mfma_f32_16x16x32_bf16 v[16:19], v[158:161], v[182:185], v[16:19]
	v_mfma_f32_16x16x32_bf16 v[4:7], v[142:145], v[190:193], v[4:7]
	v_mfma_f32_16x16x32_bf16 v[0:3], v[158:161], v[190:193], v[0:3]
	s_barrier
	s_add_i32 s73, s73, 2
	s_add_u32 s49, s49, 0x100
	s_addc_u32 s55, s55, 0
	s_add_u32 s58, s58, 0x100
	s_addc_u32 s59, s59, 0
	s_cmpk_gt_u32 s73, 0x7d
	s_cbranch_scc0 .LBB0_1144
	s_and_b64 vcc, exec, s[14:15]
	s_cbranch_vccz .LBB0_1147
	s_barrier

; #define PG8_WAIT_V(n) asm volatile("s_waitcnt vmcnt(" #n ")" ::: "memory")
; #define PG8_BAR __builtin_amdgcn_s_barrier()
; template <class Epi, class Sched, bool ALIGN_EPI = false, bool SP2 = false>
; __device__ __forceinline__ void gemm_phase(PG8_LAS unsigned char* lds, const Gemm g, const Sched& S, const Epi& E) {
;     ...
;     PG8_WAIT_V(0);
;     if constexpr (!ALIGN_EPI) { if (wr == 0) PG8_BAR; }
;     PG8_BAR;
.LBB0_1166:
	s_setprio 0
	s_waitcnt vmcnt(0)
	v_readlane_b32 s58, v255, 18
	v_readlane_b32 s60, v255, 21
	v_readlane_b32 s59, v255, 19
	v_readlane_b32 s61, v255, 22
	s_barrier
	s_add_i32 s6, s64, 3
	s_cmp_ge_i32 s6, s81
	s_cbranch_scc0 .LBB0_1167
	s_getpc_b64 s[98:99]
